# GLU epilogue regenerated with all bias/z loads hoisted (one wait per tile instead of 16 serialized round trips); hyena filter spectrum staging loop: 8 loads in flight per iteration
# speedup vs baseline: 1.0498x; 1.0054x over previous
; __device__ __forceinline__ void hyfilter_item(PRef p, int layer, bool isctx, int cg4, unsigned char* shm) {
;     ...
;         const c2* Z = KF0b + (size_t)cc * N;
; #pragma unroll 8
;         for (int i = ht; i < N; i += 256) buf[PHYS(i)] = Z[i];
.LBB0_165:
	v_lshl_add_u64 v[166:167], v[22:23], 0, v[20:21]
	global_load_dwordx2 v[168:169], v[166:167], off
	v_lshrrev_b32_e32 v170, 1, v153
	global_load_dwordx2 v[172:173], v[166:167], off offset:2048
	v_and_b32_e32 v171, 0x7ffffff8, v170
	v_lshrrev_b32_e32 v174, 1, v154
	v_and_b32_e32 v175, 0x7ffffff8, v174
	v_lshrrev_b32_e32 v176, 1, v155
	v_and_b32_e32 v177, 0x7ffffff8, v176
	v_add_u32_e32 v178, v156, v148
	s_mov_b64 s[36:37], 0x4000
	v_add_u32_e32 v153, 0x800, v153
	v_add_u32_e32 v154, 0x800, v154
	v_add_u32_e32 v155, 0x800, v155
	v_add_u32_e32 v156, 0x4400, v156
	v_add_u32_e32 v179, v152, v148
	v_lshl_add_u64 v[180:181], v[22:23], 0, v[18:19]
	global_load_dwordx2 v[182:183], v[180:181], off
	v_add_u32_e32 v184, v151, v148
	v_add_u32_e32 v151, 0x4400, v151
	v_add_u32_e32 v152, 0x4400, v152
	v_lshl_add_u64 v[186:187], v[22:23], 0, v[16:17]
	global_load_dwordx2 v[188:189], v[186:187], off
	v_add_u32_e32 v185, v150, v148
	v_add_u32_e32 v150, 0x4400, v150
	v_lshl_add_u64 v[190:191], v[22:23], 0, v[14:15]
	global_load_dwordx2 v[192:193], v[190:191], off
	v_add_u32_e32 v194, v149, v148
	v_add_u32_e32 v149, 0x4400, v149
	v_lshl_add_u64 v[22:23], v[22:23], 0, s[36:37]
	v_add_u32_e32 v196, 0x500, v10
	v_mov_b32_e32 v197, v13
	v_lshl_add_u64 v[198:199], v[196:197], 3, v[4:5]
	global_load_dwordx2 v[200:201], v[198:199], off
	v_add3_u32 v195, v11, v177, v148
	v_add_u32_e32 v11, 0x4000, v11
	v_add_u32_e32 v202, 0x600, v10
	v_mov_b32_e32 v203, v13
	v_lshl_add_u64 v[204:205], v[202:203], 3, v[4:5]
	global_load_dwordx2 v[206:207], v[204:205], off
	v_add3_u32 v208, v157, v175, v148
	v_add_u32_e32 v157, 0x4000, v157
	v_add_u32_e32 v210, 0x700, v10
	v_mov_b32_e32 v211, v13
	v_lshl_add_u64 v[212:213], v[210:211], 3, v[4:5]
	global_load_dwordx2 v[214:215], v[212:213], off
	v_add_u32_e32 v10, 0x800, v10
	v_add3_u32 v209, v158, v171, v148
	v_add_u32_e32 v158, 0x4000, v158
	s_waitcnt vmcnt(7)
	ds_write_b64 v178, v[168:169]
	s_waitcnt vmcnt(6)
	ds_write_b64 v179, v[172:173]
	s_waitcnt vmcnt(5)
	ds_write_b64 v184, v[182:183]
	s_waitcnt vmcnt(4)
	ds_write_b64 v185, v[188:189]
	s_waitcnt vmcnt(3)
	ds_write_b64 v194, v[192:193]
	s_waitcnt vmcnt(2)
	ds_write_b64 v195, v[200:201]
	s_waitcnt vmcnt(1)
	ds_write_b64 v208, v[206:207]
	s_waitcnt vmcnt(0)
	ds_write_b64 v209, v[214:215]
	v_cmp_le_u32_e32 vcc, s14, v10
	s_or_b64 s[70:71], vcc, s[70:71]
	s_andn2_b64 exec, exec, s[70:71]
	s_cbranch_execnz .LBB0_165

; #define PG8_STAGE(bufoff, gbase, voff) do { _Pragma("unroll") for (int _i = 0; _i < 2; ++_i) \
;         __builtin_amdgcn_global_load_lds((const unsigned*)((const char*)(gbase) + (size_t)_i * r64##voff + (voff)), (LAS unsigned*)(lds + (bufoff) + ldsw + _i * 8192), 16, 0, 0); } while (0)
; #define PG8_LDA(dst, b, h) do { _Pragma("unroll") for (int m = 0; m < 4; ++m) _Pragma("unroll") for (int k = 0; k < 2; ++k) dst[m][k] = *(const LAS bf16x8*)(lds + PG8_SA(b, h) + aoff + m * 2048 + k * 1024); } while (0)
; #define PG8_LDB(dst, b, h) do { _Pragma("unroll") for (int n = 0; n < 2; ++n) _Pragma("unroll") for (int k = 0; k < 2; ++k) dst[n][k] = *(const LAS bf16x8*)(lds + PG8_SB(b, h) + boff + n * 2048 + k * 1024); } while (0)
; #define PG8_MMA(ai, bj, At, Bt) do { __builtin_amdgcn_s_setprio(1); _Pragma("unroll") for (int m = 0; m < 4; ++m) _Pragma("unroll") for (int n = 0; n < 2; ++n) _Pragma("unroll") for (int k = 0; k < 2; ++k) \
;         acc[ai][bj][m][n] = __builtin_amdgcn_mfma_f32_16x16x32_bf16(Bt[n][k], At[m][k], acc[ai][bj][m][n], 0, 0, 0); __builtin_amdgcn_s_setprio(0); } while (0)
; #define PG8_WAIT_V(n) asm volatile("s_waitcnt vmcnt(" #n ")" ::: "memory")
; #define PG8_WAIT_L(n) asm volatile("s_waitcnt lgkmcnt(" #n ")" ::: "memory")
; #define PG8_BAR __builtin_amdgcn_s_barrier()
; #define PG8_SCHED __builtin_amdgcn_sched_barrier(0)
; template <class Epi, class Sched>
; __device__ __forceinline__ void gemm_phase(LAS unsigned char* lds, const Gemm g, const Sched& S, const Epi& E) {
;     ...
;             PG8_LDB(B0, 0, 0); PG8_SCHED; PG8_LDA(At, 0, 0); PG8_STAGE(PG8_SA(1, 1), a1 + hstepA, voffA);
;             PG8_WAIT_L(8); PG8_BAR; PG8_WAIT_L(0); PG8_MMA(0, 0, At, B0); PG8_BAR; PG8_SCHED;
;             PG8_LDB(B1, 0, 1); PG8_STAGE(PG8_SB(0, 0), b2, voffB);
;             PG8_BAR; PG8_WAIT_L(0); PG8_MMA(0, 1, At, B1); PG8_BAR;
;             PG8_LDA(At, 0, 1); PG8_STAGE(PG8_SA(0, 0), a2, voffA);
;             PG8_BAR; PG8_WAIT_L(0); PG8_MMA(1, 0, At, B0); PG8_BAR; PG8_SCHED;
;             PG8_STAGE(PG8_SB(0, 1), b2 + hstepB, voffB);
;             PG8_WAIT_V(6); PG8_BAR; PG8_MMA(1, 1, At, B1); PG8_BAR;
.LBB0_446:
	ds_read_b128 v[138:141], v147
	ds_read_b128 v[142:145], v147 offset:1024
	ds_read_b128 v[150:153], v147 offset:2048
	ds_read_b128 v[154:157], v147 offset:3072
	s_add_u32 s58, s6, 0xfffe0080
	s_addc_u32 s59, s7, -1
	s_cmp_eq_u32 s57, 4
	s_cselect_b32 s59, s12, s59
	s_cselect_b32 s58, s51, s58
	s_cselect_b32 s61, s49, s9
	s_cselect_b32 s60, s56, s8
	v_lshl_add_u64 v[190:191], s[6:7], 0, v[132:133]
	s_add_i32 m0, s33, 0xc000
	ds_read_b128 v[158:161], v148
	ds_read_b128 v[162:165], v148 offset:1024
	ds_read_b128 v[166:169], v148 offset:2048
	ds_read_b128 v[170:173], v148 offset:3072
	ds_read_b128 v[174:177], v148 offset:4096
	ds_read_b128 v[178:181], v148 offset:5120
	ds_read_b128 v[182:185], v148 offset:6144
	ds_read_b128 v[186:189], v148 offset:7168
	global_load_lds_dwordx4 v[190:191], off
	v_lshl_add_u64 v[190:191], v[190:191], 0, s[10:11]
	s_add_i32 m0, s33, 0xe000
	s_nop 0
	global_load_lds_dwordx4 v[190:191], off
	s_waitcnt lgkmcnt(8)
	s_barrier
	s_waitcnt lgkmcnt(0)
	s_setprio 1
	s_waitcnt lgkmcnt(0)
	v_mfma_f32_16x16x32_bf16 v[124:127], v[138:141], v[158:161], v[124:127]
	v_mfma_f32_16x16x32_bf16 v[120:123], v[150:153], v[158:161], v[120:123]
	v_mfma_f32_16x16x32_bf16 v[108:111], v[138:141], v[166:169], v[108:111]
	v_mfma_f32_16x16x32_bf16 v[104:107], v[150:153], v[166:169], v[104:107]
	v_mfma_f32_16x16x32_bf16 v[92:95], v[138:141], v[174:177], v[92:95]
	v_mfma_f32_16x16x32_bf16 v[88:91], v[150:153], v[174:177], v[88:91]
	v_mfma_f32_16x16x32_bf16 v[76:79], v[138:141], v[182:185], v[76:79]
	v_mfma_f32_16x16x32_bf16 v[72:75], v[150:153], v[182:185], v[72:75]
	v_mfma_f32_16x16x32_bf16 v[124:127], v[142:145], v[162:165], v[124:127]
	v_mfma_f32_16x16x32_bf16 v[120:123], v[154:157], v[162:165], v[120:123]
	v_mfma_f32_16x16x32_bf16 v[108:111], v[142:145], v[170:173], v[108:111]
	v_mfma_f32_16x16x32_bf16 v[104:107], v[154:157], v[170:173], v[104:107]
	v_mfma_f32_16x16x32_bf16 v[92:95], v[142:145], v[178:181], v[92:95]
	v_mfma_f32_16x16x32_bf16 v[88:91], v[154:157], v[178:181], v[88:91]
	v_mfma_f32_16x16x32_bf16 v[76:79], v[142:145], v[186:189], v[76:79]
	v_mfma_f32_16x16x32_bf16 v[72:75], v[154:157], v[186:189], v[72:75]
	s_setprio 0
	s_barrier
	v_lshl_add_u64 v[206:207], s[60:61], 0, v[128:129]
	s_add_i32 s60, s40, s31
	s_mov_b32 m0, s60
	ds_read_b128 v[190:193], v149
	ds_read_b128 v[194:197], v149 offset:1024
	ds_read_b128 v[198:201], v149 offset:2048
	ds_read_b128 v[202:205], v149 offset:3072
	global_load_lds_dwordx4 v[206:207], off
	v_lshl_add_u64 v[208:209], v[206:207], 0, s[10:11]
	s_add_i32 m0, s60, 0x2000
	s_nop 0
	global_load_lds_dwordx4 v[208:209], off
	s_barrier
	s_waitcnt lgkmcnt(0)
	s_setprio 1
	s_waitcnt lgkmcnt(0)
	v_mfma_f32_16x16x32_bf16 v[116:119], v[190:193], v[158:161], v[116:119]
	v_mfma_f32_16x16x32_bf16 v[112:115], v[198:201], v[158:161], v[112:115]
	v_mfma_f32_16x16x32_bf16 v[100:103], v[190:193], v[166:169], v[100:103]
	v_mfma_f32_16x16x32_bf16 v[96:99], v[198:201], v[166:169], v[96:99]
	v_mfma_f32_16x16x32_bf16 v[84:87], v[190:193], v[174:177], v[84:87]
	v_mfma_f32_16x16x32_bf16 v[80:83], v[198:201], v[174:177], v[80:83]
	v_mfma_f32_16x16x32_bf16 v[68:71], v[190:193], v[182:185], v[68:71]
	v_mfma_f32_16x16x32_bf16 v[64:67], v[198:201], v[182:185], v[64:67]
	v_mfma_f32_16x16x32_bf16 v[116:119], v[194:197], v[162:165], v[116:119]
	v_mfma_f32_16x16x32_bf16 v[112:115], v[202:205], v[162:165], v[112:115]
	v_mfma_f32_16x16x32_bf16 v[100:103], v[194:197], v[170:173], v[100:103]
	v_mfma_f32_16x16x32_bf16 v[96:99], v[202:205], v[170:173], v[96:99]
	v_mfma_f32_16x16x32_bf16 v[84:87], v[194:197], v[178:181], v[84:87]
	v_mfma_f32_16x16x32_bf16 v[80:83], v[202:205], v[178:181], v[80:83]
	v_mfma_f32_16x16x32_bf16 v[68:71], v[194:197], v[186:189], v[68:71]
	v_mfma_f32_16x16x32_bf16 v[64:67], v[202:205], v[186:189], v[64:67]
	s_setprio 0
	s_mov_b32 m0, s33
	v_lshl_add_u64 v[208:209], s[58:59], 0, v[130:131]
	s_barrier
	ds_read_b128 v[158:161], v148 offset:16384
	ds_read_b128 v[162:165], v148 offset:17408
	ds_read_b128 v[166:169], v148 offset:18432
	ds_read_b128 v[170:173], v148 offset:19456
	ds_read_b128 v[174:177], v148 offset:20480
	ds_read_b128 v[178:181], v148 offset:21504
	ds_read_b128 v[182:185], v148 offset:22528
	ds_read_b128 v[186:189], v148 offset:23552
	global_load_lds_dwordx4 v[208:209], off
	v_lshl_add_u64 v[210:211], v[208:209], 0, s[10:11]
	s_mov_b32 m0, s34
	s_nop 0
	global_load_lds_dwordx4 v[210:211], off
	s_barrier
	s_waitcnt lgkmcnt(0)
	s_setprio 1
	s_waitcnt lgkmcnt(0)
	v_mfma_f32_16x16x32_bf16 v[60:63], v[138:141], v[158:161], v[60:63]
	v_mfma_f32_16x16x32_bf16 v[56:59], v[150:153], v[158:161], v[56:59]
	v_mfma_f32_16x16x32_bf16 v[44:47], v[138:141], v[166:169], v[44:47]
	v_mfma_f32_16x16x32_bf16 v[40:43], v[150:153], v[166:169], v[40:43]
	v_mfma_f32_16x16x32_bf16 v[28:31], v[138:141], v[174:177], v[28:31]
	v_mfma_f32_16x16x32_bf16 v[24:27], v[150:153], v[174:177], v[24:27]
	v_mfma_f32_16x16x32_bf16 v[12:15], v[138:141], v[182:185], v[12:15]
	v_mfma_f32_16x16x32_bf16 v[8:11], v[150:153], v[182:185], v[8:11]
	v_mfma_f32_16x16x32_bf16 v[60:63], v[142:145], v[162:165], v[60:63]
	v_mfma_f32_16x16x32_bf16 v[56:59], v[154:157], v[162:165], v[56:59]
	v_mfma_f32_16x16x32_bf16 v[44:47], v[142:145], v[170:173], v[44:47]
	v_mfma_f32_16x16x32_bf16 v[40:43], v[154:157], v[170:173], v[40:43]
	v_mfma_f32_16x16x32_bf16 v[28:31], v[142:145], v[178:181], v[28:31]
	v_mfma_f32_16x16x32_bf16 v[24:27], v[154:157], v[178:181], v[24:27]
	v_mfma_f32_16x16x32_bf16 v[12:15], v[142:145], v[186:189], v[12:15]
	v_mfma_f32_16x16x32_bf16 v[8:11], v[154:157], v[186:189], v[8:11]
	s_setprio 0
	s_barrier
; #define PG8_STAGE(bufoff, gbase, voff) do { _Pragma("unroll") for (int _i = 0; _i < 2; ++_i) \
;         __builtin_amdgcn_global_load_lds((const unsigned*)((const char*)(gbase) + (size_t)_i * r64##voff + (voff)), (LAS unsigned*)(lds + (bufoff) + ldsw + _i * 8192), 16, 0, 0); } while (0)
; #define PG8_LDA(dst, b, h) do { _Pragma("unroll") for (int m = 0; m < 4; ++m) _Pragma("unroll") for (int k = 0; k < 2; ++k) dst[m][k] = *(const LAS bf16x8*)(lds + PG8_SA(b, h) + aoff + m * 2048 + k * 1024); } while (0)
; #define PG8_LDB(dst, b, h) do { _Pragma("unroll") for (int n = 0; n < 2; ++n) _Pragma("unroll") for (int k = 0; k < 2; ++k) dst[n][k] = *(const LAS bf16x8*)(lds + PG8_SB(b, h) + boff + n * 2048 + k * 1024); } while (0)
; #define PG8_MMA(ai, bj, At, Bt) do { __builtin_amdgcn_s_setprio(1); _Pragma("unroll") for (int m = 0; m < 4; ++m) _Pragma("unroll") for (int n = 0; n < 2; ++n) _Pragma("unroll") for (int k = 0; k < 2; ++k) \
;         acc[ai][bj][m][n] = __builtin_amdgcn_mfma_f32_16x16x32_bf16(Bt[n][k], At[m][k], acc[ai][bj][m][n], 0, 0, 0); __builtin_amdgcn_s_setprio(0); } while (0)
; #define PG8_WAIT_V(n) asm volatile("s_waitcnt vmcnt(" #n ")" ::: "memory")
; #define PG8_WAIT_L(n) asm volatile("s_waitcnt lgkmcnt(" #n ")" ::: "memory")
; #define PG8_BAR __builtin_amdgcn_s_barrier()
; #define PG8_SCHED __builtin_amdgcn_sched_barrier(0)
; template <class Epi, class Sched>
; __device__ __forceinline__ void gemm_phase(LAS unsigned char* lds, const Gemm g, const Sched& S, const Epi& E) {
;     ...
;             PG8_LDB(B0, 1, 0); PG8_SCHED; PG8_LDA(At, 1, 0); PG8_STAGE(PG8_SA(0, 1), a2 + hstepA, voffA);
;             PG8_WAIT_L(8); PG8_BAR; PG8_WAIT_L(0); PG8_MMA(0, 0, At, B0); PG8_BAR; PG8_SCHED;
;             PG8_LDB(B1, 1, 1); PG8_STAGE(PG8_SB(1, 0), b3, voffB);
;             PG8_BAR; PG8_WAIT_L(0); PG8_MMA(0, 1, At, B1); PG8_BAR;
;             PG8_LDA(At, 1, 1); PG8_STAGE(PG8_SA(1, 0), a3, voffA);
;             PG8_BAR; PG8_WAIT_L(0); PG8_MMA(1, 0, At, B0); PG8_BAR; PG8_SCHED;
;             PG8_STAGE(PG8_SB(1, 1), b3 + hstepB, voffB);
;             PG8_WAIT_V(6); PG8_BAR; PG8_MMA(1, 1, At, B1); PG8_BAR;
	s_add_i32 s58, s41, s31
	v_lshl_add_u64 v[138:139], v[206:207], 0, s[16:17]
	s_mov_b32 m0, s58
	s_nop 0
	global_load_lds_dwordx4 v[138:139], off
	v_lshl_add_u64 v[138:139], v[206:207], 0, s[18:19]
	s_add_i32 m0, s58, 0x2000
	s_nop 0
	global_load_lds_dwordx4 v[138:139], off
	s_waitcnt vmcnt(6)
	s_barrier
	s_setprio 1
	v_mfma_f32_16x16x32_bf16 v[52:55], v[190:193], v[158:161], v[52:55]
	v_mfma_f32_16x16x32_bf16 v[48:51], v[198:201], v[158:161], v[48:51]
	v_mfma_f32_16x16x32_bf16 v[36:39], v[190:193], v[166:169], v[36:39]
	v_mfma_f32_16x16x32_bf16 v[32:35], v[198:201], v[166:169], v[32:35]
	v_mfma_f32_16x16x32_bf16 v[20:23], v[190:193], v[174:177], v[20:23]
	v_mfma_f32_16x16x32_bf16 v[16:19], v[198:201], v[174:177], v[16:19]
	v_mfma_f32_16x16x32_bf16 v[4:7], v[190:193], v[182:185], v[4:7]
	v_mfma_f32_16x16x32_bf16 v[0:3], v[198:201], v[182:185], v[0:3]
	v_mfma_f32_16x16x32_bf16 v[52:55], v[194:197], v[162:165], v[52:55]
	v_mfma_f32_16x16x32_bf16 v[48:51], v[202:205], v[162:165], v[48:51]
	v_mfma_f32_16x16x32_bf16 v[36:39], v[194:197], v[170:173], v[36:39]
	v_mfma_f32_16x16x32_bf16 v[32:35], v[202:205], v[170:173], v[32:35]
	v_mfma_f32_16x16x32_bf16 v[20:23], v[194:197], v[178:181], v[20:23]
	v_mfma_f32_16x16x32_bf16 v[16:19], v[202:205], v[178:181], v[16:19]
	v_mfma_f32_16x16x32_bf16 v[4:7], v[194:197], v[186:189], v[4:7]
	v_mfma_f32_16x16x32_bf16 v[0:3], v[202:205], v[186:189], v[0:3]
	s_setprio 0
	s_add_i32 s58, 0, 0x18000
	v_add_u32_e32 v154, s58, v146
	s_barrier
	ds_read_b128 v[138:141], v154
	ds_read_b128 v[142:145], v154 offset:1024
	ds_read_b128 v[150:153], v154 offset:2048
	ds_read_b128 v[154:157], v154 offset:3072
	s_mov_b32 m0, s35
	v_lshl_add_u64 v[190:191], v[208:209], 0, s[16:17]
	ds_read_b128 v[158:161], v148 offset:32768
	ds_read_b128 v[162:165], v148 offset:33792
	ds_read_b128 v[166:169], v148 offset:34816
	ds_read_b128 v[170:173], v148 offset:35840
	ds_read_b128 v[174:177], v148 offset:36864
	ds_read_b128 v[178:181], v148 offset:37888
	ds_read_b128 v[182:185], v148 offset:38912
	ds_read_b128 v[186:189], v148 offset:39936
	global_load_lds_dwordx4 v[190:191], off
	v_lshl_add_u64 v[190:191], v[208:209], 0, s[18:19]
	s_mov_b32 m0, s36
	s_nop 0
	global_load_lds_dwordx4 v[190:191], off
	s_waitcnt lgkmcnt(8)
	s_barrier
	s_waitcnt lgkmcnt(0)
	s_setprio 1
	s_waitcnt lgkmcnt(0)
	v_mfma_f32_16x16x32_bf16 v[124:127], v[138:141], v[158:161], v[124:127]
	v_mfma_f32_16x16x32_bf16 v[120:123], v[150:153], v[158:161], v[120:123]
	v_mfma_f32_16x16x32_bf16 v[108:111], v[138:141], v[166:169], v[108:111]
	v_mfma_f32_16x16x32_bf16 v[104:107], v[150:153], v[166:169], v[104:107]
	v_mfma_f32_16x16x32_bf16 v[92:95], v[138:141], v[174:177], v[92:95]
	v_mfma_f32_16x16x32_bf16 v[88:91], v[150:153], v[174:177], v[88:91]
	v_mfma_f32_16x16x32_bf16 v[76:79], v[138:141], v[182:185], v[76:79]
	v_mfma_f32_16x16x32_bf16 v[72:75], v[150:153], v[182:185], v[72:75]
	v_mfma_f32_16x16x32_bf16 v[124:127], v[142:145], v[162:165], v[124:127]
	v_mfma_f32_16x16x32_bf16 v[120:123], v[154:157], v[162:165], v[120:123]
	v_mfma_f32_16x16x32_bf16 v[108:111], v[142:145], v[170:173], v[108:111]
	v_mfma_f32_16x16x32_bf16 v[104:107], v[154:157], v[170:173], v[104:107]
	v_mfma_f32_16x16x32_bf16 v[92:95], v[142:145], v[178:181], v[92:95]
	v_mfma_f32_16x16x32_bf16 v[88:91], v[154:157], v[178:181], v[88:91]
	v_mfma_f32_16x16x32_bf16 v[76:79], v[142:145], v[186:189], v[76:79]
	v_mfma_f32_16x16x32_bf16 v[72:75], v[154:157], v[186:189], v[72:75]
	s_setprio 0
	s_barrier
	s_add_i32 s59, 0, 0x1c000
	s_add_i32 s58, s58, s31
	v_add_u32_e32 v202, s59, v146
	v_lshl_add_u64 v[210:211], v[206:207], 0, s[26:27]
	s_mov_b32 m0, s58
	ds_read_b128 v[190:193], v202
	ds_read_b128 v[194:197], v202 offset:1024
	ds_read_b128 v[198:201], v202 offset:2048
	ds_read_b128 v[202:205], v202 offset:3072
	global_load_lds_dwordx4 v[210:211], off
	v_lshl_add_u64 v[210:211], v[206:207], 0, s[42:43]
	s_add_i32 m0, s58, 0x2000
	s_nop 0
	global_load_lds_dwordx4 v[210:211], off
	s_barrier
	s_waitcnt lgkmcnt(0)
	s_setprio 1
	s_waitcnt lgkmcnt(0)
	v_mfma_f32_16x16x32_bf16 v[116:119], v[190:193], v[158:161], v[116:119]
	v_mfma_f32_16x16x32_bf16 v[112:115], v[198:201], v[158:161], v[112:115]
	v_mfma_f32_16x16x32_bf16 v[100:103], v[190:193], v[166:169], v[100:103]
	v_mfma_f32_16x16x32_bf16 v[96:99], v[198:201], v[166:169], v[96:99]
	v_mfma_f32_16x16x32_bf16 v[84:87], v[190:193], v[174:177], v[84:87]
	v_mfma_f32_16x16x32_bf16 v[80:83], v[198:201], v[174:177], v[80:83]
	v_mfma_f32_16x16x32_bf16 v[68:71], v[190:193], v[182:185], v[68:71]
	v_mfma_f32_16x16x32_bf16 v[64:67], v[198:201], v[182:185], v[64:67]
	v_mfma_f32_16x16x32_bf16 v[116:119], v[194:197], v[162:165], v[116:119]
	v_mfma_f32_16x16x32_bf16 v[112:115], v[202:205], v[162:165], v[112:115]
	v_mfma_f32_16x16x32_bf16 v[100:103], v[194:197], v[170:173], v[100:103]
	v_mfma_f32_16x16x32_bf16 v[96:99], v[202:205], v[170:173], v[96:99]
	v_mfma_f32_16x16x32_bf16 v[84:87], v[194:197], v[178:181], v[84:87]
	v_mfma_f32_16x16x32_bf16 v[80:83], v[202:205], v[178:181], v[80:83]
	v_mfma_f32_16x16x32_bf16 v[68:71], v[194:197], v[186:189], v[68:71]
	v_mfma_f32_16x16x32_bf16 v[64:67], v[202:205], v[186:189], v[64:67]
	s_setprio 0
	s_mov_b32 m0, s38
	v_lshl_add_u64 v[210:211], v[208:209], 0, s[26:27]
	s_barrier
	ds_read_b128 v[158:161], v148 offset:49152
	ds_read_b128 v[162:165], v148 offset:50176
	ds_read_b128 v[166:169], v148 offset:51200
	ds_read_b128 v[170:173], v148 offset:52224
	ds_read_b128 v[174:177], v148 offset:53248
	ds_read_b128 v[178:181], v148 offset:54272
	ds_read_b128 v[182:185], v148 offset:55296
	ds_read_b128 v[186:189], v148 offset:56320
	global_load_lds_dwordx4 v[210:211], off
	v_lshl_add_u64 v[208:209], v[208:209], 0, s[42:43]
	s_mov_b32 m0, s39
	s_nop 0
	global_load_lds_dwordx4 v[208:209], off
	s_barrier
; __device__ __forceinline__ int otid() { int t = (int)__builtin_amdgcn_workitem_id_x(); asm volatile("" : "+v"(t)); return t; }
; #define PG8_STAGE(bufoff, gbase, voff) do { _Pragma("unroll") for (int _i = 0; _i < 2; ++_i) \
;         __builtin_amdgcn_global_load_lds((const unsigned*)((const char*)(gbase) + (size_t)_i * r64##voff + (voff)), (LAS unsigned*)(lds + (bufoff) + ldsw + _i * 8192), 16, 0, 0); } while (0)
; #define PG8_WAIT_V(n) asm volatile("s_waitcnt vmcnt(" #n ")" ::: "memory")
; #define PG8_WAIT_L(n) asm volatile("s_waitcnt lgkmcnt(" #n ")" ::: "memory")
; #define PG8_BAR __builtin_amdgcn_s_barrier()
; template <class Epi, class Sched>
; __device__ __forceinline__ void gemm_phase(LAS unsigned char* lds, const Gemm g, const Sched& S, const Epi& E) {
;     ...
;             PG8_WAIT_V(6); PG8_BAR; PG8_MMA(1, 1, At, B1); PG8_BAR;
;             PG8_LDB(B0, 1, 0); PG8_SCHED; PG8_LDA(At, 1, 0); PG8_STAGE(PG8_SA(0, 1), a2 + hstepA, voffA);
;             PG8_WAIT_L(8); PG8_BAR; PG8_WAIT_L(0); PG8_MMA(0, 0, At, B0); PG8_BAR; PG8_SCHED;
;             PG8_LDB(B1, 1, 1); PG8_STAGE(PG8_SB(1, 0), b3, voffB);
;             PG8_BAR; PG8_WAIT_L(0); PG8_MMA(0, 1, At, B1); PG8_BAR;
;             PG8_LDA(At, 1, 1); PG8_STAGE(PG8_SA(1, 0), a3, voffA);
;             PG8_BAR; PG8_WAIT_L(0); PG8_MMA(1, 0, At, B0); PG8_BAR; PG8_SCHED;
;             PG8_STAGE(PG8_SB(1, 1), b3 + hstepB, voffB);
;             PG8_WAIT_V(6); PG8_BAR; PG8_MMA(1, 1, At, B1); PG8_BAR;
;     __device__ __forceinline__ void operator()(const f32x4 (&acc)[2][2][4][2], const pg8::Unit& u, int wr_, int wc_, int fr_, int fq_) const {
;         const int t2_ = otid(), wr = t2_ >> 8, wc = (t2_ >> 6) & 3, fr = t2_ & 15, fq = (t2_ >> 4) & 3; (void)wr_; (void)wc_; (void)fr_; (void)fq_;
;         const int row0 = u.pm * 256 + wr * 64 + fr, col0 = u.pn * 256 + wc * 32 + 8 * fq;
; #pragma unroll
;         for (int ai = 0; ai < 2; ++ai)
; #pragma unroll
;             for (int m = 0; m < 4; ++m) { const int row = row0 + ai * 128 + m * 16;
; #pragma unroll
;                 for (int bj = 0; bj < 2; ++bj) { const int col = col0 + bj * 128;
;                     const f32x4 b0 = *(const f32x4*)(bias + col), b1 = *(const f32x4*)(bias + col + 4);
;                     const f32x4 v0 = acc[ai][bj][m][0] + b0, v1 = acc[ai][bj][m][1] + b1;
;                     const u32x4 z = *(const u32x4*)(Z + (size_t)row * 512 + col);
	s_waitcnt lgkmcnt(0)
	s_setprio 1
	s_waitcnt lgkmcnt(0)
	v_mfma_f32_16x16x32_bf16 v[60:63], v[138:141], v[158:161], v[60:63]
	v_mfma_f32_16x16x32_bf16 v[56:59], v[150:153], v[158:161], v[56:59]
	v_mfma_f32_16x16x32_bf16 v[44:47], v[138:141], v[166:169], v[44:47]
	v_mfma_f32_16x16x32_bf16 v[40:43], v[150:153], v[166:169], v[40:43]
	v_mfma_f32_16x16x32_bf16 v[28:31], v[138:141], v[174:177], v[28:31]
	v_mfma_f32_16x16x32_bf16 v[24:27], v[150:153], v[174:177], v[24:27]
	v_mfma_f32_16x16x32_bf16 v[12:15], v[138:141], v[182:185], v[12:15]
	v_mfma_f32_16x16x32_bf16 v[8:11], v[150:153], v[182:185], v[8:11]
	v_mfma_f32_16x16x32_bf16 v[60:63], v[142:145], v[162:165], v[60:63]
	v_mfma_f32_16x16x32_bf16 v[56:59], v[154:157], v[162:165], v[56:59]
	v_mfma_f32_16x16x32_bf16 v[44:47], v[142:145], v[170:173], v[44:47]
	v_mfma_f32_16x16x32_bf16 v[40:43], v[154:157], v[170:173], v[40:43]
	v_mfma_f32_16x16x32_bf16 v[28:31], v[142:145], v[178:181], v[28:31]
	v_mfma_f32_16x16x32_bf16 v[24:27], v[154:157], v[178:181], v[24:27]
	v_mfma_f32_16x16x32_bf16 v[12:15], v[142:145], v[186:189], v[12:15]
	v_mfma_f32_16x16x32_bf16 v[8:11], v[154:157], v[186:189], v[8:11]
	s_setprio 0
	s_barrier
	s_add_i32 s58, s59, s31
	v_lshl_add_u64 v[138:139], v[206:207], 0, s[44:45]
	s_mov_b32 m0, s58
	s_nop 0
	global_load_lds_dwordx4 v[138:139], off
	v_lshl_add_u64 v[138:139], v[206:207], 0, s[46:47]
	s_add_i32 m0, s58, 0x2000
	s_nop 0
	global_load_lds_dwordx4 v[138:139], off
	s_waitcnt vmcnt(6)
	s_barrier
	s_setprio 1
	v_mfma_f32_16x16x32_bf16 v[52:55], v[190:193], v[158:161], v[52:55]
	v_mfma_f32_16x16x32_bf16 v[48:51], v[198:201], v[158:161], v[48:51]
	v_mfma_f32_16x16x32_bf16 v[36:39], v[190:193], v[166:169], v[36:39]
	v_mfma_f32_16x16x32_bf16 v[32:35], v[198:201], v[166:169], v[32:35]
	v_mfma_f32_16x16x32_bf16 v[20:23], v[190:193], v[174:177], v[20:23]
	v_mfma_f32_16x16x32_bf16 v[16:19], v[198:201], v[174:177], v[16:19]
	v_mfma_f32_16x16x32_bf16 v[4:7], v[190:193], v[182:185], v[4:7]
	v_mfma_f32_16x16x32_bf16 v[0:3], v[198:201], v[182:185], v[0:3]
	v_mfma_f32_16x16x32_bf16 v[52:55], v[194:197], v[162:165], v[52:55]
	v_mfma_f32_16x16x32_bf16 v[48:51], v[202:205], v[162:165], v[48:51]
	v_mfma_f32_16x16x32_bf16 v[36:39], v[194:197], v[170:173], v[36:39]
	v_mfma_f32_16x16x32_bf16 v[32:35], v[202:205], v[170:173], v[32:35]
	v_mfma_f32_16x16x32_bf16 v[20:23], v[194:197], v[178:181], v[20:23]
	v_mfma_f32_16x16x32_bf16 v[16:19], v[202:205], v[178:181], v[16:19]
	v_mfma_f32_16x16x32_bf16 v[4:7], v[194:197], v[186:189], v[4:7]
	v_mfma_f32_16x16x32_bf16 v[0:3], v[202:205], v[186:189], v[0:3]
	s_setprio 0
	s_add_i32 s57, s57, 2
	s_add_u32 s6, s6, 0x100
	s_addc_u32 s7, s7, 0
	s_add_u32 s8, s8, 0x100
	s_addc_u32 s9, s9, 0
	s_cmp_gt_u32 s57, 5
	s_barrier
	s_cbranch_scc0 .LBB0_446
	v_mov_b32_e32 v142, v222
	s_lshl_b32 s4, s4, 8
	v_lshrrev_b32_e32 v138, 1, v142
	v_and_b32_e32 v138, 0x78, v138
	v_lshl_or_b32 v140, s5, 8, v138
	v_ashrrev_i32_e32 v141, 31, v140
	v_lshl_add_u64 v[138:139], v[140:141], 2, s[20:21]
	v_ashrrev_i32_e32 v143, 2, v142
	v_and_b32_e32 v143, 0xffffffc0, v143
	v_and_or_b32 v142, v142, 15, s4
	v_add_u32_e32 v142, v142, v143
	v_ashrrev_i32_e32 v143, 31, v142
	v_lshlrev_b64 v[144:145], 10, v[142:143]
	v_lshl_add_u64 v[144:145], s[22:23], 0, v[144:145]
	v_lshlrev_b64 v[140:141], 1, v[140:141]
	v_lshl_add_u64 v[144:145], v[144:145], 0, v[140:141]
	v_lshlrev_b64 v[162:163], 12, v[142:143]
	s_mov_b64 s[8:9], s[54:55]
	s_mov_b64 s[6:7], s[52:53]
	s_and_b64 vcc, exec, s[2:3]
	s_mov_b32 s5, s48
	s_mov_b32 s4, s50
	v_lshl_add_u64 v[162:163], s[24:25], 0, v[162:163]
	v_lshl_add_u64 v[162:163], v[162:163], 0, v[140:141]
	s_mov_b32 s99, 0
	global_load_dwordx4 v[150:153], v[138:139], off
	global_load_dwordx4 v[154:157], v[138:139], off offset:16
	global_load_dwordx4 v[158:161], v[138:139], off offset:512
	global_load_dwordx4 v[164:167], v[138:139], off offset:528
	global_load_dwordx4 v[168:171], v[144:145], off
	global_load_dwordx4 v[172:175], v[144:145], off offset:256
	s_mov_b32 s98, 0x4000
	v_lshl_add_u64 v[144:145], v[144:145], 0, s[98:99]
	global_load_dwordx4 v[176:179], v[144:145], off
	global_load_dwordx4 v[180:183], v[144:145], off offset:256
	s_mov_b32 s98, 0x4000
	v_lshl_add_u64 v[144:145], v[144:145], 0, s[98:99]
	global_load_dwordx4 v[184:187], v[144:145], off
	global_load_dwordx4 v[188:191], v[144:145], off offset:256
	s_mov_b32 s98, 0x4000
	v_lshl_add_u64 v[144:145], v[144:145], 0, s[98:99]
	global_load_dwordx4 v[192:195], v[144:145], off
	global_load_dwordx4 v[196:199], v[144:145], off offset:256
	s_mov_b32 s98, 0x14000
	v_lshl_add_u64 v[144:145], v[144:145], 0, s[98:99]
	global_load_dwordx4 v[200:203], v[144:145], off
	global_load_dwordx4 v[204:207], v[144:145], off offset:256
	s_mov_b32 s98, 0x4000
	v_lshl_add_u64 v[144:145], v[144:145], 0, s[98:99]
	global_load_dwordx4 v[208:211], v[144:145], off
	global_load_dwordx4 v[212:215], v[144:145], off offset:256
	s_mov_b32 s98, 0x4000
	v_lshl_add_u64 v[144:145], v[144:145], 0, s[98:99]
	global_load_dwordx4 v[216:219], v[144:145], off
	global_load_dwordx4 v[224:227], v[144:145], off offset:256
	s_mov_b32 s98, 0x4000
	v_lshl_add_u64 v[144:145], v[144:145], 0, s[98:99]
	global_load_dwordx4 v[228:231], v[144:145], off
	global_load_dwordx4 v[232:235], v[144:145], off offset:256
	s_waitcnt vmcnt(0)
; __device__ __forceinline__ unsigned cvt_pk_bf16(float lo, float hi) { unsigned r; asm("v_cvt_pk_bf16_f32 %0, %1, %2" : "=v"(r) : "v"(lo), "v"(hi)); return r; }
; __device__ __forceinline__ float bflo(unsigned w) { return __uint_as_float(w << 16); }
; __device__ __forceinline__ float bfhi(unsigned w) { return __uint_as_float(w & 0xffff0000u); }
; __device__ __forceinline__ float sigmoidf_(float x) { return 1.f / (1.f + __expf(-x)); }
;     __device__ __forceinline__ void operator()(const f32x4 (&acc)[2][2][4][2], const pg8::Unit& u, int wr_, int wc_, int fr_, int fq_) const {
;     ...
;                 for (int bj = 0; bj < 2; ++bj) { const int col = col0 + bj * 128;
;                     const f32x4 b0 = *(const f32x4*)(bias + col), b1 = *(const f32x4*)(bias + col + 4);
;                     const f32x4 v0 = acc[ai][bj][m][0] + b0, v1 = acc[ai][bj][m][1] + b1;
;                     const u32x4 z = *(const u32x4*)(Z + (size_t)row * 512 + col);
;                     u32x4 w;
;                     w.x = cvt_pk_bf16(bflo(z.x) * sigmoidf_(v0[0]), bfhi(z.x) * sigmoidf_(v0[1]));
;                     w.y = cvt_pk_bf16(bflo(z.y) * sigmoidf_(v0[2]), bfhi(z.y) * sigmoidf_(v0[3]));
;                     w.z = cvt_pk_bf16(bflo(z.z) * sigmoidf_(v1[0]), bfhi(z.z) * sigmoidf_(v1[1]));
;                     w.w = cvt_pk_bf16(bflo(z.w) * sigmoidf_(v1[2]), bfhi(z.w) * sigmoidf_(v1[3]));
;                     *(u32x4*)(MIX + (size_t)row * 2048 + 1536 + col) = w; } }
	v_pk_add_f32 v[124:125], v[124:125], v[150:151]
	v_pk_add_f32 v[126:127], v[126:127], v[152:153]
	v_pk_add_f32 v[120:121], v[120:121], v[154:155]
	v_pk_add_f32 v[122:123], v[122:123], v[156:157]
	v_mul_f32_e32 v124, 0xbfb8aa3b, v124
	v_mul_f32_e32 v125, 0xbfb8aa3b, v125
	v_mul_f32_e32 v126, 0xbfb8aa3b, v126
	v_mul_f32_e32 v127, 0xbfb8aa3b, v127
	v_mul_f32_e32 v120, 0xbfb8aa3b, v120
	v_mul_f32_e32 v121, 0xbfb8aa3b, v121
	v_mul_f32_e32 v122, 0xbfb8aa3b, v122
	v_mul_f32_e32 v123, 0xbfb8aa3b, v123
	v_exp_f32_e32 v124, v124
	v_exp_f32_e32 v125, v125
	v_exp_f32_e32 v126, v126
	v_exp_f32_e32 v127, v127
	v_exp_f32_e32 v120, v120
	v_exp_f32_e32 v121, v121
	v_exp_f32_e32 v122, v122
	v_exp_f32_e32 v123, v123
	v_add_f32_e32 v124, 1.0, v124
	v_add_f32_e32 v125, 1.0, v125
	v_add_f32_e32 v126, 1.0, v126
	v_add_f32_e32 v127, 1.0, v127
	v_add_f32_e32 v120, 1.0, v120
	v_add_f32_e32 v121, 1.0, v121
	v_add_f32_e32 v122, 1.0, v122
	v_add_f32_e32 v123, 1.0, v123
	v_rcp_f32_e32 v124, v124
	v_rcp_f32_e32 v125, v125
	v_rcp_f32_e32 v126, v126
	v_rcp_f32_e32 v127, v127
	v_rcp_f32_e32 v120, v120
	v_rcp_f32_e32 v121, v121
	v_rcp_f32_e32 v122, v122
	v_rcp_f32_e32 v123, v123
	v_lshlrev_b32_e32 v236, 16, v168
	v_and_b32_e32 v237, 0xffff0000, v168
	v_lshlrev_b32_e32 v238, 16, v169
	v_and_b32_e32 v239, 0xffff0000, v169
	v_lshlrev_b32_e32 v240, 16, v170
	v_and_b32_e32 v241, 0xffff0000, v170
	v_lshlrev_b32_e32 v242, 16, v171
	v_and_b32_e32 v243, 0xffff0000, v171
	v_mul_f32_e32 v124, v124, v236
	v_mul_f32_e32 v125, v125, v237
	v_mul_f32_e32 v126, v126, v238
	v_mul_f32_e32 v127, v127, v239
	v_mul_f32_e32 v120, v120, v240
	v_mul_f32_e32 v121, v121, v241
	v_mul_f32_e32 v122, v122, v242
	v_mul_f32_e32 v123, v123, v243
	v_cvt_pk_bf16_f32 v124, v124, v125
	v_cvt_pk_bf16_f32 v125, v126, v127
	v_cvt_pk_bf16_f32 v126, v120, v121
	v_cvt_pk_bf16_f32 v127, v122, v123
	global_store_dwordx4 v[162:163], v[124:127], off offset:3072
	v_pk_add_f32 v[116:117], v[116:117], v[158:159]
	v_pk_add_f32 v[118:119], v[118:119], v[160:161]
	v_pk_add_f32 v[112:113], v[112:113], v[164:165]
	v_pk_add_f32 v[114:115], v[114:115], v[166:167]
	v_mul_f32_e32 v116, 0xbfb8aa3b, v116
	v_mul_f32_e32 v117, 0xbfb8aa3b, v117
	v_mul_f32_e32 v118, 0xbfb8aa3b, v118
	v_mul_f32_e32 v119, 0xbfb8aa3b, v119
	v_mul_f32_e32 v112, 0xbfb8aa3b, v112
	v_mul_f32_e32 v113, 0xbfb8aa3b, v113
	v_mul_f32_e32 v114, 0xbfb8aa3b, v114
	v_mul_f32_e32 v115, 0xbfb8aa3b, v115
	v_exp_f32_e32 v116, v116
	v_exp_f32_e32 v117, v117
	v_exp_f32_e32 v118, v118
	v_exp_f32_e32 v119, v119
	v_exp_f32_e32 v112, v112
	v_exp_f32_e32 v113, v113
	v_exp_f32_e32 v114, v114
	v_exp_f32_e32 v115, v115
	v_add_f32_e32 v116, 1.0, v116
	v_add_f32_e32 v117, 1.0, v117
	v_add_f32_e32 v118, 1.0, v118
	v_add_f32_e32 v119, 1.0, v119
	v_add_f32_e32 v112, 1.0, v112
	v_add_f32_e32 v113, 1.0, v113
	v_add_f32_e32 v114, 1.0, v114
	v_add_f32_e32 v115, 1.0, v115
	v_rcp_f32_e32 v116, v116
	v_rcp_f32_e32 v117, v117
	v_rcp_f32_e32 v118, v118
	v_rcp_f32_e32 v119, v119
	v_rcp_f32_e32 v112, v112
	v_rcp_f32_e32 v113, v113
	v_rcp_f32_e32 v114, v114
	v_rcp_f32_e32 v115, v115
	v_lshlrev_b32_e32 v236, 16, v172
	v_and_b32_e32 v237, 0xffff0000, v172
	v_lshlrev_b32_e32 v238, 16, v173
	v_and_b32_e32 v239, 0xffff0000, v173
	v_lshlrev_b32_e32 v240, 16, v174
	v_and_b32_e32 v241, 0xffff0000, v174
	v_lshlrev_b32_e32 v242, 16, v175
	v_and_b32_e32 v243, 0xffff0000, v175
	v_mul_f32_e32 v116, v116, v236
	v_mul_f32_e32 v117, v117, v237
	v_mul_f32_e32 v118, v118, v238
	v_mul_f32_e32 v119, v119, v239
	v_mul_f32_e32 v112, v112, v240
	v_mul_f32_e32 v113, v113, v241
	v_mul_f32_e32 v114, v114, v242
	v_mul_f32_e32 v115, v115, v243
	v_cvt_pk_bf16_f32 v116, v116, v117
	v_cvt_pk_bf16_f32 v117, v118, v119
	v_cvt_pk_bf16_f32 v118, v112, v113
	v_cvt_pk_bf16_f32 v119, v114, v115
	global_store_dwordx4 v[162:163], v[116:119], off offset:3328
	s_mov_b32 s98, 0x10000
	v_lshl_add_u64 v[162:163], v[162:163], 0, s[98:99]
	v_pk_add_f32 v[108:109], v[108:109], v[150:151]
	v_pk_add_f32 v[110:111], v[110:111], v[152:153]
	v_pk_add_f32 v[104:105], v[104:105], v[154:155]
	v_pk_add_f32 v[106:107], v[106:107], v[156:157]
	v_mul_f32_e32 v108, 0xbfb8aa3b, v108
	v_mul_f32_e32 v109, 0xbfb8aa3b, v109
	v_mul_f32_e32 v110, 0xbfb8aa3b, v110
	v_mul_f32_e32 v111, 0xbfb8aa3b, v111
	v_mul_f32_e32 v104, 0xbfb8aa3b, v104
	v_mul_f32_e32 v105, 0xbfb8aa3b, v105
	v_mul_f32_e32 v106, 0xbfb8aa3b, v106
	v_mul_f32_e32 v107, 0xbfb8aa3b, v107
	v_exp_f32_e32 v108, v108
	v_exp_f32_e32 v109, v109
	v_exp_f32_e32 v110, v110
	v_exp_f32_e32 v111, v111
	v_exp_f32_e32 v104, v104
	v_exp_f32_e32 v105, v105
	v_exp_f32_e32 v106, v106
	v_exp_f32_e32 v107, v107
	v_add_f32_e32 v108, 1.0, v108
	v_add_f32_e32 v109, 1.0, v109
	v_add_f32_e32 v110, 1.0, v110
	v_add_f32_e32 v111, 1.0, v111
	v_add_f32_e32 v104, 1.0, v104
	v_add_f32_e32 v105, 1.0, v105
	v_add_f32_e32 v106, 1.0, v106
	v_add_f32_e32 v107, 1.0, v107
	v_rcp_f32_e32 v108, v108
	v_rcp_f32_e32 v109, v109
	v_rcp_f32_e32 v110, v110
	v_rcp_f32_e32 v111, v111
	v_rcp_f32_e32 v104, v104
	v_rcp_f32_e32 v105, v105
	v_rcp_f32_e32 v106, v106
	v_rcp_f32_e32 v107, v107
	v_lshlrev_b32_e32 v236, 16, v176
	v_and_b32_e32 v237, 0xffff0000, v176
	v_lshlrev_b32_e32 v238, 16, v177
	v_and_b32_e32 v239, 0xffff0000, v177
	v_lshlrev_b32_e32 v240, 16, v178
	v_and_b32_e32 v241, 0xffff0000, v178
	v_lshlrev_b32_e32 v242, 16, v179
	v_and_b32_e32 v243, 0xffff0000, v179
	v_mul_f32_e32 v108, v108, v236
	v_mul_f32_e32 v109, v109, v237
	v_mul_f32_e32 v110, v110, v238
	v_mul_f32_e32 v111, v111, v239
	v_mul_f32_e32 v104, v104, v240
	v_mul_f32_e32 v105, v105, v241
	v_mul_f32_e32 v106, v106, v242
	v_mul_f32_e32 v107, v107, v243
	v_cvt_pk_bf16_f32 v108, v108, v109
; __device__ __forceinline__ unsigned cvt_pk_bf16(float lo, float hi) { unsigned r; asm("v_cvt_pk_bf16_f32 %0, %1, %2" : "=v"(r) : "v"(lo), "v"(hi)); return r; }
; __device__ __forceinline__ float bflo(unsigned w) { return __uint_as_float(w << 16); }
; __device__ __forceinline__ float bfhi(unsigned w) { return __uint_as_float(w & 0xffff0000u); }
; __device__ __forceinline__ float sigmoidf_(float x) { return 1.f / (1.f + __expf(-x)); }
;     __device__ __forceinline__ void operator()(const f32x4 (&acc)[2][2][4][2], const pg8::Unit& u, int wr_, int wc_, int fr_, int fq_) const {
;     ...
;                 for (int bj = 0; bj < 2; ++bj) { const int col = col0 + bj * 128;
;                     const f32x4 b0 = *(const f32x4*)(bias + col), b1 = *(const f32x4*)(bias + col + 4);
;                     const f32x4 v0 = acc[ai][bj][m][0] + b0, v1 = acc[ai][bj][m][1] + b1;
;                     const u32x4 z = *(const u32x4*)(Z + (size_t)row * 512 + col);
;                     u32x4 w;
;                     w.x = cvt_pk_bf16(bflo(z.x) * sigmoidf_(v0[0]), bfhi(z.x) * sigmoidf_(v0[1]));
;                     w.y = cvt_pk_bf16(bflo(z.y) * sigmoidf_(v0[2]), bfhi(z.y) * sigmoidf_(v0[3]));
;                     w.z = cvt_pk_bf16(bflo(z.z) * sigmoidf_(v1[0]), bfhi(z.z) * sigmoidf_(v1[1]));
;                     w.w = cvt_pk_bf16(bflo(z.w) * sigmoidf_(v1[2]), bfhi(z.w) * sigmoidf_(v1[3]));
;                     *(u32x4*)(MIX + (size_t)row * 2048 + 1536 + col) = w; } }
	v_cvt_pk_bf16_f32 v109, v110, v111
	v_cvt_pk_bf16_f32 v110, v104, v105
	v_cvt_pk_bf16_f32 v111, v106, v107
	global_store_dwordx4 v[162:163], v[108:111], off offset:3072
	v_pk_add_f32 v[100:101], v[100:101], v[158:159]
	v_pk_add_f32 v[102:103], v[102:103], v[160:161]
	v_pk_add_f32 v[96:97], v[96:97], v[164:165]
	v_pk_add_f32 v[98:99], v[98:99], v[166:167]
	v_mul_f32_e32 v100, 0xbfb8aa3b, v100
	v_mul_f32_e32 v101, 0xbfb8aa3b, v101
	v_mul_f32_e32 v102, 0xbfb8aa3b, v102
	v_mul_f32_e32 v103, 0xbfb8aa3b, v103
	v_mul_f32_e32 v96, 0xbfb8aa3b, v96
	v_mul_f32_e32 v97, 0xbfb8aa3b, v97
	v_mul_f32_e32 v98, 0xbfb8aa3b, v98
	v_mul_f32_e32 v99, 0xbfb8aa3b, v99
	v_exp_f32_e32 v100, v100
	v_exp_f32_e32 v101, v101
	v_exp_f32_e32 v102, v102
	v_exp_f32_e32 v103, v103
	v_exp_f32_e32 v96, v96
	v_exp_f32_e32 v97, v97
	v_exp_f32_e32 v98, v98
	v_exp_f32_e32 v99, v99
	v_add_f32_e32 v100, 1.0, v100
	v_add_f32_e32 v101, 1.0, v101
	v_add_f32_e32 v102, 1.0, v102
	v_add_f32_e32 v103, 1.0, v103
	v_add_f32_e32 v96, 1.0, v96
	v_add_f32_e32 v97, 1.0, v97
	v_add_f32_e32 v98, 1.0, v98
	v_add_f32_e32 v99, 1.0, v99
	v_rcp_f32_e32 v100, v100
	v_rcp_f32_e32 v101, v101
	v_rcp_f32_e32 v102, v102
	v_rcp_f32_e32 v103, v103
	v_rcp_f32_e32 v96, v96
	v_rcp_f32_e32 v97, v97
	v_rcp_f32_e32 v98, v98
	v_rcp_f32_e32 v99, v99
	v_lshlrev_b32_e32 v236, 16, v180
	v_and_b32_e32 v237, 0xffff0000, v180
	v_lshlrev_b32_e32 v238, 16, v181
	v_and_b32_e32 v239, 0xffff0000, v181
	v_lshlrev_b32_e32 v240, 16, v182
	v_and_b32_e32 v241, 0xffff0000, v182
	v_lshlrev_b32_e32 v242, 16, v183
	v_and_b32_e32 v243, 0xffff0000, v183
	v_mul_f32_e32 v100, v100, v236
	v_mul_f32_e32 v101, v101, v237
	v_mul_f32_e32 v102, v102, v238
	v_mul_f32_e32 v103, v103, v239
	v_mul_f32_e32 v96, v96, v240
	v_mul_f32_e32 v97, v97, v241
	v_mul_f32_e32 v98, v98, v242
	v_mul_f32_e32 v99, v99, v243
	v_cvt_pk_bf16_f32 v100, v100, v101
	v_cvt_pk_bf16_f32 v101, v102, v103
	v_cvt_pk_bf16_f32 v102, v96, v97
	v_cvt_pk_bf16_f32 v103, v98, v99
	global_store_dwordx4 v[162:163], v[100:103], off offset:3328
	s_mov_b32 s98, 0x10000
	v_lshl_add_u64 v[162:163], v[162:163], 0, s[98:99]
	v_pk_add_f32 v[92:93], v[92:93], v[150:151]
	v_pk_add_f32 v[94:95], v[94:95], v[152:153]
	v_pk_add_f32 v[88:89], v[88:89], v[154:155]
	v_pk_add_f32 v[90:91], v[90:91], v[156:157]
	v_mul_f32_e32 v92, 0xbfb8aa3b, v92
	v_mul_f32_e32 v93, 0xbfb8aa3b, v93
	v_mul_f32_e32 v94, 0xbfb8aa3b, v94
	v_mul_f32_e32 v95, 0xbfb8aa3b, v95
	v_mul_f32_e32 v88, 0xbfb8aa3b, v88
	v_mul_f32_e32 v89, 0xbfb8aa3b, v89
	v_mul_f32_e32 v90, 0xbfb8aa3b, v90
	v_mul_f32_e32 v91, 0xbfb8aa3b, v91
	v_exp_f32_e32 v92, v92
	v_exp_f32_e32 v93, v93
	v_exp_f32_e32 v94, v94
	v_exp_f32_e32 v95, v95
	v_exp_f32_e32 v88, v88
	v_exp_f32_e32 v89, v89
	v_exp_f32_e32 v90, v90
	v_exp_f32_e32 v91, v91
	v_add_f32_e32 v92, 1.0, v92
	v_add_f32_e32 v93, 1.0, v93
	v_add_f32_e32 v94, 1.0, v94
	v_add_f32_e32 v95, 1.0, v95
	v_add_f32_e32 v88, 1.0, v88
	v_add_f32_e32 v89, 1.0, v89
	v_add_f32_e32 v90, 1.0, v90
	v_add_f32_e32 v91, 1.0, v91
	v_rcp_f32_e32 v92, v92
	v_rcp_f32_e32 v93, v93
	v_rcp_f32_e32 v94, v94
	v_rcp_f32_e32 v95, v95
	v_rcp_f32_e32 v88, v88
	v_rcp_f32_e32 v89, v89
	v_rcp_f32_e32 v90, v90
	v_rcp_f32_e32 v91, v91
	v_lshlrev_b32_e32 v236, 16, v184
	v_and_b32_e32 v237, 0xffff0000, v184
	v_lshlrev_b32_e32 v238, 16, v185
	v_and_b32_e32 v239, 0xffff0000, v185
	v_lshlrev_b32_e32 v240, 16, v186
	v_and_b32_e32 v241, 0xffff0000, v186
	v_lshlrev_b32_e32 v242, 16, v187
	v_and_b32_e32 v243, 0xffff0000, v187
	v_mul_f32_e32 v92, v92, v236
	v_mul_f32_e32 v93, v93, v237
	v_mul_f32_e32 v94, v94, v238
	v_mul_f32_e32 v95, v95, v239
	v_mul_f32_e32 v88, v88, v240
	v_mul_f32_e32 v89, v89, v241
	v_mul_f32_e32 v90, v90, v242
	v_mul_f32_e32 v91, v91, v243
	v_cvt_pk_bf16_f32 v92, v92, v93
	v_cvt_pk_bf16_f32 v93, v94, v95
	v_cvt_pk_bf16_f32 v94, v88, v89
	v_cvt_pk_bf16_f32 v95, v90, v91
	global_store_dwordx4 v[162:163], v[92:95], off offset:3072
	v_pk_add_f32 v[84:85], v[84:85], v[158:159]
	v_pk_add_f32 v[86:87], v[86:87], v[160:161]
	v_pk_add_f32 v[80:81], v[80:81], v[164:165]
	v_pk_add_f32 v[82:83], v[82:83], v[166:167]
	v_mul_f32_e32 v84, 0xbfb8aa3b, v84
	v_mul_f32_e32 v85, 0xbfb8aa3b, v85
	v_mul_f32_e32 v86, 0xbfb8aa3b, v86
	v_mul_f32_e32 v87, 0xbfb8aa3b, v87
	v_mul_f32_e32 v80, 0xbfb8aa3b, v80
	v_mul_f32_e32 v81, 0xbfb8aa3b, v81
	v_mul_f32_e32 v82, 0xbfb8aa3b, v82
	v_mul_f32_e32 v83, 0xbfb8aa3b, v83
	v_exp_f32_e32 v84, v84
	v_exp_f32_e32 v85, v85
	v_exp_f32_e32 v86, v86
	v_exp_f32_e32 v87, v87
	v_exp_f32_e32 v80, v80
	v_exp_f32_e32 v81, v81
	v_exp_f32_e32 v82, v82
	v_exp_f32_e32 v83, v83
	v_add_f32_e32 v84, 1.0, v84
	v_add_f32_e32 v85, 1.0, v85
	v_add_f32_e32 v86, 1.0, v86
	v_add_f32_e32 v87, 1.0, v87
	v_add_f32_e32 v80, 1.0, v80
	v_add_f32_e32 v81, 1.0, v81
	v_add_f32_e32 v82, 1.0, v82
	v_add_f32_e32 v83, 1.0, v83
	v_rcp_f32_e32 v84, v84
	v_rcp_f32_e32 v85, v85
	v_rcp_f32_e32 v86, v86
	v_rcp_f32_e32 v87, v87
	v_rcp_f32_e32 v80, v80
	v_rcp_f32_e32 v81, v81
	v_rcp_f32_e32 v82, v82
	v_rcp_f32_e32 v83, v83
	v_lshlrev_b32_e32 v236, 16, v188
	v_and_b32_e32 v237, 0xffff0000, v188
	v_lshlrev_b32_e32 v238, 16, v189
	v_and_b32_e32 v239, 0xffff0000, v189
	v_lshlrev_b32_e32 v240, 16, v190
	v_and_b32_e32 v241, 0xffff0000, v190
	v_lshlrev_b32_e32 v242, 16, v191
	v_and_b32_e32 v243, 0xffff0000, v191
	v_mul_f32_e32 v84, v84, v236
	v_mul_f32_e32 v85, v85, v237
	v_mul_f32_e32 v86, v86, v238
	v_mul_f32_e32 v87, v87, v239
	v_mul_f32_e32 v80, v80, v240
	v_mul_f32_e32 v81, v81, v241
	v_mul_f32_e32 v82, v82, v242
	v_mul_f32_e32 v83, v83, v243
	v_cvt_pk_bf16_f32 v84, v84, v85
	v_cvt_pk_bf16_f32 v85, v86, v87
	v_cvt_pk_bf16_f32 v86, v80, v81
	v_cvt_pk_bf16_f32 v87, v82, v83
; __device__ __forceinline__ unsigned cvt_pk_bf16(float lo, float hi) { unsigned r; asm("v_cvt_pk_bf16_f32 %0, %1, %2" : "=v"(r) : "v"(lo), "v"(hi)); return r; }
; __device__ __forceinline__ float bflo(unsigned w) { return __uint_as_float(w << 16); }
; __device__ __forceinline__ float bfhi(unsigned w) { return __uint_as_float(w & 0xffff0000u); }
; __device__ __forceinline__ float sigmoidf_(float x) { return 1.f / (1.f + __expf(-x)); }
;     __device__ __forceinline__ void operator()(const f32x4 (&acc)[2][2][4][2], const pg8::Unit& u, int wr_, int wc_, int fr_, int fq_) const {
;     ...
;                 for (int bj = 0; bj < 2; ++bj) { const int col = col0 + bj * 128;
;                     const f32x4 b0 = *(const f32x4*)(bias + col), b1 = *(const f32x4*)(bias + col + 4);
;                     const f32x4 v0 = acc[ai][bj][m][0] + b0, v1 = acc[ai][bj][m][1] + b1;
;                     const u32x4 z = *(const u32x4*)(Z + (size_t)row * 512 + col);
;                     u32x4 w;
;                     w.x = cvt_pk_bf16(bflo(z.x) * sigmoidf_(v0[0]), bfhi(z.x) * sigmoidf_(v0[1]));
;                     w.y = cvt_pk_bf16(bflo(z.y) * sigmoidf_(v0[2]), bfhi(z.y) * sigmoidf_(v0[3]));
;                     w.z = cvt_pk_bf16(bflo(z.z) * sigmoidf_(v1[0]), bfhi(z.z) * sigmoidf_(v1[1]));
;                     w.w = cvt_pk_bf16(bflo(z.w) * sigmoidf_(v1[2]), bfhi(z.w) * sigmoidf_(v1[3]));
;                     *(u32x4*)(MIX + (size_t)row * 2048 + 1536 + col) = w; } }
	global_store_dwordx4 v[162:163], v[84:87], off offset:3328
	s_mov_b32 s98, 0x10000
	v_lshl_add_u64 v[162:163], v[162:163], 0, s[98:99]
	v_pk_add_f32 v[76:77], v[76:77], v[150:151]
	v_pk_add_f32 v[78:79], v[78:79], v[152:153]
	v_pk_add_f32 v[72:73], v[72:73], v[154:155]
	v_pk_add_f32 v[74:75], v[74:75], v[156:157]
	v_mul_f32_e32 v76, 0xbfb8aa3b, v76
	v_mul_f32_e32 v77, 0xbfb8aa3b, v77
	v_mul_f32_e32 v78, 0xbfb8aa3b, v78
	v_mul_f32_e32 v79, 0xbfb8aa3b, v79
	v_mul_f32_e32 v72, 0xbfb8aa3b, v72
	v_mul_f32_e32 v73, 0xbfb8aa3b, v73
	v_mul_f32_e32 v74, 0xbfb8aa3b, v74
	v_mul_f32_e32 v75, 0xbfb8aa3b, v75
	v_exp_f32_e32 v76, v76
	v_exp_f32_e32 v77, v77
	v_exp_f32_e32 v78, v78
	v_exp_f32_e32 v79, v79
	v_exp_f32_e32 v72, v72
	v_exp_f32_e32 v73, v73
	v_exp_f32_e32 v74, v74
	v_exp_f32_e32 v75, v75
	v_add_f32_e32 v76, 1.0, v76
	v_add_f32_e32 v77, 1.0, v77
	v_add_f32_e32 v78, 1.0, v78
	v_add_f32_e32 v79, 1.0, v79
	v_add_f32_e32 v72, 1.0, v72
	v_add_f32_e32 v73, 1.0, v73
	v_add_f32_e32 v74, 1.0, v74
	v_add_f32_e32 v75, 1.0, v75
	v_rcp_f32_e32 v76, v76
	v_rcp_f32_e32 v77, v77
	v_rcp_f32_e32 v78, v78
	v_rcp_f32_e32 v79, v79
	v_rcp_f32_e32 v72, v72
	v_rcp_f32_e32 v73, v73
	v_rcp_f32_e32 v74, v74
	v_rcp_f32_e32 v75, v75
	v_lshlrev_b32_e32 v236, 16, v192
	v_and_b32_e32 v237, 0xffff0000, v192
	v_lshlrev_b32_e32 v238, 16, v193
	v_and_b32_e32 v239, 0xffff0000, v193
	v_lshlrev_b32_e32 v240, 16, v194
	v_and_b32_e32 v241, 0xffff0000, v194
	v_lshlrev_b32_e32 v242, 16, v195
	v_and_b32_e32 v243, 0xffff0000, v195
	v_mul_f32_e32 v76, v76, v236
	v_mul_f32_e32 v77, v77, v237
	v_mul_f32_e32 v78, v78, v238
	v_mul_f32_e32 v79, v79, v239
	v_mul_f32_e32 v72, v72, v240
	v_mul_f32_e32 v73, v73, v241
	v_mul_f32_e32 v74, v74, v242
	v_mul_f32_e32 v75, v75, v243
	v_cvt_pk_bf16_f32 v76, v76, v77
	v_cvt_pk_bf16_f32 v77, v78, v79
	v_cvt_pk_bf16_f32 v78, v72, v73
	v_cvt_pk_bf16_f32 v79, v74, v75
	global_store_dwordx4 v[162:163], v[76:79], off offset:3072
	v_pk_add_f32 v[68:69], v[68:69], v[158:159]
	v_pk_add_f32 v[70:71], v[70:71], v[160:161]
	v_pk_add_f32 v[64:65], v[64:65], v[164:165]
	v_pk_add_f32 v[66:67], v[66:67], v[166:167]
	v_mul_f32_e32 v68, 0xbfb8aa3b, v68
	v_mul_f32_e32 v69, 0xbfb8aa3b, v69
	v_mul_f32_e32 v70, 0xbfb8aa3b, v70
	v_mul_f32_e32 v71, 0xbfb8aa3b, v71
	v_mul_f32_e32 v64, 0xbfb8aa3b, v64
	v_mul_f32_e32 v65, 0xbfb8aa3b, v65
	v_mul_f32_e32 v66, 0xbfb8aa3b, v66
	v_mul_f32_e32 v67, 0xbfb8aa3b, v67
	v_exp_f32_e32 v68, v68
	v_exp_f32_e32 v69, v69
	v_exp_f32_e32 v70, v70
	v_exp_f32_e32 v71, v71
	v_exp_f32_e32 v64, v64
	v_exp_f32_e32 v65, v65
	v_exp_f32_e32 v66, v66
	v_exp_f32_e32 v67, v67
	v_add_f32_e32 v68, 1.0, v68
	v_add_f32_e32 v69, 1.0, v69
	v_add_f32_e32 v70, 1.0, v70
	v_add_f32_e32 v71, 1.0, v71
	v_add_f32_e32 v64, 1.0, v64
	v_add_f32_e32 v65, 1.0, v65
	v_add_f32_e32 v66, 1.0, v66
	v_add_f32_e32 v67, 1.0, v67
	v_rcp_f32_e32 v68, v68
	v_rcp_f32_e32 v69, v69
	v_rcp_f32_e32 v70, v70
	v_rcp_f32_e32 v71, v71
	v_rcp_f32_e32 v64, v64
	v_rcp_f32_e32 v65, v65
	v_rcp_f32_e32 v66, v66
	v_rcp_f32_e32 v67, v67
	v_lshlrev_b32_e32 v236, 16, v196
	v_and_b32_e32 v237, 0xffff0000, v196
	v_lshlrev_b32_e32 v238, 16, v197
	v_and_b32_e32 v239, 0xffff0000, v197
	v_lshlrev_b32_e32 v240, 16, v198
	v_and_b32_e32 v241, 0xffff0000, v198
	v_lshlrev_b32_e32 v242, 16, v199
	v_and_b32_e32 v243, 0xffff0000, v199
	v_mul_f32_e32 v68, v68, v236
	v_mul_f32_e32 v69, v69, v237
	v_mul_f32_e32 v70, v70, v238
	v_mul_f32_e32 v71, v71, v239
	v_mul_f32_e32 v64, v64, v240
	v_mul_f32_e32 v65, v65, v241
	v_mul_f32_e32 v66, v66, v242
	v_mul_f32_e32 v67, v67, v243
	v_cvt_pk_bf16_f32 v68, v68, v69
	v_cvt_pk_bf16_f32 v69, v70, v71
	v_cvt_pk_bf16_f32 v70, v64, v65
	v_cvt_pk_bf16_f32 v71, v66, v67
	global_store_dwordx4 v[162:163], v[68:71], off offset:3328
	s_mov_b32 s98, 0x50000
	v_lshl_add_u64 v[162:163], v[162:163], 0, s[98:99]
	v_pk_add_f32 v[60:61], v[60:61], v[150:151]
	v_pk_add_f32 v[62:63], v[62:63], v[152:153]
	v_pk_add_f32 v[56:57], v[56:57], v[154:155]
	v_pk_add_f32 v[58:59], v[58:59], v[156:157]
	v_mul_f32_e32 v60, 0xbfb8aa3b, v60
	v_mul_f32_e32 v61, 0xbfb8aa3b, v61
	v_mul_f32_e32 v62, 0xbfb8aa3b, v62
	v_mul_f32_e32 v63, 0xbfb8aa3b, v63
	v_mul_f32_e32 v56, 0xbfb8aa3b, v56
	v_mul_f32_e32 v57, 0xbfb8aa3b, v57
	v_mul_f32_e32 v58, 0xbfb8aa3b, v58
	v_mul_f32_e32 v59, 0xbfb8aa3b, v59
	v_exp_f32_e32 v60, v60
	v_exp_f32_e32 v61, v61
	v_exp_f32_e32 v62, v62
	v_exp_f32_e32 v63, v63
	v_exp_f32_e32 v56, v56
	v_exp_f32_e32 v57, v57
	v_exp_f32_e32 v58, v58
	v_exp_f32_e32 v59, v59
	v_add_f32_e32 v60, 1.0, v60
	v_add_f32_e32 v61, 1.0, v61
	v_add_f32_e32 v62, 1.0, v62
	v_add_f32_e32 v63, 1.0, v63
	v_add_f32_e32 v56, 1.0, v56
	v_add_f32_e32 v57, 1.0, v57
	v_add_f32_e32 v58, 1.0, v58
	v_add_f32_e32 v59, 1.0, v59
	v_rcp_f32_e32 v60, v60
	v_rcp_f32_e32 v61, v61
	v_rcp_f32_e32 v62, v62
	v_rcp_f32_e32 v63, v63
	v_rcp_f32_e32 v56, v56
	v_rcp_f32_e32 v57, v57
	v_rcp_f32_e32 v58, v58
	v_rcp_f32_e32 v59, v59
	v_lshlrev_b32_e32 v236, 16, v200
	v_and_b32_e32 v237, 0xffff0000, v200
	v_lshlrev_b32_e32 v238, 16, v201
	v_and_b32_e32 v239, 0xffff0000, v201
	v_lshlrev_b32_e32 v240, 16, v202
	v_and_b32_e32 v241, 0xffff0000, v202
	v_lshlrev_b32_e32 v242, 16, v203
	v_and_b32_e32 v243, 0xffff0000, v203
	v_mul_f32_e32 v60, v60, v236
	v_mul_f32_e32 v61, v61, v237
	v_mul_f32_e32 v62, v62, v238
	v_mul_f32_e32 v63, v63, v239
	v_mul_f32_e32 v56, v56, v240
	v_mul_f32_e32 v57, v57, v241
	v_mul_f32_e32 v58, v58, v242
	v_mul_f32_e32 v59, v59, v243
	v_cvt_pk_bf16_f32 v60, v60, v61
	v_cvt_pk_bf16_f32 v61, v62, v63
	v_cvt_pk_bf16_f32 v62, v56, v57
	v_cvt_pk_bf16_f32 v63, v58, v59
	global_store_dwordx4 v[162:163], v[60:63], off offset:3072
; __device__ __forceinline__ unsigned cvt_pk_bf16(float lo, float hi) { unsigned r; asm("v_cvt_pk_bf16_f32 %0, %1, %2" : "=v"(r) : "v"(lo), "v"(hi)); return r; }
; __device__ __forceinline__ float bflo(unsigned w) { return __uint_as_float(w << 16); }
; __device__ __forceinline__ float bfhi(unsigned w) { return __uint_as_float(w & 0xffff0000u); }
; __device__ __forceinline__ float sigmoidf_(float x) { return 1.f / (1.f + __expf(-x)); }
;     __device__ __forceinline__ void operator()(const f32x4 (&acc)[2][2][4][2], const pg8::Unit& u, int wr_, int wc_, int fr_, int fq_) const {
;     ...
;                 for (int bj = 0; bj < 2; ++bj) { const int col = col0 + bj * 128;
;                     const f32x4 b0 = *(const f32x4*)(bias + col), b1 = *(const f32x4*)(bias + col + 4);
;                     const f32x4 v0 = acc[ai][bj][m][0] + b0, v1 = acc[ai][bj][m][1] + b1;
;                     const u32x4 z = *(const u32x4*)(Z + (size_t)row * 512 + col);
;                     u32x4 w;
;                     w.x = cvt_pk_bf16(bflo(z.x) * sigmoidf_(v0[0]), bfhi(z.x) * sigmoidf_(v0[1]));
;                     w.y = cvt_pk_bf16(bflo(z.y) * sigmoidf_(v0[2]), bfhi(z.y) * sigmoidf_(v0[3]));
;                     w.z = cvt_pk_bf16(bflo(z.z) * sigmoidf_(v1[0]), bfhi(z.z) * sigmoidf_(v1[1]));
;                     w.w = cvt_pk_bf16(bflo(z.w) * sigmoidf_(v1[2]), bfhi(z.w) * sigmoidf_(v1[3]));
;                     *(u32x4*)(MIX + (size_t)row * 2048 + 1536 + col) = w; } }
	v_pk_add_f32 v[52:53], v[52:53], v[158:159]
	v_pk_add_f32 v[54:55], v[54:55], v[160:161]
	v_pk_add_f32 v[48:49], v[48:49], v[164:165]
	v_pk_add_f32 v[50:51], v[50:51], v[166:167]
	v_mul_f32_e32 v52, 0xbfb8aa3b, v52
	v_mul_f32_e32 v53, 0xbfb8aa3b, v53
	v_mul_f32_e32 v54, 0xbfb8aa3b, v54
	v_mul_f32_e32 v55, 0xbfb8aa3b, v55
	v_mul_f32_e32 v48, 0xbfb8aa3b, v48
	v_mul_f32_e32 v49, 0xbfb8aa3b, v49
	v_mul_f32_e32 v50, 0xbfb8aa3b, v50
	v_mul_f32_e32 v51, 0xbfb8aa3b, v51
	v_exp_f32_e32 v52, v52
	v_exp_f32_e32 v53, v53
	v_exp_f32_e32 v54, v54
	v_exp_f32_e32 v55, v55
	v_exp_f32_e32 v48, v48
	v_exp_f32_e32 v49, v49
	v_exp_f32_e32 v50, v50
	v_exp_f32_e32 v51, v51
	v_add_f32_e32 v52, 1.0, v52
	v_add_f32_e32 v53, 1.0, v53
	v_add_f32_e32 v54, 1.0, v54
	v_add_f32_e32 v55, 1.0, v55
	v_add_f32_e32 v48, 1.0, v48
	v_add_f32_e32 v49, 1.0, v49
	v_add_f32_e32 v50, 1.0, v50
	v_add_f32_e32 v51, 1.0, v51
	v_rcp_f32_e32 v52, v52
	v_rcp_f32_e32 v53, v53
	v_rcp_f32_e32 v54, v54
	v_rcp_f32_e32 v55, v55
	v_rcp_f32_e32 v48, v48
	v_rcp_f32_e32 v49, v49
	v_rcp_f32_e32 v50, v50
	v_rcp_f32_e32 v51, v51
	v_lshlrev_b32_e32 v236, 16, v204
	v_and_b32_e32 v237, 0xffff0000, v204
	v_lshlrev_b32_e32 v238, 16, v205
	v_and_b32_e32 v239, 0xffff0000, v205
	v_lshlrev_b32_e32 v240, 16, v206
	v_and_b32_e32 v241, 0xffff0000, v206
	v_lshlrev_b32_e32 v242, 16, v207
	v_and_b32_e32 v243, 0xffff0000, v207
	v_mul_f32_e32 v52, v52, v236
	v_mul_f32_e32 v53, v53, v237
	v_mul_f32_e32 v54, v54, v238
	v_mul_f32_e32 v55, v55, v239
	v_mul_f32_e32 v48, v48, v240
	v_mul_f32_e32 v49, v49, v241
	v_mul_f32_e32 v50, v50, v242
	v_mul_f32_e32 v51, v51, v243
	v_cvt_pk_bf16_f32 v52, v52, v53
	v_cvt_pk_bf16_f32 v53, v54, v55
	v_cvt_pk_bf16_f32 v54, v48, v49
	v_cvt_pk_bf16_f32 v55, v50, v51
	global_store_dwordx4 v[162:163], v[52:55], off offset:3328
	s_mov_b32 s98, 0x10000
	v_lshl_add_u64 v[162:163], v[162:163], 0, s[98:99]
	v_pk_add_f32 v[44:45], v[44:45], v[150:151]
	v_pk_add_f32 v[46:47], v[46:47], v[152:153]
	v_pk_add_f32 v[40:41], v[40:41], v[154:155]
	v_pk_add_f32 v[42:43], v[42:43], v[156:157]
	v_mul_f32_e32 v44, 0xbfb8aa3b, v44
	v_mul_f32_e32 v45, 0xbfb8aa3b, v45
	v_mul_f32_e32 v46, 0xbfb8aa3b, v46
	v_mul_f32_e32 v47, 0xbfb8aa3b, v47
	v_mul_f32_e32 v40, 0xbfb8aa3b, v40
	v_mul_f32_e32 v41, 0xbfb8aa3b, v41
	v_mul_f32_e32 v42, 0xbfb8aa3b, v42
	v_mul_f32_e32 v43, 0xbfb8aa3b, v43
	v_exp_f32_e32 v44, v44
	v_exp_f32_e32 v45, v45
	v_exp_f32_e32 v46, v46
	v_exp_f32_e32 v47, v47
	v_exp_f32_e32 v40, v40
	v_exp_f32_e32 v41, v41
	v_exp_f32_e32 v42, v42
	v_exp_f32_e32 v43, v43
	v_add_f32_e32 v44, 1.0, v44
	v_add_f32_e32 v45, 1.0, v45
	v_add_f32_e32 v46, 1.0, v46
	v_add_f32_e32 v47, 1.0, v47
	v_add_f32_e32 v40, 1.0, v40
	v_add_f32_e32 v41, 1.0, v41
	v_add_f32_e32 v42, 1.0, v42
	v_add_f32_e32 v43, 1.0, v43
	v_rcp_f32_e32 v44, v44
	v_rcp_f32_e32 v45, v45
	v_rcp_f32_e32 v46, v46
	v_rcp_f32_e32 v47, v47
	v_rcp_f32_e32 v40, v40
	v_rcp_f32_e32 v41, v41
	v_rcp_f32_e32 v42, v42
	v_rcp_f32_e32 v43, v43
	v_lshlrev_b32_e32 v236, 16, v208
	v_and_b32_e32 v237, 0xffff0000, v208
	v_lshlrev_b32_e32 v238, 16, v209
	v_and_b32_e32 v239, 0xffff0000, v209
	v_lshlrev_b32_e32 v240, 16, v210
	v_and_b32_e32 v241, 0xffff0000, v210
	v_lshlrev_b32_e32 v242, 16, v211
	v_and_b32_e32 v243, 0xffff0000, v211
	v_mul_f32_e32 v44, v44, v236
	v_mul_f32_e32 v45, v45, v237
	v_mul_f32_e32 v46, v46, v238
	v_mul_f32_e32 v47, v47, v239
	v_mul_f32_e32 v40, v40, v240
	v_mul_f32_e32 v41, v41, v241
	v_mul_f32_e32 v42, v42, v242
	v_mul_f32_e32 v43, v43, v243
	v_cvt_pk_bf16_f32 v44, v44, v45
	v_cvt_pk_bf16_f32 v45, v46, v47
	v_cvt_pk_bf16_f32 v46, v40, v41
	v_cvt_pk_bf16_f32 v47, v42, v43
	global_store_dwordx4 v[162:163], v[44:47], off offset:3072
	v_pk_add_f32 v[36:37], v[36:37], v[158:159]
	v_pk_add_f32 v[38:39], v[38:39], v[160:161]
	v_pk_add_f32 v[32:33], v[32:33], v[164:165]
	v_pk_add_f32 v[34:35], v[34:35], v[166:167]
	v_mul_f32_e32 v36, 0xbfb8aa3b, v36
	v_mul_f32_e32 v37, 0xbfb8aa3b, v37
	v_mul_f32_e32 v38, 0xbfb8aa3b, v38
	v_mul_f32_e32 v39, 0xbfb8aa3b, v39
	v_mul_f32_e32 v32, 0xbfb8aa3b, v32
	v_mul_f32_e32 v33, 0xbfb8aa3b, v33
	v_mul_f32_e32 v34, 0xbfb8aa3b, v34
	v_mul_f32_e32 v35, 0xbfb8aa3b, v35
	v_exp_f32_e32 v36, v36
	v_exp_f32_e32 v37, v37
	v_exp_f32_e32 v38, v38
	v_exp_f32_e32 v39, v39
	v_exp_f32_e32 v32, v32
	v_exp_f32_e32 v33, v33
	v_exp_f32_e32 v34, v34
	v_exp_f32_e32 v35, v35
	v_add_f32_e32 v36, 1.0, v36
	v_add_f32_e32 v37, 1.0, v37
	v_add_f32_e32 v38, 1.0, v38
	v_add_f32_e32 v39, 1.0, v39
	v_add_f32_e32 v32, 1.0, v32
	v_add_f32_e32 v33, 1.0, v33
	v_add_f32_e32 v34, 1.0, v34
	v_add_f32_e32 v35, 1.0, v35
	v_rcp_f32_e32 v36, v36
	v_rcp_f32_e32 v37, v37
	v_rcp_f32_e32 v38, v38
	v_rcp_f32_e32 v39, v39
	v_rcp_f32_e32 v32, v32
	v_rcp_f32_e32 v33, v33
	v_rcp_f32_e32 v34, v34
	v_rcp_f32_e32 v35, v35
	v_lshlrev_b32_e32 v236, 16, v212
	v_and_b32_e32 v237, 0xffff0000, v212
	v_lshlrev_b32_e32 v238, 16, v213
	v_and_b32_e32 v239, 0xffff0000, v213
	v_lshlrev_b32_e32 v240, 16, v214
	v_and_b32_e32 v241, 0xffff0000, v214
	v_lshlrev_b32_e32 v242, 16, v215
	v_and_b32_e32 v243, 0xffff0000, v215
	v_mul_f32_e32 v36, v36, v236
	v_mul_f32_e32 v37, v37, v237
	v_mul_f32_e32 v38, v38, v238
	v_mul_f32_e32 v39, v39, v239
	v_mul_f32_e32 v32, v32, v240
	v_mul_f32_e32 v33, v33, v241
	v_mul_f32_e32 v34, v34, v242
	v_mul_f32_e32 v35, v35, v243
	v_cvt_pk_bf16_f32 v36, v36, v37
	v_cvt_pk_bf16_f32 v37, v38, v39
	v_cvt_pk_bf16_f32 v38, v32, v33
	v_cvt_pk_bf16_f32 v39, v34, v35
	global_store_dwordx4 v[162:163], v[36:39], off offset:3328
	s_mov_b32 s98, 0x10000
	v_lshl_add_u64 v[162:163], v[162:163], 0, s[98:99]
	v_pk_add_f32 v[28:29], v[28:29], v[150:151]
	v_pk_add_f32 v[30:31], v[30:31], v[152:153]
; __device__ __forceinline__ unsigned cvt_pk_bf16(float lo, float hi) { unsigned r; asm("v_cvt_pk_bf16_f32 %0, %1, %2" : "=v"(r) : "v"(lo), "v"(hi)); return r; }
; __device__ __forceinline__ float bflo(unsigned w) { return __uint_as_float(w << 16); }
; __device__ __forceinline__ float bfhi(unsigned w) { return __uint_as_float(w & 0xffff0000u); }
; __device__ __forceinline__ float sigmoidf_(float x) { return 1.f / (1.f + __expf(-x)); }
;     __device__ __forceinline__ void operator()(const f32x4 (&acc)[2][2][4][2], const pg8::Unit& u, int wr_, int wc_, int fr_, int fq_) const {
;     ...
;                 for (int bj = 0; bj < 2; ++bj) { const int col = col0 + bj * 128;
;                     const f32x4 b0 = *(const f32x4*)(bias + col), b1 = *(const f32x4*)(bias + col + 4);
;                     const f32x4 v0 = acc[ai][bj][m][0] + b0, v1 = acc[ai][bj][m][1] + b1;
;                     const u32x4 z = *(const u32x4*)(Z + (size_t)row * 512 + col);
;                     u32x4 w;
;                     w.x = cvt_pk_bf16(bflo(z.x) * sigmoidf_(v0[0]), bfhi(z.x) * sigmoidf_(v0[1]));
;                     w.y = cvt_pk_bf16(bflo(z.y) * sigmoidf_(v0[2]), bfhi(z.y) * sigmoidf_(v0[3]));
;                     w.z = cvt_pk_bf16(bflo(z.z) * sigmoidf_(v1[0]), bfhi(z.z) * sigmoidf_(v1[1]));
;                     w.w = cvt_pk_bf16(bflo(z.w) * sigmoidf_(v1[2]), bfhi(z.w) * sigmoidf_(v1[3]));
;                     *(u32x4*)(MIX + (size_t)row * 2048 + 1536 + col) = w; } }
	v_pk_add_f32 v[24:25], v[24:25], v[154:155]
	v_pk_add_f32 v[26:27], v[26:27], v[156:157]
	v_mul_f32_e32 v28, 0xbfb8aa3b, v28
	v_mul_f32_e32 v29, 0xbfb8aa3b, v29
	v_mul_f32_e32 v30, 0xbfb8aa3b, v30
	v_mul_f32_e32 v31, 0xbfb8aa3b, v31
	v_mul_f32_e32 v24, 0xbfb8aa3b, v24
	v_mul_f32_e32 v25, 0xbfb8aa3b, v25
	v_mul_f32_e32 v26, 0xbfb8aa3b, v26
	v_mul_f32_e32 v27, 0xbfb8aa3b, v27
	v_exp_f32_e32 v28, v28
	v_exp_f32_e32 v29, v29
	v_exp_f32_e32 v30, v30
	v_exp_f32_e32 v31, v31
	v_exp_f32_e32 v24, v24
	v_exp_f32_e32 v25, v25
	v_exp_f32_e32 v26, v26
	v_exp_f32_e32 v27, v27
	v_add_f32_e32 v28, 1.0, v28
	v_add_f32_e32 v29, 1.0, v29
	v_add_f32_e32 v30, 1.0, v30
	v_add_f32_e32 v31, 1.0, v31
	v_add_f32_e32 v24, 1.0, v24
	v_add_f32_e32 v25, 1.0, v25
	v_add_f32_e32 v26, 1.0, v26
	v_add_f32_e32 v27, 1.0, v27
	v_rcp_f32_e32 v28, v28
	v_rcp_f32_e32 v29, v29
	v_rcp_f32_e32 v30, v30
	v_rcp_f32_e32 v31, v31
	v_rcp_f32_e32 v24, v24
	v_rcp_f32_e32 v25, v25
	v_rcp_f32_e32 v26, v26
	v_rcp_f32_e32 v27, v27
	v_lshlrev_b32_e32 v236, 16, v216
	v_and_b32_e32 v237, 0xffff0000, v216
	v_lshlrev_b32_e32 v238, 16, v217
	v_and_b32_e32 v239, 0xffff0000, v217
	v_lshlrev_b32_e32 v240, 16, v218
	v_and_b32_e32 v241, 0xffff0000, v218
	v_lshlrev_b32_e32 v242, 16, v219
	v_and_b32_e32 v243, 0xffff0000, v219
	v_mul_f32_e32 v28, v28, v236
	v_mul_f32_e32 v29, v29, v237
	v_mul_f32_e32 v30, v30, v238
	v_mul_f32_e32 v31, v31, v239
	v_mul_f32_e32 v24, v24, v240
	v_mul_f32_e32 v25, v25, v241
	v_mul_f32_e32 v26, v26, v242
	v_mul_f32_e32 v27, v27, v243
	v_cvt_pk_bf16_f32 v28, v28, v29
	v_cvt_pk_bf16_f32 v29, v30, v31
	v_cvt_pk_bf16_f32 v30, v24, v25
	v_cvt_pk_bf16_f32 v31, v26, v27
	global_store_dwordx4 v[162:163], v[28:31], off offset:3072
	v_pk_add_f32 v[20:21], v[20:21], v[158:159]
	v_pk_add_f32 v[22:23], v[22:23], v[160:161]
	v_pk_add_f32 v[16:17], v[16:17], v[164:165]
	v_pk_add_f32 v[18:19], v[18:19], v[166:167]
	v_mul_f32_e32 v20, 0xbfb8aa3b, v20
	v_mul_f32_e32 v21, 0xbfb8aa3b, v21
	v_mul_f32_e32 v22, 0xbfb8aa3b, v22
	v_mul_f32_e32 v23, 0xbfb8aa3b, v23
	v_mul_f32_e32 v16, 0xbfb8aa3b, v16
	v_mul_f32_e32 v17, 0xbfb8aa3b, v17
	v_mul_f32_e32 v18, 0xbfb8aa3b, v18
	v_mul_f32_e32 v19, 0xbfb8aa3b, v19
	v_exp_f32_e32 v20, v20
	v_exp_f32_e32 v21, v21
	v_exp_f32_e32 v22, v22
	v_exp_f32_e32 v23, v23
	v_exp_f32_e32 v16, v16
	v_exp_f32_e32 v17, v17
	v_exp_f32_e32 v18, v18
	v_exp_f32_e32 v19, v19
	v_add_f32_e32 v20, 1.0, v20
	v_add_f32_e32 v21, 1.0, v21
	v_add_f32_e32 v22, 1.0, v22
	v_add_f32_e32 v23, 1.0, v23
	v_add_f32_e32 v16, 1.0, v16
	v_add_f32_e32 v17, 1.0, v17
	v_add_f32_e32 v18, 1.0, v18
	v_add_f32_e32 v19, 1.0, v19
	v_rcp_f32_e32 v20, v20
	v_rcp_f32_e32 v21, v21
	v_rcp_f32_e32 v22, v22
	v_rcp_f32_e32 v23, v23
	v_rcp_f32_e32 v16, v16
	v_rcp_f32_e32 v17, v17
	v_rcp_f32_e32 v18, v18
	v_rcp_f32_e32 v19, v19
	v_lshlrev_b32_e32 v236, 16, v224
	v_and_b32_e32 v237, 0xffff0000, v224
	v_lshlrev_b32_e32 v238, 16, v225
	v_and_b32_e32 v239, 0xffff0000, v225
	v_lshlrev_b32_e32 v240, 16, v226
	v_and_b32_e32 v241, 0xffff0000, v226
	v_lshlrev_b32_e32 v242, 16, v227
	v_and_b32_e32 v243, 0xffff0000, v227
	v_mul_f32_e32 v20, v20, v236
	v_mul_f32_e32 v21, v21, v237
	v_mul_f32_e32 v22, v22, v238
	v_mul_f32_e32 v23, v23, v239
	v_mul_f32_e32 v16, v16, v240
	v_mul_f32_e32 v17, v17, v241
	v_mul_f32_e32 v18, v18, v242
	v_mul_f32_e32 v19, v19, v243
	v_cvt_pk_bf16_f32 v20, v20, v21
	v_cvt_pk_bf16_f32 v21, v22, v23
	v_cvt_pk_bf16_f32 v22, v16, v17
	v_cvt_pk_bf16_f32 v23, v18, v19
	global_store_dwordx4 v[162:163], v[20:23], off offset:3328
	s_mov_b32 s98, 0x10000
	v_lshl_add_u64 v[162:163], v[162:163], 0, s[98:99]
; __device__ __forceinline__ unsigned cvt_pk_bf16(float lo, float hi) { unsigned r; asm("v_cvt_pk_bf16_f32 %0, %1, %2" : "=v"(r) : "v"(lo), "v"(hi)); return r; }
; __device__ __forceinline__ float bflo(unsigned w) { return __uint_as_float(w << 16); }
; __device__ __forceinline__ float bfhi(unsigned w) { return __uint_as_float(w & 0xffff0000u); }
; __device__ __forceinline__ float sigmoidf_(float x) { return 1.f / (1.f + __expf(-x)); }
;     __device__ __forceinline__ void operator()(const f32x4 (&acc)[2][2][4][2], const pg8::Unit& u, int wr_, int wc_, int fr_, int fq_) const {
;     ...
;                 for (int bj = 0; bj < 2; ++bj) { const int col = col0 + bj * 128;
;                     const f32x4 b0 = *(const f32x4*)(bias + col), b1 = *(const f32x4*)(bias + col + 4);
;                     const f32x4 v0 = acc[ai][bj][m][0] + b0, v1 = acc[ai][bj][m][1] + b1;
;                     const u32x4 z = *(const u32x4*)(Z + (size_t)row * 512 + col);
;                     u32x4 w;
;                     w.x = cvt_pk_bf16(bflo(z.x) * sigmoidf_(v0[0]), bfhi(z.x) * sigmoidf_(v0[1]));
;                     w.y = cvt_pk_bf16(bflo(z.y) * sigmoidf_(v0[2]), bfhi(z.y) * sigmoidf_(v0[3]));
;                     w.z = cvt_pk_bf16(bflo(z.z) * sigmoidf_(v1[0]), bfhi(z.z) * sigmoidf_(v1[1]));
;                     w.w = cvt_pk_bf16(bflo(z.w) * sigmoidf_(v1[2]), bfhi(z.w) * sigmoidf_(v1[3]));
;                     *(u32x4*)(MIX + (size_t)row * 2048 + 1536 + col) = w; } }
	v_pk_add_f32 v[12:13], v[12:13], v[150:151]
	v_pk_add_f32 v[14:15], v[14:15], v[152:153]
	v_pk_add_f32 v[8:9], v[8:9], v[154:155]
	v_pk_add_f32 v[10:11], v[10:11], v[156:157]
	v_mul_f32_e32 v12, 0xbfb8aa3b, v12
	v_mul_f32_e32 v13, 0xbfb8aa3b, v13
	v_mul_f32_e32 v14, 0xbfb8aa3b, v14
	v_mul_f32_e32 v15, 0xbfb8aa3b, v15
	v_mul_f32_e32 v8, 0xbfb8aa3b, v8
	v_mul_f32_e32 v9, 0xbfb8aa3b, v9
	v_mul_f32_e32 v10, 0xbfb8aa3b, v10
	v_mul_f32_e32 v11, 0xbfb8aa3b, v11
	v_exp_f32_e32 v12, v12
	v_exp_f32_e32 v13, v13
	v_exp_f32_e32 v14, v14
	v_exp_f32_e32 v15, v15
	v_exp_f32_e32 v8, v8
	v_exp_f32_e32 v9, v9
	v_exp_f32_e32 v10, v10
	v_exp_f32_e32 v11, v11
	v_add_f32_e32 v12, 1.0, v12
	v_add_f32_e32 v13, 1.0, v13
	v_add_f32_e32 v14, 1.0, v14
	v_add_f32_e32 v15, 1.0, v15
	v_add_f32_e32 v8, 1.0, v8
	v_add_f32_e32 v9, 1.0, v9
	v_add_f32_e32 v10, 1.0, v10
	v_add_f32_e32 v11, 1.0, v11
	v_rcp_f32_e32 v12, v12
	v_rcp_f32_e32 v13, v13
	v_rcp_f32_e32 v14, v14
	v_rcp_f32_e32 v15, v15
	v_rcp_f32_e32 v8, v8
	v_rcp_f32_e32 v9, v9
	v_rcp_f32_e32 v10, v10
	v_rcp_f32_e32 v11, v11
	v_lshlrev_b32_e32 v236, 16, v228
	v_and_b32_e32 v237, 0xffff0000, v228
	v_lshlrev_b32_e32 v238, 16, v229
	v_and_b32_e32 v239, 0xffff0000, v229
	v_lshlrev_b32_e32 v240, 16, v230
	v_and_b32_e32 v241, 0xffff0000, v230
	v_lshlrev_b32_e32 v242, 16, v231
	v_and_b32_e32 v243, 0xffff0000, v231
	v_mul_f32_e32 v12, v12, v236
	v_mul_f32_e32 v13, v13, v237
	v_mul_f32_e32 v14, v14, v238
	v_mul_f32_e32 v15, v15, v239
	v_mul_f32_e32 v8, v8, v240
	v_mul_f32_e32 v9, v9, v241
	v_mul_f32_e32 v10, v10, v242
	v_mul_f32_e32 v11, v11, v243
	v_cvt_pk_bf16_f32 v12, v12, v13
	v_cvt_pk_bf16_f32 v13, v14, v15
	v_cvt_pk_bf16_f32 v14, v8, v9
	v_cvt_pk_bf16_f32 v15, v10, v11
	global_store_dwordx4 v[162:163], v[12:15], off offset:3072
	v_pk_add_f32 v[4:5], v[4:5], v[158:159]
	v_pk_add_f32 v[6:7], v[6:7], v[160:161]
	v_pk_add_f32 v[0:1], v[0:1], v[164:165]
	v_pk_add_f32 v[2:3], v[2:3], v[166:167]
	v_mul_f32_e32 v4, 0xbfb8aa3b, v4
	v_mul_f32_e32 v5, 0xbfb8aa3b, v5
	v_mul_f32_e32 v6, 0xbfb8aa3b, v6
	v_mul_f32_e32 v7, 0xbfb8aa3b, v7
	v_mul_f32_e32 v0, 0xbfb8aa3b, v0
	v_mul_f32_e32 v1, 0xbfb8aa3b, v1
	v_mul_f32_e32 v2, 0xbfb8aa3b, v2
	v_mul_f32_e32 v3, 0xbfb8aa3b, v3
	v_exp_f32_e32 v4, v4
	v_exp_f32_e32 v5, v5
	v_exp_f32_e32 v6, v6
	v_exp_f32_e32 v7, v7
	v_exp_f32_e32 v0, v0
	v_exp_f32_e32 v1, v1
	v_exp_f32_e32 v2, v2
	v_exp_f32_e32 v3, v3
	v_add_f32_e32 v4, 1.0, v4
	v_add_f32_e32 v5, 1.0, v5
	v_add_f32_e32 v6, 1.0, v6
	v_add_f32_e32 v7, 1.0, v7
	v_add_f32_e32 v0, 1.0, v0
	v_add_f32_e32 v1, 1.0, v1
	v_add_f32_e32 v2, 1.0, v2
	v_add_f32_e32 v3, 1.0, v3
	v_rcp_f32_e32 v4, v4
	v_rcp_f32_e32 v5, v5
	v_rcp_f32_e32 v6, v6
	v_rcp_f32_e32 v7, v7
	v_rcp_f32_e32 v0, v0
	v_rcp_f32_e32 v1, v1
	v_rcp_f32_e32 v2, v2
	v_rcp_f32_e32 v3, v3
	v_lshlrev_b32_e32 v236, 16, v232
	v_and_b32_e32 v237, 0xffff0000, v232
	v_lshlrev_b32_e32 v238, 16, v233
	v_and_b32_e32 v239, 0xffff0000, v233
	v_lshlrev_b32_e32 v240, 16, v234
	v_and_b32_e32 v241, 0xffff0000, v234
	v_lshlrev_b32_e32 v242, 16, v235
	v_and_b32_e32 v243, 0xffff0000, v235
	v_mul_f32_e32 v4, v4, v236
	v_mul_f32_e32 v5, v5, v237
	v_mul_f32_e32 v6, v6, v238
	v_mul_f32_e32 v7, v7, v239
	v_mul_f32_e32 v0, v0, v240
	v_mul_f32_e32 v1, v1, v241
	v_mul_f32_e32 v2, v2, v242
	v_mul_f32_e32 v3, v3, v243
	v_cvt_pk_bf16_f32 v4, v4, v5
	v_cvt_pk_bf16_f32 v5, v6, v7
	v_cvt_pk_bf16_f32 v6, v0, v1
	v_cvt_pk_bf16_f32 v7, v2, v3
	global_store_dwordx4 v[162:163], v[4:7], off offset:3328
	s_cbranch_vccz .LBB0_443
	s_waitcnt vmcnt(0)
	s_cmpk_gt_u32 s13, 0xff
	s_cbranch_scc1 .LBB0_450
	s_barrier

; __device__ __forceinline__ void hyfilter_item(PRef p, int layer, bool isctx, int cg4, unsigned char* shm) {
;     ...
;         const c2* Z = KF0b + (size_t)cc * N;
; #pragma unroll 8
;         for (int i = ht; i < N; i += 256) buf[PHYS(i)] = Z[i];
.LBB0_731:
	v_add_co_u32_e32 v188, vcc, 0xffffd000, v8
	v_add_u32_e32 v190, v101, v12
	s_nop 0
	v_addc_co_u32_e32 v189, vcc, -1, v9, vcc
	global_load_dwordx2 v[192:193], v[188:189], off offset:-2048
	s_mov_b64 s[2:3], 0x4000
	global_load_dwordx2 v[194:195], v[188:189], off
	v_add_u32_e32 v109, 0x800, v109
	v_add_u32_e32 v101, 0x4400, v101
	v_add_u32_e32 v191, v102, v12
	v_add_co_u32_e32 v196, vcc, 0xffffe000, v8
	v_add_u32_e32 v198, v103, v12
	s_nop 0
	v_addc_co_u32_e32 v197, vcc, -1, v9, vcc
	global_load_dwordx2 v[200:201], v[196:197], off offset:-2048
	v_add_u32_e32 v103, 0x4400, v103
	global_load_dwordx2 v[202:203], v[196:197], off
	v_add_u32_e32 v102, 0x4400, v102
	v_add_u32_e32 v199, v104, v12
	v_add_co_u32_e32 v204, vcc, 0xfffff000, v8
	v_add_u32_e32 v206, v105, v12
	s_nop 0
	v_addc_co_u32_e32 v205, vcc, -1, v9, vcc
	global_load_dwordx2 v[208:209], v[204:205], off offset:-2048
	v_add_u32_e32 v105, 0x4400, v105
	v_add_u32_e32 v104, 0x4400, v104
	global_load_dwordx2 v[210:211], v[8:9], off offset:-4096
	v_add_u32_e32 v207, v106, v12
	v_add_u32_e32 v106, 0x4400, v106
	global_load_dwordx2 v[212:213], v[8:9], off offset:-2048
	v_add_u32_e32 v214, v107, v12
	v_add_u32_e32 v107, 0x4400, v107
	global_load_dwordx2 v[216:217], v[8:9], off
	v_lshl_add_u64 v[8:9], v[8:9], 0, s[2:3]
	s_movk_i32 s2, 0x17ff
	v_add_u32_e32 v215, v108, v12
	v_add_u32_e32 v108, 0x4400, v108
	s_waitcnt vmcnt(7)
	ds_write_b64 v190, v[192:193]
	s_waitcnt vmcnt(6)
	ds_write_b64 v191, v[194:195]
	s_waitcnt vmcnt(5)
	ds_write_b64 v198, v[200:201]
	s_waitcnt vmcnt(4)
	ds_write_b64 v199, v[202:203]
	s_waitcnt vmcnt(3)
	ds_write_b64 v206, v[208:209]
	s_waitcnt vmcnt(2)
	ds_write_b64 v207, v[210:211]
	s_waitcnt vmcnt(1)
	ds_write_b64 v214, v[212:213]
	s_waitcnt vmcnt(0)
	ds_write_b64 v215, v[216:217]
	v_cmp_lt_u32_e32 vcc, s2, v109
	s_or_b64 s[6:7], vcc, s[6:7]
	s_andn2_b64 exec, exec, s[6:7]
	s_cbranch_execnz .LBB0_731
	s_or_b64 exec, exec, s[6:7]
	s_mov_b32 s2, 0xe800
	s_mov_b32 s3, 0xc800
	s_mov_b32 s11, 0xa800
	s_mov_b32 s33, 0x8800
	s_movk_i32 s37, 0x6800
	s_movk_i32 s40, 0x4800
	s_movk_i32 s41, 0x2800
	s_mov_b32 s44, 0xe000
	s_mov_b32 s45, 0xc000
	s_mov_b32 s46, 0xa000
	s_mov_b32 s47, 0x8000
	s_movk_i32 s50, 0x6000
	s_movk_i32 s51, 0x4000
	s_movk_i32 s52, 0x2000
	s_mov_b64 s[6:7], 0
	v_mov_b32_e32 v8, v56
	v_mov_b32_e32 v9, v55
	v_mov_b32_e32 v101, v47
	v_mov_b32_e32 v102, v46
	v_mov_b32_e32 v103, v45
	v_mov_b32_e32 v104, v44
	v_mov_b32_e32 v105, v43
	v_mov_b32_e32 v106, v42
	v_mov_b32_e32 v107, v41
	v_mov_b32_e32 v108, v33
	s_waitcnt lgkmcnt(0)
	s_barrier

; #define PG8_STAGE(bufoff, gbase, voff) do { _Pragma("unroll") for (int _i = 0; _i < 2; ++_i) \
;         __builtin_amdgcn_global_load_lds((const unsigned*)((const char*)(gbase) + (size_t)_i * r64##voff + (voff)), (LAS unsigned*)(lds + (bufoff) + ldsw + _i * 8192), 16, 0, 0); } while (0)
; #define PG8_LDA(dst, b, h) do { _Pragma("unroll") for (int m = 0; m < 4; ++m) _Pragma("unroll") for (int k = 0; k < 2; ++k) dst[m][k] = *(const LAS bf16x8*)(lds + PG8_SA(b, h) + aoff + m * 2048 + k * 1024); } while (0)
; #define PG8_LDB(dst, b, h) do { _Pragma("unroll") for (int n = 0; n < 2; ++n) _Pragma("unroll") for (int k = 0; k < 2; ++k) dst[n][k] = *(const LAS bf16x8*)(lds + PG8_SB(b, h) + boff + n * 2048 + k * 1024); } while (0)
; #define PG8_MMA(ai, bj, At, Bt) do { __builtin_amdgcn_s_setprio(1); _Pragma("unroll") for (int m = 0; m < 4; ++m) _Pragma("unroll") for (int n = 0; n < 2; ++n) _Pragma("unroll") for (int k = 0; k < 2; ++k) \
;         acc[ai][bj][m][n] = __builtin_amdgcn_mfma_f32_16x16x32_bf16(Bt[n][k], At[m][k], acc[ai][bj][m][n], 0, 0, 0); __builtin_amdgcn_s_setprio(0); } while (0)
; #define PG8_WAIT_V(n) asm volatile("s_waitcnt vmcnt(" #n ")" ::: "memory")
; #define PG8_WAIT_L(n) asm volatile("s_waitcnt lgkmcnt(" #n ")" ::: "memory")
; #define PG8_BAR __builtin_amdgcn_s_barrier()
; #define PG8_SCHED __builtin_amdgcn_sched_barrier(0)
; template <class Epi, class Sched>
; __device__ __forceinline__ void gemm_phase(LAS unsigned char* lds, const Gemm g, const Sched& S, const Epi& E) {
;     ...
;             PG8_LDB(B0, 0, 0); PG8_SCHED; PG8_LDA(At, 0, 0); PG8_STAGE(PG8_SA(1, 1), a1 + hstepA, voffA);
;             PG8_WAIT_L(8); PG8_BAR; PG8_WAIT_L(0); PG8_MMA(0, 0, At, B0); PG8_BAR; PG8_SCHED;
;             PG8_LDB(B1, 0, 1); PG8_STAGE(PG8_SB(0, 0), b2, voffB);
;             PG8_BAR; PG8_WAIT_L(0); PG8_MMA(0, 1, At, B1); PG8_BAR;
;             PG8_LDA(At, 0, 1); PG8_STAGE(PG8_SA(0, 0), a2, voffA);
;             PG8_BAR; PG8_WAIT_L(0); PG8_MMA(1, 0, At, B0); PG8_BAR; PG8_SCHED;
;             PG8_STAGE(PG8_SB(0, 1), b2 + hstepB, voffB);
;             PG8_WAIT_V(6); PG8_BAR; PG8_MMA(1, 1, At, B1); PG8_BAR;
.LBB0_954:
	ds_read_b128 v[138:141], v147
	ds_read_b128 v[142:145], v147 offset:1024
	ds_read_b128 v[150:153], v147 offset:2048
	ds_read_b128 v[154:157], v147 offset:3072
	s_add_u32 s10, s8, 0x100
	s_addc_u32 s11, s9, 0
	s_cmp_eq_u32 s59, 4
	s_cselect_b32 s61, s12, s11
	s_cselect_b32 s60, s43, s10
	s_cselect_b32 s63, s41, s58
	s_cselect_b32 s62, s56, s57
	v_lshl_add_u64 v[190:191], s[8:9], 0, v[132:133]
	v_lshl_add_u64 v[192:193], v[190:191], 0, s[36:37]
	s_add_i32 m0, s33, 0xc000
	ds_read_b128 v[158:161], v148
	ds_read_b128 v[162:165], v148 offset:1024
	ds_read_b128 v[166:169], v148 offset:2048
	ds_read_b128 v[170:173], v148 offset:3072
	ds_read_b128 v[174:177], v148 offset:4096
	ds_read_b128 v[178:181], v148 offset:5120
	ds_read_b128 v[182:185], v148 offset:6144
	ds_read_b128 v[186:189], v148 offset:7168
	global_load_lds_dwordx4 v[192:193], off
	v_lshl_add_u64 v[190:191], v[190:191], 0, s[38:39]
	s_add_i32 m0, s33, 0xe000
	s_nop 0
	global_load_lds_dwordx4 v[190:191], off
	s_waitcnt lgkmcnt(8)
	s_barrier
	s_waitcnt lgkmcnt(0)
	s_setprio 1
	s_waitcnt lgkmcnt(0)
	v_mfma_f32_16x16x32_bf16 v[124:127], v[138:141], v[158:161], v[124:127]
	v_mfma_f32_16x16x32_bf16 v[120:123], v[150:153], v[158:161], v[120:123]
	v_mfma_f32_16x16x32_bf16 v[108:111], v[138:141], v[166:169], v[108:111]
	v_mfma_f32_16x16x32_bf16 v[104:107], v[150:153], v[166:169], v[104:107]
	v_mfma_f32_16x16x32_bf16 v[92:95], v[138:141], v[174:177], v[92:95]
	v_mfma_f32_16x16x32_bf16 v[88:91], v[150:153], v[174:177], v[88:91]
	v_mfma_f32_16x16x32_bf16 v[76:79], v[138:141], v[182:185], v[76:79]
	v_mfma_f32_16x16x32_bf16 v[72:75], v[150:153], v[182:185], v[72:75]
	v_mfma_f32_16x16x32_bf16 v[124:127], v[142:145], v[162:165], v[124:127]
	v_mfma_f32_16x16x32_bf16 v[120:123], v[154:157], v[162:165], v[120:123]
	v_mfma_f32_16x16x32_bf16 v[108:111], v[142:145], v[170:173], v[108:111]
	v_mfma_f32_16x16x32_bf16 v[104:107], v[154:157], v[170:173], v[104:107]
	v_mfma_f32_16x16x32_bf16 v[92:95], v[142:145], v[178:181], v[92:95]
	v_mfma_f32_16x16x32_bf16 v[88:91], v[154:157], v[178:181], v[88:91]
	v_mfma_f32_16x16x32_bf16 v[76:79], v[142:145], v[186:189], v[76:79]
	v_mfma_f32_16x16x32_bf16 v[72:75], v[154:157], v[186:189], v[72:75]
	s_setprio 0
	s_barrier
	s_add_i32 s8, s54, s29
	v_lshl_add_u64 v[206:207], s[62:63], 0, v[128:129]
	s_mov_b32 m0, s8
	ds_read_b128 v[190:193], v149
	ds_read_b128 v[194:197], v149 offset:1024
	ds_read_b128 v[198:201], v149 offset:2048
	ds_read_b128 v[202:205], v149 offset:3072
	global_load_lds_dwordx4 v[206:207], off
	v_lshl_add_u64 v[208:209], v[206:207], 0, s[16:17]
	s_add_i32 m0, s8, 0x2000
	s_nop 0
	global_load_lds_dwordx4 v[208:209], off
	s_barrier
	s_waitcnt lgkmcnt(0)
	s_setprio 1
	s_waitcnt lgkmcnt(0)
	v_mfma_f32_16x16x32_bf16 v[116:119], v[190:193], v[158:161], v[116:119]
	v_mfma_f32_16x16x32_bf16 v[112:115], v[198:201], v[158:161], v[112:115]
	v_mfma_f32_16x16x32_bf16 v[100:103], v[190:193], v[166:169], v[100:103]
	v_mfma_f32_16x16x32_bf16 v[96:99], v[198:201], v[166:169], v[96:99]
	v_mfma_f32_16x16x32_bf16 v[84:87], v[190:193], v[174:177], v[84:87]
	v_mfma_f32_16x16x32_bf16 v[80:83], v[198:201], v[174:177], v[80:83]
	v_mfma_f32_16x16x32_bf16 v[68:71], v[190:193], v[182:185], v[68:71]
	v_mfma_f32_16x16x32_bf16 v[64:67], v[198:201], v[182:185], v[64:67]
	v_mfma_f32_16x16x32_bf16 v[116:119], v[194:197], v[162:165], v[116:119]
	v_mfma_f32_16x16x32_bf16 v[112:115], v[202:205], v[162:165], v[112:115]
	v_mfma_f32_16x16x32_bf16 v[100:103], v[194:197], v[170:173], v[100:103]
	v_mfma_f32_16x16x32_bf16 v[96:99], v[202:205], v[170:173], v[96:99]
	v_mfma_f32_16x16x32_bf16 v[84:87], v[194:197], v[178:181], v[84:87]
	v_mfma_f32_16x16x32_bf16 v[80:83], v[202:205], v[178:181], v[80:83]
	v_mfma_f32_16x16x32_bf16 v[68:71], v[194:197], v[186:189], v[68:71]
	v_mfma_f32_16x16x32_bf16 v[64:67], v[202:205], v[186:189], v[64:67]
	s_setprio 0
	s_mov_b32 m0, s33
	v_lshl_add_u64 v[208:209], s[60:61], 0, v[130:131]
	s_barrier
	ds_read_b128 v[158:161], v148 offset:16384
	ds_read_b128 v[162:165], v148 offset:17408
	ds_read_b128 v[166:169], v148 offset:18432
	ds_read_b128 v[170:173], v148 offset:19456
	ds_read_b128 v[174:177], v148 offset:20480
	ds_read_b128 v[178:181], v148 offset:21504
	ds_read_b128 v[182:185], v148 offset:22528
	ds_read_b128 v[186:189], v148 offset:23552
	global_load_lds_dwordx4 v[208:209], off
	v_lshl_add_u64 v[210:211], v[208:209], 0, s[16:17]
	s_mov_b32 m0, s48
	s_nop 0
	global_load_lds_dwordx4 v[210:211], off
	s_barrier
	s_waitcnt lgkmcnt(0)
	s_setprio 1
	s_waitcnt lgkmcnt(0)
	v_mfma_f32_16x16x32_bf16 v[60:63], v[138:141], v[158:161], v[60:63]
	v_mfma_f32_16x16x32_bf16 v[56:59], v[150:153], v[158:161], v[56:59]
	v_mfma_f32_16x16x32_bf16 v[44:47], v[138:141], v[166:169], v[44:47]
	v_mfma_f32_16x16x32_bf16 v[40:43], v[150:153], v[166:169], v[40:43]
	v_mfma_f32_16x16x32_bf16 v[28:31], v[138:141], v[174:177], v[28:31]
	v_mfma_f32_16x16x32_bf16 v[24:27], v[150:153], v[174:177], v[24:27]
	v_mfma_f32_16x16x32_bf16 v[12:15], v[138:141], v[182:185], v[12:15]
	v_mfma_f32_16x16x32_bf16 v[8:11], v[150:153], v[182:185], v[8:11]
	v_mfma_f32_16x16x32_bf16 v[60:63], v[142:145], v[162:165], v[60:63]
	v_mfma_f32_16x16x32_bf16 v[56:59], v[154:157], v[162:165], v[56:59]
	v_mfma_f32_16x16x32_bf16 v[44:47], v[142:145], v[170:173], v[44:47]
	v_mfma_f32_16x16x32_bf16 v[40:43], v[154:157], v[170:173], v[40:43]
	v_mfma_f32_16x16x32_bf16 v[28:31], v[142:145], v[178:181], v[28:31]
	v_mfma_f32_16x16x32_bf16 v[24:27], v[154:157], v[178:181], v[24:27]
	v_mfma_f32_16x16x32_bf16 v[12:15], v[142:145], v[186:189], v[12:15]
	v_mfma_f32_16x16x32_bf16 v[8:11], v[154:157], v[186:189], v[8:11]
	s_setprio 0
	s_barrier
; #define PG8_STAGE(bufoff, gbase, voff) do { _Pragma("unroll") for (int _i = 0; _i < 2; ++_i) \
;         __builtin_amdgcn_global_load_lds((const unsigned*)((const char*)(gbase) + (size_t)_i * r64##voff + (voff)), (LAS unsigned*)(lds + (bufoff) + ldsw + _i * 8192), 16, 0, 0); } while (0)
; #define PG8_LDA(dst, b, h) do { _Pragma("unroll") for (int m = 0; m < 4; ++m) _Pragma("unroll") for (int k = 0; k < 2; ++k) dst[m][k] = *(const LAS bf16x8*)(lds + PG8_SA(b, h) + aoff + m * 2048 + k * 1024); } while (0)
; #define PG8_LDB(dst, b, h) do { _Pragma("unroll") for (int n = 0; n < 2; ++n) _Pragma("unroll") for (int k = 0; k < 2; ++k) dst[n][k] = *(const LAS bf16x8*)(lds + PG8_SB(b, h) + boff + n * 2048 + k * 1024); } while (0)
; #define PG8_MMA(ai, bj, At, Bt) do { __builtin_amdgcn_s_setprio(1); _Pragma("unroll") for (int m = 0; m < 4; ++m) _Pragma("unroll") for (int n = 0; n < 2; ++n) _Pragma("unroll") for (int k = 0; k < 2; ++k) \
;         acc[ai][bj][m][n] = __builtin_amdgcn_mfma_f32_16x16x32_bf16(Bt[n][k], At[m][k], acc[ai][bj][m][n], 0, 0, 0); __builtin_amdgcn_s_setprio(0); } while (0)
; #define PG8_WAIT_V(n) asm volatile("s_waitcnt vmcnt(" #n ")" ::: "memory")
; #define PG8_WAIT_L(n) asm volatile("s_waitcnt lgkmcnt(" #n ")" ::: "memory")
; #define PG8_BAR __builtin_amdgcn_s_barrier()
; #define PG8_SCHED __builtin_amdgcn_sched_barrier(0)
; template <class Epi, class Sched>
; __device__ __forceinline__ void gemm_phase(LAS unsigned char* lds, const Gemm g, const Sched& S, const Epi& E) {
;     ...
;             PG8_LDB(B0, 1, 0); PG8_SCHED; PG8_LDA(At, 1, 0); PG8_STAGE(PG8_SA(0, 1), a2 + hstepA, voffA);
;             PG8_WAIT_L(8); PG8_BAR; PG8_WAIT_L(0); PG8_MMA(0, 0, At, B0); PG8_BAR; PG8_SCHED;
;             PG8_LDB(B1, 1, 1); PG8_STAGE(PG8_SB(1, 0), b3, voffB);
;             PG8_BAR; PG8_WAIT_L(0); PG8_MMA(0, 1, At, B1); PG8_BAR;
;             PG8_LDA(At, 1, 1); PG8_STAGE(PG8_SA(1, 0), a3, voffA);
;             PG8_BAR; PG8_WAIT_L(0); PG8_MMA(1, 0, At, B0); PG8_BAR; PG8_SCHED;
;             PG8_STAGE(PG8_SB(1, 1), b3 + hstepB, voffB);
;             PG8_WAIT_V(6); PG8_BAR; PG8_MMA(1, 1, At, B1); PG8_BAR;
	s_add_i32 s8, s55, s29
	v_lshl_add_u64 v[138:139], v[206:207], 0, s[18:19]
	s_mov_b32 m0, s8
	s_nop 0
	global_load_lds_dwordx4 v[138:139], off
	v_lshl_add_u64 v[138:139], v[206:207], 0, s[20:21]
	s_add_i32 m0, s8, 0x2000
	s_nop 0
	global_load_lds_dwordx4 v[138:139], off
	s_waitcnt vmcnt(6)
	s_barrier
	s_setprio 1
	v_mfma_f32_16x16x32_bf16 v[52:55], v[190:193], v[158:161], v[52:55]
	v_mfma_f32_16x16x32_bf16 v[48:51], v[198:201], v[158:161], v[48:51]
	v_mfma_f32_16x16x32_bf16 v[36:39], v[190:193], v[166:169], v[36:39]
	v_mfma_f32_16x16x32_bf16 v[32:35], v[198:201], v[166:169], v[32:35]
	v_mfma_f32_16x16x32_bf16 v[20:23], v[190:193], v[174:177], v[20:23]
	v_mfma_f32_16x16x32_bf16 v[16:19], v[198:201], v[174:177], v[16:19]
	v_mfma_f32_16x16x32_bf16 v[4:7], v[190:193], v[182:185], v[4:7]
	v_mfma_f32_16x16x32_bf16 v[0:3], v[198:201], v[182:185], v[0:3]
	v_mfma_f32_16x16x32_bf16 v[52:55], v[194:197], v[162:165], v[52:55]
	v_mfma_f32_16x16x32_bf16 v[48:51], v[202:205], v[162:165], v[48:51]
	v_mfma_f32_16x16x32_bf16 v[36:39], v[194:197], v[170:173], v[36:39]
	v_mfma_f32_16x16x32_bf16 v[32:35], v[202:205], v[170:173], v[32:35]
	v_mfma_f32_16x16x32_bf16 v[20:23], v[194:197], v[178:181], v[20:23]
	v_mfma_f32_16x16x32_bf16 v[16:19], v[202:205], v[178:181], v[16:19]
	v_mfma_f32_16x16x32_bf16 v[4:7], v[194:197], v[186:189], v[4:7]
	v_mfma_f32_16x16x32_bf16 v[0:3], v[202:205], v[186:189], v[0:3]
	s_setprio 0
	s_add_i32 s8, 0, 0x18000
	v_add_u32_e32 v154, s8, v146
	s_barrier
	ds_read_b128 v[138:141], v154
	ds_read_b128 v[142:145], v154 offset:1024
	ds_read_b128 v[150:153], v154 offset:2048
	ds_read_b128 v[154:157], v154 offset:3072
	s_mov_b32 m0, s49
	v_lshl_add_u64 v[190:191], v[208:209], 0, s[18:19]
	ds_read_b128 v[158:161], v148 offset:32768
	ds_read_b128 v[162:165], v148 offset:33792
	ds_read_b128 v[166:169], v148 offset:34816
	ds_read_b128 v[170:173], v148 offset:35840
	ds_read_b128 v[174:177], v148 offset:36864
	ds_read_b128 v[178:181], v148 offset:37888
	ds_read_b128 v[182:185], v148 offset:38912
	ds_read_b128 v[186:189], v148 offset:39936
	global_load_lds_dwordx4 v[190:191], off
	v_lshl_add_u64 v[190:191], v[208:209], 0, s[20:21]
	s_mov_b32 m0, s50
	s_nop 0
	global_load_lds_dwordx4 v[190:191], off
	s_waitcnt lgkmcnt(8)
	s_barrier
	s_waitcnt lgkmcnt(0)
	s_setprio 1
	s_waitcnt lgkmcnt(0)
	v_mfma_f32_16x16x32_bf16 v[124:127], v[138:141], v[158:161], v[124:127]
	v_mfma_f32_16x16x32_bf16 v[120:123], v[150:153], v[158:161], v[120:123]
	v_mfma_f32_16x16x32_bf16 v[108:111], v[138:141], v[166:169], v[108:111]
	v_mfma_f32_16x16x32_bf16 v[104:107], v[150:153], v[166:169], v[104:107]
	v_mfma_f32_16x16x32_bf16 v[92:95], v[138:141], v[174:177], v[92:95]
	v_mfma_f32_16x16x32_bf16 v[88:91], v[150:153], v[174:177], v[88:91]
	v_mfma_f32_16x16x32_bf16 v[76:79], v[138:141], v[182:185], v[76:79]
	v_mfma_f32_16x16x32_bf16 v[72:75], v[150:153], v[182:185], v[72:75]
	v_mfma_f32_16x16x32_bf16 v[124:127], v[142:145], v[162:165], v[124:127]
	v_mfma_f32_16x16x32_bf16 v[120:123], v[154:157], v[162:165], v[120:123]
	v_mfma_f32_16x16x32_bf16 v[108:111], v[142:145], v[170:173], v[108:111]
	v_mfma_f32_16x16x32_bf16 v[104:107], v[154:157], v[170:173], v[104:107]
	v_mfma_f32_16x16x32_bf16 v[92:95], v[142:145], v[178:181], v[92:95]
	v_mfma_f32_16x16x32_bf16 v[88:91], v[154:157], v[178:181], v[88:91]
	v_mfma_f32_16x16x32_bf16 v[76:79], v[142:145], v[186:189], v[76:79]
	v_mfma_f32_16x16x32_bf16 v[72:75], v[154:157], v[186:189], v[72:75]
	s_setprio 0
	s_barrier
	s_add_i32 s9, 0, 0x1c000
	s_add_i32 s8, s8, s29
	v_add_u32_e32 v202, s9, v146
	v_lshl_add_u64 v[210:211], v[206:207], 0, s[30:31]
	s_mov_b32 m0, s8
	ds_read_b128 v[190:193], v202
	ds_read_b128 v[194:197], v202 offset:1024
	ds_read_b128 v[198:201], v202 offset:2048
	ds_read_b128 v[202:205], v202 offset:3072
	global_load_lds_dwordx4 v[210:211], off
	v_lshl_add_u64 v[210:211], v[206:207], 0, s[34:35]
	s_add_i32 m0, s8, 0x2000
	s_nop 0
	global_load_lds_dwordx4 v[210:211], off
	s_barrier
	s_waitcnt lgkmcnt(0)
	s_setprio 1
	s_waitcnt lgkmcnt(0)
	v_mfma_f32_16x16x32_bf16 v[116:119], v[190:193], v[158:161], v[116:119]
	v_mfma_f32_16x16x32_bf16 v[112:115], v[198:201], v[158:161], v[112:115]
	v_mfma_f32_16x16x32_bf16 v[100:103], v[190:193], v[166:169], v[100:103]
	v_mfma_f32_16x16x32_bf16 v[96:99], v[198:201], v[166:169], v[96:99]
	v_mfma_f32_16x16x32_bf16 v[84:87], v[190:193], v[174:177], v[84:87]
	v_mfma_f32_16x16x32_bf16 v[80:83], v[198:201], v[174:177], v[80:83]
	v_mfma_f32_16x16x32_bf16 v[68:71], v[190:193], v[182:185], v[68:71]
	v_mfma_f32_16x16x32_bf16 v[64:67], v[198:201], v[182:185], v[64:67]
	v_mfma_f32_16x16x32_bf16 v[116:119], v[194:197], v[162:165], v[116:119]
	v_mfma_f32_16x16x32_bf16 v[112:115], v[202:205], v[162:165], v[112:115]
	v_mfma_f32_16x16x32_bf16 v[100:103], v[194:197], v[170:173], v[100:103]
	v_mfma_f32_16x16x32_bf16 v[96:99], v[202:205], v[170:173], v[96:99]
	v_mfma_f32_16x16x32_bf16 v[84:87], v[194:197], v[178:181], v[84:87]
	v_mfma_f32_16x16x32_bf16 v[80:83], v[202:205], v[178:181], v[80:83]
	v_mfma_f32_16x16x32_bf16 v[68:71], v[194:197], v[186:189], v[68:71]
	v_mfma_f32_16x16x32_bf16 v[64:67], v[202:205], v[186:189], v[64:67]
	s_setprio 0
	s_mov_b32 m0, s52
	v_lshl_add_u64 v[210:211], v[208:209], 0, s[30:31]
	s_barrier
	ds_read_b128 v[158:161], v148 offset:49152
	ds_read_b128 v[162:165], v148 offset:50176
	ds_read_b128 v[166:169], v148 offset:51200
	ds_read_b128 v[170:173], v148 offset:52224
	ds_read_b128 v[174:177], v148 offset:53248
	ds_read_b128 v[178:181], v148 offset:54272
	ds_read_b128 v[182:185], v148 offset:55296
	ds_read_b128 v[186:189], v148 offset:56320
	global_load_lds_dwordx4 v[210:211], off
	v_lshl_add_u64 v[208:209], v[208:209], 0, s[34:35]
	s_mov_b32 m0, s53
	s_nop 0
	global_load_lds_dwordx4 v[208:209], off
	s_barrier
; __device__ __forceinline__ int otid() { int t = (int)__builtin_amdgcn_workitem_id_x(); asm volatile("" : "+v"(t)); return t; }
; #define PG8_STAGE(bufoff, gbase, voff) do { _Pragma("unroll") for (int _i = 0; _i < 2; ++_i) \
;         __builtin_amdgcn_global_load_lds((const unsigned*)((const char*)(gbase) + (size_t)_i * r64##voff + (voff)), (LAS unsigned*)(lds + (bufoff) + ldsw + _i * 8192), 16, 0, 0); } while (0)
; #define PG8_WAIT_V(n) asm volatile("s_waitcnt vmcnt(" #n ")" ::: "memory")
; #define PG8_WAIT_L(n) asm volatile("s_waitcnt lgkmcnt(" #n ")" ::: "memory")
; #define PG8_BAR __builtin_amdgcn_s_barrier()
; template <class Epi, class Sched>
; __device__ __forceinline__ void gemm_phase(LAS unsigned char* lds, const Gemm g, const Sched& S, const Epi& E) {
;     ...
;             PG8_WAIT_V(6); PG8_BAR; PG8_MMA(1, 1, At, B1); PG8_BAR;
;             PG8_LDB(B0, 1, 0); PG8_SCHED; PG8_LDA(At, 1, 0); PG8_STAGE(PG8_SA(0, 1), a2 + hstepA, voffA);
;             PG8_WAIT_L(8); PG8_BAR; PG8_WAIT_L(0); PG8_MMA(0, 0, At, B0); PG8_BAR; PG8_SCHED;
;             PG8_LDB(B1, 1, 1); PG8_STAGE(PG8_SB(1, 0), b3, voffB);
;             PG8_BAR; PG8_WAIT_L(0); PG8_MMA(0, 1, At, B1); PG8_BAR;
;             PG8_LDA(At, 1, 1); PG8_STAGE(PG8_SA(1, 0), a3, voffA);
;             PG8_BAR; PG8_WAIT_L(0); PG8_MMA(1, 0, At, B0); PG8_BAR; PG8_SCHED;
;             PG8_STAGE(PG8_SB(1, 1), b3 + hstepB, voffB);
;             PG8_WAIT_V(6); PG8_BAR; PG8_MMA(1, 1, At, B1); PG8_BAR;
;     __device__ __forceinline__ void operator()(const f32x4 (&acc)[2][2][4][2], const pg8::Unit& u, int wr_, int wc_, int fr_, int fq_) const {
;         const int t2_ = otid(), wr = t2_ >> 8, wc = (t2_ >> 6) & 3, fr = t2_ & 15, fq = (t2_ >> 4) & 3; (void)wr_; (void)wc_; (void)fr_; (void)fq_;
;         const int row0 = u.pm * 256 + wr * 64 + fr, col0 = u.pn * 256 + wc * 32 + 8 * fq;
; #pragma unroll
;         for (int ai = 0; ai < 2; ++ai)
; #pragma unroll
;             for (int m = 0; m < 4; ++m) { const int row = row0 + ai * 128 + m * 16;
; #pragma unroll
;                 for (int bj = 0; bj < 2; ++bj) { const int col = col0 + bj * 128;
;                     const f32x4 b0 = *(const f32x4*)(bias + col), b1 = *(const f32x4*)(bias + col + 4);
;                     const f32x4 v0 = acc[ai][bj][m][0] + b0, v1 = acc[ai][bj][m][1] + b1;
;                     const u32x4 z = *(const u32x4*)(Z + (size_t)row * 512 + col);
	s_waitcnt lgkmcnt(0)
	s_setprio 1
	s_waitcnt lgkmcnt(0)
	v_mfma_f32_16x16x32_bf16 v[60:63], v[138:141], v[158:161], v[60:63]
	v_mfma_f32_16x16x32_bf16 v[56:59], v[150:153], v[158:161], v[56:59]
	v_mfma_f32_16x16x32_bf16 v[44:47], v[138:141], v[166:169], v[44:47]
	v_mfma_f32_16x16x32_bf16 v[40:43], v[150:153], v[166:169], v[40:43]
	v_mfma_f32_16x16x32_bf16 v[28:31], v[138:141], v[174:177], v[28:31]
	v_mfma_f32_16x16x32_bf16 v[24:27], v[150:153], v[174:177], v[24:27]
	v_mfma_f32_16x16x32_bf16 v[12:15], v[138:141], v[182:185], v[12:15]
	v_mfma_f32_16x16x32_bf16 v[8:11], v[150:153], v[182:185], v[8:11]
	v_mfma_f32_16x16x32_bf16 v[60:63], v[142:145], v[162:165], v[60:63]
	v_mfma_f32_16x16x32_bf16 v[56:59], v[154:157], v[162:165], v[56:59]
	v_mfma_f32_16x16x32_bf16 v[44:47], v[142:145], v[170:173], v[44:47]
	v_mfma_f32_16x16x32_bf16 v[40:43], v[154:157], v[170:173], v[40:43]
	v_mfma_f32_16x16x32_bf16 v[28:31], v[142:145], v[178:181], v[28:31]
	v_mfma_f32_16x16x32_bf16 v[24:27], v[154:157], v[178:181], v[24:27]
	v_mfma_f32_16x16x32_bf16 v[12:15], v[142:145], v[186:189], v[12:15]
	v_mfma_f32_16x16x32_bf16 v[8:11], v[154:157], v[186:189], v[8:11]
	s_setprio 0
	s_barrier
	s_add_i32 s8, s9, s29
	v_lshl_add_u64 v[138:139], v[206:207], 0, s[36:37]
	s_mov_b32 m0, s8
	s_nop 0
	global_load_lds_dwordx4 v[138:139], off
	v_lshl_add_u64 v[138:139], v[206:207], 0, s[38:39]
	s_add_i32 m0, s8, 0x2000
	s_nop 0
	global_load_lds_dwordx4 v[138:139], off
	s_waitcnt vmcnt(6)
	s_barrier
	s_setprio 1
	v_mfma_f32_16x16x32_bf16 v[52:55], v[190:193], v[158:161], v[52:55]
	v_mfma_f32_16x16x32_bf16 v[48:51], v[198:201], v[158:161], v[48:51]
	v_mfma_f32_16x16x32_bf16 v[36:39], v[190:193], v[166:169], v[36:39]
	v_mfma_f32_16x16x32_bf16 v[32:35], v[198:201], v[166:169], v[32:35]
	v_mfma_f32_16x16x32_bf16 v[20:23], v[190:193], v[174:177], v[20:23]
	v_mfma_f32_16x16x32_bf16 v[16:19], v[198:201], v[174:177], v[16:19]
	v_mfma_f32_16x16x32_bf16 v[4:7], v[190:193], v[182:185], v[4:7]
	v_mfma_f32_16x16x32_bf16 v[0:3], v[198:201], v[182:185], v[0:3]
	v_mfma_f32_16x16x32_bf16 v[52:55], v[194:197], v[162:165], v[52:55]
	v_mfma_f32_16x16x32_bf16 v[48:51], v[202:205], v[162:165], v[48:51]
	v_mfma_f32_16x16x32_bf16 v[36:39], v[194:197], v[170:173], v[36:39]
	v_mfma_f32_16x16x32_bf16 v[32:35], v[202:205], v[170:173], v[32:35]
	v_mfma_f32_16x16x32_bf16 v[20:23], v[194:197], v[178:181], v[20:23]
	v_mfma_f32_16x16x32_bf16 v[16:19], v[202:205], v[178:181], v[16:19]
	v_mfma_f32_16x16x32_bf16 v[4:7], v[194:197], v[186:189], v[4:7]
	v_mfma_f32_16x16x32_bf16 v[0:3], v[202:205], v[186:189], v[0:3]
	s_setprio 0
	s_add_i32 s59, s59, 2
	s_add_u32 s57, s57, 0x100
	s_addc_u32 s58, s58, 0
	s_cmp_lt_u32 s59, 6
	s_mov_b64 s[8:9], s[10:11]
	s_barrier
	s_cbranch_scc1 .LBB0_954
	v_mov_b32_e32 v142, v222
	s_lshl_b32 s6, s6, 8
	v_lshrrev_b32_e32 v138, 1, v142
	v_and_b32_e32 v138, 0x78, v138
	v_lshl_or_b32 v140, s7, 8, v138
	v_ashrrev_i32_e32 v141, 31, v140
	v_lshl_add_u64 v[138:139], v[140:141], 2, s[22:23]
	v_ashrrev_i32_e32 v143, 2, v142
	v_and_b32_e32 v143, 0xffffffc0, v143
	v_and_or_b32 v142, v142, 15, s6
	v_add_u32_e32 v142, v142, v143
	v_ashrrev_i32_e32 v143, 31, v142
	v_lshlrev_b64 v[144:145], 10, v[142:143]
	v_lshl_add_u64 v[144:145], s[24:25], 0, v[144:145]
	v_lshlrev_b64 v[140:141], 1, v[140:141]
	v_lshl_add_u64 v[144:145], v[144:145], 0, v[140:141]
	v_lshlrev_b64 v[162:163], 12, v[142:143]
	s_mov_b64 s[10:11], s[46:47]
	s_mov_b64 s[8:9], s[44:45]
	s_andn2_b64 vcc, exec, s[4:5]
	s_mov_b32 s7, s40
	s_mov_b32 s6, s42
	v_lshl_add_u64 v[162:163], s[26:27], 0, v[162:163]
	v_lshl_add_u64 v[162:163], v[162:163], 0, v[140:141]
	s_mov_b32 s99, 0
	global_load_dwordx4 v[150:153], v[138:139], off offset:2048
	global_load_dwordx4 v[154:157], v[138:139], off offset:2064
	global_load_dwordx4 v[158:161], v[138:139], off offset:2560
	global_load_dwordx4 v[164:167], v[138:139], off offset:2576
	global_load_dwordx4 v[168:171], v[144:145], off
	global_load_dwordx4 v[172:175], v[144:145], off offset:256
	s_mov_b32 s98, 0x4000
	v_lshl_add_u64 v[144:145], v[144:145], 0, s[98:99]
	global_load_dwordx4 v[176:179], v[144:145], off
	global_load_dwordx4 v[180:183], v[144:145], off offset:256
	s_mov_b32 s98, 0x4000
	v_lshl_add_u64 v[144:145], v[144:145], 0, s[98:99]
	global_load_dwordx4 v[184:187], v[144:145], off
	global_load_dwordx4 v[188:191], v[144:145], off offset:256
	s_mov_b32 s98, 0x4000
	v_lshl_add_u64 v[144:145], v[144:145], 0, s[98:99]
	global_load_dwordx4 v[192:195], v[144:145], off
	global_load_dwordx4 v[196:199], v[144:145], off offset:256
	s_mov_b32 s98, 0x14000
	v_lshl_add_u64 v[144:145], v[144:145], 0, s[98:99]
	global_load_dwordx4 v[200:203], v[144:145], off
	global_load_dwordx4 v[204:207], v[144:145], off offset:256
	s_mov_b32 s98, 0x4000
	v_lshl_add_u64 v[144:145], v[144:145], 0, s[98:99]
	global_load_dwordx4 v[208:211], v[144:145], off
	global_load_dwordx4 v[212:215], v[144:145], off offset:256
	s_mov_b32 s98, 0x4000
	v_lshl_add_u64 v[144:145], v[144:145], 0, s[98:99]
	global_load_dwordx4 v[216:219], v[144:145], off
	global_load_dwordx4 v[224:227], v[144:145], off offset:256
	s_mov_b32 s98, 0x4000
	v_lshl_add_u64 v[144:145], v[144:145], 0, s[98:99]
	global_load_dwordx4 v[228:231], v[144:145], off
	global_load_dwordx4 v[232:235], v[144:145], off offset:256
	s_waitcnt vmcnt(0)
; __device__ __forceinline__ unsigned cvt_pk_bf16(float lo, float hi) { unsigned r; asm("v_cvt_pk_bf16_f32 %0, %1, %2" : "=v"(r) : "v"(lo), "v"(hi)); return r; }
; __device__ __forceinline__ float bflo(unsigned w) { return __uint_as_float(w << 16); }
; __device__ __forceinline__ float bfhi(unsigned w) { return __uint_as_float(w & 0xffff0000u); }
; __device__ __forceinline__ float sigmoidf_(float x) { return 1.f / (1.f + __expf(-x)); }
;     __device__ __forceinline__ void operator()(const f32x4 (&acc)[2][2][4][2], const pg8::Unit& u, int wr_, int wc_, int fr_, int fq_) const {
;     ...
;                 for (int bj = 0; bj < 2; ++bj) { const int col = col0 + bj * 128;
;                     const f32x4 b0 = *(const f32x4*)(bias + col), b1 = *(const f32x4*)(bias + col + 4);
;                     const f32x4 v0 = acc[ai][bj][m][0] + b0, v1 = acc[ai][bj][m][1] + b1;
;                     const u32x4 z = *(const u32x4*)(Z + (size_t)row * 512 + col);
;                     u32x4 w;
;                     w.x = cvt_pk_bf16(bflo(z.x) * sigmoidf_(v0[0]), bfhi(z.x) * sigmoidf_(v0[1]));
;                     w.y = cvt_pk_bf16(bflo(z.y) * sigmoidf_(v0[2]), bfhi(z.y) * sigmoidf_(v0[3]));
;                     w.z = cvt_pk_bf16(bflo(z.z) * sigmoidf_(v1[0]), bfhi(z.z) * sigmoidf_(v1[1]));
;                     w.w = cvt_pk_bf16(bflo(z.w) * sigmoidf_(v1[2]), bfhi(z.w) * sigmoidf_(v1[3]));
;                     *(u32x4*)(MIX + (size_t)row * 2048 + 1536 + col) = w; } }
	v_pk_add_f32 v[124:125], v[124:125], v[150:151]
	v_pk_add_f32 v[126:127], v[126:127], v[152:153]
	v_pk_add_f32 v[120:121], v[120:121], v[154:155]
	v_pk_add_f32 v[122:123], v[122:123], v[156:157]
	v_mul_f32_e32 v124, 0xbfb8aa3b, v124
	v_mul_f32_e32 v125, 0xbfb8aa3b, v125
	v_mul_f32_e32 v126, 0xbfb8aa3b, v126
	v_mul_f32_e32 v127, 0xbfb8aa3b, v127
	v_mul_f32_e32 v120, 0xbfb8aa3b, v120
	v_mul_f32_e32 v121, 0xbfb8aa3b, v121
	v_mul_f32_e32 v122, 0xbfb8aa3b, v122
	v_mul_f32_e32 v123, 0xbfb8aa3b, v123
	v_exp_f32_e32 v124, v124
	v_exp_f32_e32 v125, v125
	v_exp_f32_e32 v126, v126
	v_exp_f32_e32 v127, v127
	v_exp_f32_e32 v120, v120
	v_exp_f32_e32 v121, v121
	v_exp_f32_e32 v122, v122
	v_exp_f32_e32 v123, v123
	v_add_f32_e32 v124, 1.0, v124
	v_add_f32_e32 v125, 1.0, v125
	v_add_f32_e32 v126, 1.0, v126
	v_add_f32_e32 v127, 1.0, v127
	v_add_f32_e32 v120, 1.0, v120
	v_add_f32_e32 v121, 1.0, v121
	v_add_f32_e32 v122, 1.0, v122
	v_add_f32_e32 v123, 1.0, v123
	v_rcp_f32_e32 v124, v124
	v_rcp_f32_e32 v125, v125
	v_rcp_f32_e32 v126, v126
	v_rcp_f32_e32 v127, v127
	v_rcp_f32_e32 v120, v120
	v_rcp_f32_e32 v121, v121
	v_rcp_f32_e32 v122, v122
	v_rcp_f32_e32 v123, v123
	v_lshlrev_b32_e32 v236, 16, v168
	v_and_b32_e32 v237, 0xffff0000, v168
	v_lshlrev_b32_e32 v238, 16, v169
	v_and_b32_e32 v239, 0xffff0000, v169
	v_lshlrev_b32_e32 v240, 16, v170
	v_and_b32_e32 v241, 0xffff0000, v170
	v_lshlrev_b32_e32 v242, 16, v171
	v_and_b32_e32 v243, 0xffff0000, v171
	v_mul_f32_e32 v124, v124, v236
	v_mul_f32_e32 v125, v125, v237
	v_mul_f32_e32 v126, v126, v238
	v_mul_f32_e32 v127, v127, v239
	v_mul_f32_e32 v120, v120, v240
	v_mul_f32_e32 v121, v121, v241
	v_mul_f32_e32 v122, v122, v242
	v_mul_f32_e32 v123, v123, v243
	v_cvt_pk_bf16_f32 v124, v124, v125
	v_cvt_pk_bf16_f32 v125, v126, v127
	v_cvt_pk_bf16_f32 v126, v120, v121
	v_cvt_pk_bf16_f32 v127, v122, v123
	global_store_dwordx4 v[162:163], v[124:127], off offset:3072
	v_pk_add_f32 v[116:117], v[116:117], v[158:159]
	v_pk_add_f32 v[118:119], v[118:119], v[160:161]
	v_pk_add_f32 v[112:113], v[112:113], v[164:165]
	v_pk_add_f32 v[114:115], v[114:115], v[166:167]
	v_mul_f32_e32 v116, 0xbfb8aa3b, v116
	v_mul_f32_e32 v117, 0xbfb8aa3b, v117
	v_mul_f32_e32 v118, 0xbfb8aa3b, v118
	v_mul_f32_e32 v119, 0xbfb8aa3b, v119
	v_mul_f32_e32 v112, 0xbfb8aa3b, v112
	v_mul_f32_e32 v113, 0xbfb8aa3b, v113
	v_mul_f32_e32 v114, 0xbfb8aa3b, v114
	v_mul_f32_e32 v115, 0xbfb8aa3b, v115
	v_exp_f32_e32 v116, v116
	v_exp_f32_e32 v117, v117
	v_exp_f32_e32 v118, v118
	v_exp_f32_e32 v119, v119
	v_exp_f32_e32 v112, v112
	v_exp_f32_e32 v113, v113
	v_exp_f32_e32 v114, v114
	v_exp_f32_e32 v115, v115
	v_add_f32_e32 v116, 1.0, v116
	v_add_f32_e32 v117, 1.0, v117
	v_add_f32_e32 v118, 1.0, v118
	v_add_f32_e32 v119, 1.0, v119
	v_add_f32_e32 v112, 1.0, v112
	v_add_f32_e32 v113, 1.0, v113
	v_add_f32_e32 v114, 1.0, v114
	v_add_f32_e32 v115, 1.0, v115
	v_rcp_f32_e32 v116, v116
	v_rcp_f32_e32 v117, v117
	v_rcp_f32_e32 v118, v118
	v_rcp_f32_e32 v119, v119
	v_rcp_f32_e32 v112, v112
	v_rcp_f32_e32 v113, v113
	v_rcp_f32_e32 v114, v114
	v_rcp_f32_e32 v115, v115
	v_lshlrev_b32_e32 v236, 16, v172
	v_and_b32_e32 v237, 0xffff0000, v172
	v_lshlrev_b32_e32 v238, 16, v173
	v_and_b32_e32 v239, 0xffff0000, v173
	v_lshlrev_b32_e32 v240, 16, v174
	v_and_b32_e32 v241, 0xffff0000, v174
	v_lshlrev_b32_e32 v242, 16, v175
	v_and_b32_e32 v243, 0xffff0000, v175
	v_mul_f32_e32 v116, v116, v236
	v_mul_f32_e32 v117, v117, v237
	v_mul_f32_e32 v118, v118, v238
	v_mul_f32_e32 v119, v119, v239
	v_mul_f32_e32 v112, v112, v240
	v_mul_f32_e32 v113, v113, v241
	v_mul_f32_e32 v114, v114, v242
	v_mul_f32_e32 v115, v115, v243
	v_cvt_pk_bf16_f32 v116, v116, v117
	v_cvt_pk_bf16_f32 v117, v118, v119
	v_cvt_pk_bf16_f32 v118, v112, v113
	v_cvt_pk_bf16_f32 v119, v114, v115
	global_store_dwordx4 v[162:163], v[116:119], off offset:3328
	s_mov_b32 s98, 0x10000
	v_lshl_add_u64 v[162:163], v[162:163], 0, s[98:99]
	v_pk_add_f32 v[108:109], v[108:109], v[150:151]
	v_pk_add_f32 v[110:111], v[110:111], v[152:153]
	v_pk_add_f32 v[104:105], v[104:105], v[154:155]
	v_pk_add_f32 v[106:107], v[106:107], v[156:157]
	v_mul_f32_e32 v108, 0xbfb8aa3b, v108
	v_mul_f32_e32 v109, 0xbfb8aa3b, v109
	v_mul_f32_e32 v110, 0xbfb8aa3b, v110
	v_mul_f32_e32 v111, 0xbfb8aa3b, v111
	v_mul_f32_e32 v104, 0xbfb8aa3b, v104
	v_mul_f32_e32 v105, 0xbfb8aa3b, v105
	v_mul_f32_e32 v106, 0xbfb8aa3b, v106
	v_mul_f32_e32 v107, 0xbfb8aa3b, v107
	v_exp_f32_e32 v108, v108
	v_exp_f32_e32 v109, v109
	v_exp_f32_e32 v110, v110
	v_exp_f32_e32 v111, v111
	v_exp_f32_e32 v104, v104
	v_exp_f32_e32 v105, v105
	v_exp_f32_e32 v106, v106
	v_exp_f32_e32 v107, v107
	v_add_f32_e32 v108, 1.0, v108
	v_add_f32_e32 v109, 1.0, v109
	v_add_f32_e32 v110, 1.0, v110
	v_add_f32_e32 v111, 1.0, v111
	v_add_f32_e32 v104, 1.0, v104
	v_add_f32_e32 v105, 1.0, v105
	v_add_f32_e32 v106, 1.0, v106
	v_add_f32_e32 v107, 1.0, v107
	v_rcp_f32_e32 v108, v108
	v_rcp_f32_e32 v109, v109
	v_rcp_f32_e32 v110, v110
	v_rcp_f32_e32 v111, v111
	v_rcp_f32_e32 v104, v104
	v_rcp_f32_e32 v105, v105
	v_rcp_f32_e32 v106, v106
	v_rcp_f32_e32 v107, v107
	v_lshlrev_b32_e32 v236, 16, v176
	v_and_b32_e32 v237, 0xffff0000, v176
	v_lshlrev_b32_e32 v238, 16, v177
	v_and_b32_e32 v239, 0xffff0000, v177
	v_lshlrev_b32_e32 v240, 16, v178
	v_and_b32_e32 v241, 0xffff0000, v178
	v_lshlrev_b32_e32 v242, 16, v179
	v_and_b32_e32 v243, 0xffff0000, v179
	v_mul_f32_e32 v108, v108, v236
	v_mul_f32_e32 v109, v109, v237
	v_mul_f32_e32 v110, v110, v238
	v_mul_f32_e32 v111, v111, v239
	v_mul_f32_e32 v104, v104, v240
	v_mul_f32_e32 v105, v105, v241
	v_mul_f32_e32 v106, v106, v242
	v_mul_f32_e32 v107, v107, v243
	v_cvt_pk_bf16_f32 v108, v108, v109
; __device__ __forceinline__ unsigned cvt_pk_bf16(float lo, float hi) { unsigned r; asm("v_cvt_pk_bf16_f32 %0, %1, %2" : "=v"(r) : "v"(lo), "v"(hi)); return r; }
; __device__ __forceinline__ float bflo(unsigned w) { return __uint_as_float(w << 16); }
; __device__ __forceinline__ float bfhi(unsigned w) { return __uint_as_float(w & 0xffff0000u); }
; __device__ __forceinline__ float sigmoidf_(float x) { return 1.f / (1.f + __expf(-x)); }
;     __device__ __forceinline__ void operator()(const f32x4 (&acc)[2][2][4][2], const pg8::Unit& u, int wr_, int wc_, int fr_, int fq_) const {
;     ...
;                 for (int bj = 0; bj < 2; ++bj) { const int col = col0 + bj * 128;
;                     const f32x4 b0 = *(const f32x4*)(bias + col), b1 = *(const f32x4*)(bias + col + 4);
;                     const f32x4 v0 = acc[ai][bj][m][0] + b0, v1 = acc[ai][bj][m][1] + b1;
;                     const u32x4 z = *(const u32x4*)(Z + (size_t)row * 512 + col);
;                     u32x4 w;
;                     w.x = cvt_pk_bf16(bflo(z.x) * sigmoidf_(v0[0]), bfhi(z.x) * sigmoidf_(v0[1]));
;                     w.y = cvt_pk_bf16(bflo(z.y) * sigmoidf_(v0[2]), bfhi(z.y) * sigmoidf_(v0[3]));
;                     w.z = cvt_pk_bf16(bflo(z.z) * sigmoidf_(v1[0]), bfhi(z.z) * sigmoidf_(v1[1]));
;                     w.w = cvt_pk_bf16(bflo(z.w) * sigmoidf_(v1[2]), bfhi(z.w) * sigmoidf_(v1[3]));
;                     *(u32x4*)(MIX + (size_t)row * 2048 + 1536 + col) = w; } }
	v_cvt_pk_bf16_f32 v109, v110, v111
	v_cvt_pk_bf16_f32 v110, v104, v105
	v_cvt_pk_bf16_f32 v111, v106, v107
	global_store_dwordx4 v[162:163], v[108:111], off offset:3072
	v_pk_add_f32 v[100:101], v[100:101], v[158:159]
	v_pk_add_f32 v[102:103], v[102:103], v[160:161]
	v_pk_add_f32 v[96:97], v[96:97], v[164:165]
	v_pk_add_f32 v[98:99], v[98:99], v[166:167]
	v_mul_f32_e32 v100, 0xbfb8aa3b, v100
	v_mul_f32_e32 v101, 0xbfb8aa3b, v101
	v_mul_f32_e32 v102, 0xbfb8aa3b, v102
	v_mul_f32_e32 v103, 0xbfb8aa3b, v103
	v_mul_f32_e32 v96, 0xbfb8aa3b, v96
	v_mul_f32_e32 v97, 0xbfb8aa3b, v97
	v_mul_f32_e32 v98, 0xbfb8aa3b, v98
	v_mul_f32_e32 v99, 0xbfb8aa3b, v99
	v_exp_f32_e32 v100, v100
	v_exp_f32_e32 v101, v101
	v_exp_f32_e32 v102, v102
	v_exp_f32_e32 v103, v103
	v_exp_f32_e32 v96, v96
	v_exp_f32_e32 v97, v97
	v_exp_f32_e32 v98, v98
	v_exp_f32_e32 v99, v99
	v_add_f32_e32 v100, 1.0, v100
	v_add_f32_e32 v101, 1.0, v101
	v_add_f32_e32 v102, 1.0, v102
	v_add_f32_e32 v103, 1.0, v103
	v_add_f32_e32 v96, 1.0, v96
	v_add_f32_e32 v97, 1.0, v97
	v_add_f32_e32 v98, 1.0, v98
	v_add_f32_e32 v99, 1.0, v99
	v_rcp_f32_e32 v100, v100
	v_rcp_f32_e32 v101, v101
	v_rcp_f32_e32 v102, v102
	v_rcp_f32_e32 v103, v103
	v_rcp_f32_e32 v96, v96
	v_rcp_f32_e32 v97, v97
	v_rcp_f32_e32 v98, v98
	v_rcp_f32_e32 v99, v99
	v_lshlrev_b32_e32 v236, 16, v180
	v_and_b32_e32 v237, 0xffff0000, v180
	v_lshlrev_b32_e32 v238, 16, v181
	v_and_b32_e32 v239, 0xffff0000, v181
	v_lshlrev_b32_e32 v240, 16, v182
	v_and_b32_e32 v241, 0xffff0000, v182
	v_lshlrev_b32_e32 v242, 16, v183
	v_and_b32_e32 v243, 0xffff0000, v183
	v_mul_f32_e32 v100, v100, v236
	v_mul_f32_e32 v101, v101, v237
	v_mul_f32_e32 v102, v102, v238
	v_mul_f32_e32 v103, v103, v239
	v_mul_f32_e32 v96, v96, v240
	v_mul_f32_e32 v97, v97, v241
	v_mul_f32_e32 v98, v98, v242
	v_mul_f32_e32 v99, v99, v243
	v_cvt_pk_bf16_f32 v100, v100, v101
	v_cvt_pk_bf16_f32 v101, v102, v103
	v_cvt_pk_bf16_f32 v102, v96, v97
	v_cvt_pk_bf16_f32 v103, v98, v99
	global_store_dwordx4 v[162:163], v[100:103], off offset:3328
	s_mov_b32 s98, 0x10000
	v_lshl_add_u64 v[162:163], v[162:163], 0, s[98:99]
	v_pk_add_f32 v[92:93], v[92:93], v[150:151]
	v_pk_add_f32 v[94:95], v[94:95], v[152:153]
	v_pk_add_f32 v[88:89], v[88:89], v[154:155]
	v_pk_add_f32 v[90:91], v[90:91], v[156:157]
	v_mul_f32_e32 v92, 0xbfb8aa3b, v92
	v_mul_f32_e32 v93, 0xbfb8aa3b, v93
	v_mul_f32_e32 v94, 0xbfb8aa3b, v94
	v_mul_f32_e32 v95, 0xbfb8aa3b, v95
	v_mul_f32_e32 v88, 0xbfb8aa3b, v88
	v_mul_f32_e32 v89, 0xbfb8aa3b, v89
	v_mul_f32_e32 v90, 0xbfb8aa3b, v90
	v_mul_f32_e32 v91, 0xbfb8aa3b, v91
	v_exp_f32_e32 v92, v92
	v_exp_f32_e32 v93, v93
	v_exp_f32_e32 v94, v94
	v_exp_f32_e32 v95, v95
	v_exp_f32_e32 v88, v88
	v_exp_f32_e32 v89, v89
	v_exp_f32_e32 v90, v90
	v_exp_f32_e32 v91, v91
	v_add_f32_e32 v92, 1.0, v92
	v_add_f32_e32 v93, 1.0, v93
	v_add_f32_e32 v94, 1.0, v94
	v_add_f32_e32 v95, 1.0, v95
	v_add_f32_e32 v88, 1.0, v88
	v_add_f32_e32 v89, 1.0, v89
	v_add_f32_e32 v90, 1.0, v90
	v_add_f32_e32 v91, 1.0, v91
	v_rcp_f32_e32 v92, v92
	v_rcp_f32_e32 v93, v93
	v_rcp_f32_e32 v94, v94
	v_rcp_f32_e32 v95, v95
	v_rcp_f32_e32 v88, v88
	v_rcp_f32_e32 v89, v89
	v_rcp_f32_e32 v90, v90
	v_rcp_f32_e32 v91, v91
	v_lshlrev_b32_e32 v236, 16, v184
	v_and_b32_e32 v237, 0xffff0000, v184
	v_lshlrev_b32_e32 v238, 16, v185
	v_and_b32_e32 v239, 0xffff0000, v185
	v_lshlrev_b32_e32 v240, 16, v186
	v_and_b32_e32 v241, 0xffff0000, v186
	v_lshlrev_b32_e32 v242, 16, v187
	v_and_b32_e32 v243, 0xffff0000, v187
	v_mul_f32_e32 v92, v92, v236
	v_mul_f32_e32 v93, v93, v237
	v_mul_f32_e32 v94, v94, v238
	v_mul_f32_e32 v95, v95, v239
	v_mul_f32_e32 v88, v88, v240
	v_mul_f32_e32 v89, v89, v241
	v_mul_f32_e32 v90, v90, v242
	v_mul_f32_e32 v91, v91, v243
	v_cvt_pk_bf16_f32 v92, v92, v93
	v_cvt_pk_bf16_f32 v93, v94, v95
	v_cvt_pk_bf16_f32 v94, v88, v89
	v_cvt_pk_bf16_f32 v95, v90, v91
	global_store_dwordx4 v[162:163], v[92:95], off offset:3072
	v_pk_add_f32 v[84:85], v[84:85], v[158:159]
	v_pk_add_f32 v[86:87], v[86:87], v[160:161]
	v_pk_add_f32 v[80:81], v[80:81], v[164:165]
	v_pk_add_f32 v[82:83], v[82:83], v[166:167]
	v_mul_f32_e32 v84, 0xbfb8aa3b, v84
	v_mul_f32_e32 v85, 0xbfb8aa3b, v85
	v_mul_f32_e32 v86, 0xbfb8aa3b, v86
	v_mul_f32_e32 v87, 0xbfb8aa3b, v87
	v_mul_f32_e32 v80, 0xbfb8aa3b, v80
	v_mul_f32_e32 v81, 0xbfb8aa3b, v81
	v_mul_f32_e32 v82, 0xbfb8aa3b, v82
	v_mul_f32_e32 v83, 0xbfb8aa3b, v83
	v_exp_f32_e32 v84, v84
	v_exp_f32_e32 v85, v85
	v_exp_f32_e32 v86, v86
	v_exp_f32_e32 v87, v87
	v_exp_f32_e32 v80, v80
	v_exp_f32_e32 v81, v81
	v_exp_f32_e32 v82, v82
	v_exp_f32_e32 v83, v83
	v_add_f32_e32 v84, 1.0, v84
	v_add_f32_e32 v85, 1.0, v85
	v_add_f32_e32 v86, 1.0, v86
	v_add_f32_e32 v87, 1.0, v87
	v_add_f32_e32 v80, 1.0, v80
	v_add_f32_e32 v81, 1.0, v81
	v_add_f32_e32 v82, 1.0, v82
	v_add_f32_e32 v83, 1.0, v83
	v_rcp_f32_e32 v84, v84
	v_rcp_f32_e32 v85, v85
	v_rcp_f32_e32 v86, v86
	v_rcp_f32_e32 v87, v87
	v_rcp_f32_e32 v80, v80
	v_rcp_f32_e32 v81, v81
	v_rcp_f32_e32 v82, v82
	v_rcp_f32_e32 v83, v83
	v_lshlrev_b32_e32 v236, 16, v188
	v_and_b32_e32 v237, 0xffff0000, v188
	v_lshlrev_b32_e32 v238, 16, v189
	v_and_b32_e32 v239, 0xffff0000, v189
	v_lshlrev_b32_e32 v240, 16, v190
	v_and_b32_e32 v241, 0xffff0000, v190
	v_lshlrev_b32_e32 v242, 16, v191
	v_and_b32_e32 v243, 0xffff0000, v191
	v_mul_f32_e32 v84, v84, v236
	v_mul_f32_e32 v85, v85, v237
	v_mul_f32_e32 v86, v86, v238
	v_mul_f32_e32 v87, v87, v239
	v_mul_f32_e32 v80, v80, v240
	v_mul_f32_e32 v81, v81, v241
	v_mul_f32_e32 v82, v82, v242
	v_mul_f32_e32 v83, v83, v243
	v_cvt_pk_bf16_f32 v84, v84, v85
	v_cvt_pk_bf16_f32 v85, v86, v87
	v_cvt_pk_bf16_f32 v86, v80, v81
	v_cvt_pk_bf16_f32 v87, v82, v83
; __device__ __forceinline__ unsigned cvt_pk_bf16(float lo, float hi) { unsigned r; asm("v_cvt_pk_bf16_f32 %0, %1, %2" : "=v"(r) : "v"(lo), "v"(hi)); return r; }
; __device__ __forceinline__ float bflo(unsigned w) { return __uint_as_float(w << 16); }
; __device__ __forceinline__ float bfhi(unsigned w) { return __uint_as_float(w & 0xffff0000u); }
; __device__ __forceinline__ float sigmoidf_(float x) { return 1.f / (1.f + __expf(-x)); }
;     __device__ __forceinline__ void operator()(const f32x4 (&acc)[2][2][4][2], const pg8::Unit& u, int wr_, int wc_, int fr_, int fq_) const {
;     ...
;                 for (int bj = 0; bj < 2; ++bj) { const int col = col0 + bj * 128;
;                     const f32x4 b0 = *(const f32x4*)(bias + col), b1 = *(const f32x4*)(bias + col + 4);
;                     const f32x4 v0 = acc[ai][bj][m][0] + b0, v1 = acc[ai][bj][m][1] + b1;
;                     const u32x4 z = *(const u32x4*)(Z + (size_t)row * 512 + col);
;                     u32x4 w;
;                     w.x = cvt_pk_bf16(bflo(z.x) * sigmoidf_(v0[0]), bfhi(z.x) * sigmoidf_(v0[1]));
;                     w.y = cvt_pk_bf16(bflo(z.y) * sigmoidf_(v0[2]), bfhi(z.y) * sigmoidf_(v0[3]));
;                     w.z = cvt_pk_bf16(bflo(z.z) * sigmoidf_(v1[0]), bfhi(z.z) * sigmoidf_(v1[1]));
;                     w.w = cvt_pk_bf16(bflo(z.w) * sigmoidf_(v1[2]), bfhi(z.w) * sigmoidf_(v1[3]));
;                     *(u32x4*)(MIX + (size_t)row * 2048 + 1536 + col) = w; } }
	global_store_dwordx4 v[162:163], v[84:87], off offset:3328
	s_mov_b32 s98, 0x10000
	v_lshl_add_u64 v[162:163], v[162:163], 0, s[98:99]
	v_pk_add_f32 v[76:77], v[76:77], v[150:151]
	v_pk_add_f32 v[78:79], v[78:79], v[152:153]
	v_pk_add_f32 v[72:73], v[72:73], v[154:155]
	v_pk_add_f32 v[74:75], v[74:75], v[156:157]
	v_mul_f32_e32 v76, 0xbfb8aa3b, v76
	v_mul_f32_e32 v77, 0xbfb8aa3b, v77
	v_mul_f32_e32 v78, 0xbfb8aa3b, v78
	v_mul_f32_e32 v79, 0xbfb8aa3b, v79
	v_mul_f32_e32 v72, 0xbfb8aa3b, v72
	v_mul_f32_e32 v73, 0xbfb8aa3b, v73
	v_mul_f32_e32 v74, 0xbfb8aa3b, v74
	v_mul_f32_e32 v75, 0xbfb8aa3b, v75
	v_exp_f32_e32 v76, v76
	v_exp_f32_e32 v77, v77
	v_exp_f32_e32 v78, v78
	v_exp_f32_e32 v79, v79
	v_exp_f32_e32 v72, v72
	v_exp_f32_e32 v73, v73
	v_exp_f32_e32 v74, v74
	v_exp_f32_e32 v75, v75
	v_add_f32_e32 v76, 1.0, v76
	v_add_f32_e32 v77, 1.0, v77
	v_add_f32_e32 v78, 1.0, v78
	v_add_f32_e32 v79, 1.0, v79
	v_add_f32_e32 v72, 1.0, v72
	v_add_f32_e32 v73, 1.0, v73
	v_add_f32_e32 v74, 1.0, v74
	v_add_f32_e32 v75, 1.0, v75
	v_rcp_f32_e32 v76, v76
	v_rcp_f32_e32 v77, v77
	v_rcp_f32_e32 v78, v78
	v_rcp_f32_e32 v79, v79
	v_rcp_f32_e32 v72, v72
	v_rcp_f32_e32 v73, v73
	v_rcp_f32_e32 v74, v74
	v_rcp_f32_e32 v75, v75
	v_lshlrev_b32_e32 v236, 16, v192
	v_and_b32_e32 v237, 0xffff0000, v192
	v_lshlrev_b32_e32 v238, 16, v193
	v_and_b32_e32 v239, 0xffff0000, v193
	v_lshlrev_b32_e32 v240, 16, v194
	v_and_b32_e32 v241, 0xffff0000, v194
	v_lshlrev_b32_e32 v242, 16, v195
	v_and_b32_e32 v243, 0xffff0000, v195
	v_mul_f32_e32 v76, v76, v236
	v_mul_f32_e32 v77, v77, v237
	v_mul_f32_e32 v78, v78, v238
	v_mul_f32_e32 v79, v79, v239
	v_mul_f32_e32 v72, v72, v240
	v_mul_f32_e32 v73, v73, v241
	v_mul_f32_e32 v74, v74, v242
	v_mul_f32_e32 v75, v75, v243
	v_cvt_pk_bf16_f32 v76, v76, v77
	v_cvt_pk_bf16_f32 v77, v78, v79
	v_cvt_pk_bf16_f32 v78, v72, v73
	v_cvt_pk_bf16_f32 v79, v74, v75
	global_store_dwordx4 v[162:163], v[76:79], off offset:3072
	v_pk_add_f32 v[68:69], v[68:69], v[158:159]
	v_pk_add_f32 v[70:71], v[70:71], v[160:161]
	v_pk_add_f32 v[64:65], v[64:65], v[164:165]
	v_pk_add_f32 v[66:67], v[66:67], v[166:167]
	v_mul_f32_e32 v68, 0xbfb8aa3b, v68
	v_mul_f32_e32 v69, 0xbfb8aa3b, v69
	v_mul_f32_e32 v70, 0xbfb8aa3b, v70
	v_mul_f32_e32 v71, 0xbfb8aa3b, v71
	v_mul_f32_e32 v64, 0xbfb8aa3b, v64
	v_mul_f32_e32 v65, 0xbfb8aa3b, v65
	v_mul_f32_e32 v66, 0xbfb8aa3b, v66
	v_mul_f32_e32 v67, 0xbfb8aa3b, v67
	v_exp_f32_e32 v68, v68
	v_exp_f32_e32 v69, v69
	v_exp_f32_e32 v70, v70
	v_exp_f32_e32 v71, v71
	v_exp_f32_e32 v64, v64
	v_exp_f32_e32 v65, v65
	v_exp_f32_e32 v66, v66
	v_exp_f32_e32 v67, v67
	v_add_f32_e32 v68, 1.0, v68
	v_add_f32_e32 v69, 1.0, v69
	v_add_f32_e32 v70, 1.0, v70
	v_add_f32_e32 v71, 1.0, v71
	v_add_f32_e32 v64, 1.0, v64
	v_add_f32_e32 v65, 1.0, v65
	v_add_f32_e32 v66, 1.0, v66
	v_add_f32_e32 v67, 1.0, v67
	v_rcp_f32_e32 v68, v68
	v_rcp_f32_e32 v69, v69
	v_rcp_f32_e32 v70, v70
	v_rcp_f32_e32 v71, v71
	v_rcp_f32_e32 v64, v64
	v_rcp_f32_e32 v65, v65
	v_rcp_f32_e32 v66, v66
	v_rcp_f32_e32 v67, v67
	v_lshlrev_b32_e32 v236, 16, v196
	v_and_b32_e32 v237, 0xffff0000, v196
	v_lshlrev_b32_e32 v238, 16, v197
	v_and_b32_e32 v239, 0xffff0000, v197
	v_lshlrev_b32_e32 v240, 16, v198
	v_and_b32_e32 v241, 0xffff0000, v198
	v_lshlrev_b32_e32 v242, 16, v199
	v_and_b32_e32 v243, 0xffff0000, v199
	v_mul_f32_e32 v68, v68, v236
	v_mul_f32_e32 v69, v69, v237
	v_mul_f32_e32 v70, v70, v238
	v_mul_f32_e32 v71, v71, v239
	v_mul_f32_e32 v64, v64, v240
	v_mul_f32_e32 v65, v65, v241
	v_mul_f32_e32 v66, v66, v242
	v_mul_f32_e32 v67, v67, v243
	v_cvt_pk_bf16_f32 v68, v68, v69
	v_cvt_pk_bf16_f32 v69, v70, v71
	v_cvt_pk_bf16_f32 v70, v64, v65
	v_cvt_pk_bf16_f32 v71, v66, v67
	global_store_dwordx4 v[162:163], v[68:71], off offset:3328
	s_mov_b32 s98, 0x50000
	v_lshl_add_u64 v[162:163], v[162:163], 0, s[98:99]
	v_pk_add_f32 v[60:61], v[60:61], v[150:151]
	v_pk_add_f32 v[62:63], v[62:63], v[152:153]
	v_pk_add_f32 v[56:57], v[56:57], v[154:155]
	v_pk_add_f32 v[58:59], v[58:59], v[156:157]
	v_mul_f32_e32 v60, 0xbfb8aa3b, v60
	v_mul_f32_e32 v61, 0xbfb8aa3b, v61
	v_mul_f32_e32 v62, 0xbfb8aa3b, v62
	v_mul_f32_e32 v63, 0xbfb8aa3b, v63
	v_mul_f32_e32 v56, 0xbfb8aa3b, v56
	v_mul_f32_e32 v57, 0xbfb8aa3b, v57
	v_mul_f32_e32 v58, 0xbfb8aa3b, v58
	v_mul_f32_e32 v59, 0xbfb8aa3b, v59
	v_exp_f32_e32 v60, v60
	v_exp_f32_e32 v61, v61
	v_exp_f32_e32 v62, v62
	v_exp_f32_e32 v63, v63
	v_exp_f32_e32 v56, v56
	v_exp_f32_e32 v57, v57
	v_exp_f32_e32 v58, v58
	v_exp_f32_e32 v59, v59
	v_add_f32_e32 v60, 1.0, v60
	v_add_f32_e32 v61, 1.0, v61
	v_add_f32_e32 v62, 1.0, v62
	v_add_f32_e32 v63, 1.0, v63
	v_add_f32_e32 v56, 1.0, v56
	v_add_f32_e32 v57, 1.0, v57
	v_add_f32_e32 v58, 1.0, v58
	v_add_f32_e32 v59, 1.0, v59
	v_rcp_f32_e32 v60, v60
	v_rcp_f32_e32 v61, v61
	v_rcp_f32_e32 v62, v62
	v_rcp_f32_e32 v63, v63
	v_rcp_f32_e32 v56, v56
	v_rcp_f32_e32 v57, v57
	v_rcp_f32_e32 v58, v58
	v_rcp_f32_e32 v59, v59
	v_lshlrev_b32_e32 v236, 16, v200
	v_and_b32_e32 v237, 0xffff0000, v200
	v_lshlrev_b32_e32 v238, 16, v201
	v_and_b32_e32 v239, 0xffff0000, v201
	v_lshlrev_b32_e32 v240, 16, v202
	v_and_b32_e32 v241, 0xffff0000, v202
	v_lshlrev_b32_e32 v242, 16, v203
	v_and_b32_e32 v243, 0xffff0000, v203
	v_mul_f32_e32 v60, v60, v236
	v_mul_f32_e32 v61, v61, v237
	v_mul_f32_e32 v62, v62, v238
	v_mul_f32_e32 v63, v63, v239
	v_mul_f32_e32 v56, v56, v240
	v_mul_f32_e32 v57, v57, v241
	v_mul_f32_e32 v58, v58, v242
	v_mul_f32_e32 v59, v59, v243
	v_cvt_pk_bf16_f32 v60, v60, v61
	v_cvt_pk_bf16_f32 v61, v62, v63
	v_cvt_pk_bf16_f32 v62, v56, v57
	v_cvt_pk_bf16_f32 v63, v58, v59
	global_store_dwordx4 v[162:163], v[60:63], off offset:3072
; __device__ __forceinline__ unsigned cvt_pk_bf16(float lo, float hi) { unsigned r; asm("v_cvt_pk_bf16_f32 %0, %1, %2" : "=v"(r) : "v"(lo), "v"(hi)); return r; }
; __device__ __forceinline__ float bflo(unsigned w) { return __uint_as_float(w << 16); }
; __device__ __forceinline__ float bfhi(unsigned w) { return __uint_as_float(w & 0xffff0000u); }
; __device__ __forceinline__ float sigmoidf_(float x) { return 1.f / (1.f + __expf(-x)); }
;     __device__ __forceinline__ void operator()(const f32x4 (&acc)[2][2][4][2], const pg8::Unit& u, int wr_, int wc_, int fr_, int fq_) const {
;     ...
;         for (int ai = 0; ai < 2; ++ai)
; #pragma unroll
;             for (int m = 0; m < 4; ++m) { const int row = row0 + ai * 128 + m * 16;
; #pragma unroll
;                 for (int bj = 0; bj < 2; ++bj) { const int col = col0 + bj * 128;
;                     const f32x4 b0 = *(const f32x4*)(bias + col), b1 = *(const f32x4*)(bias + col + 4);
;                     const f32x4 v0 = acc[ai][bj][m][0] + b0, v1 = acc[ai][bj][m][1] + b1;
;                     const u32x4 z = *(const u32x4*)(Z + (size_t)row * 512 + col);
;                     u32x4 w;
;                     w.x = cvt_pk_bf16(bflo(z.x) * sigmoidf_(v0[0]), bfhi(z.x) * sigmoidf_(v0[1]));
;                     w.y = cvt_pk_bf16(bflo(z.y) * sigmoidf_(v0[2]), bfhi(z.y) * sigmoidf_(v0[3]));
;                     w.z = cvt_pk_bf16(bflo(z.z) * sigmoidf_(v1[0]), bfhi(z.z) * sigmoidf_(v1[1]));
;                     w.w = cvt_pk_bf16(bflo(z.w) * sigmoidf_(v1[2]), bfhi(z.w) * sigmoidf_(v1[3]));
;                     *(u32x4*)(MIX + (size_t)row * 2048 + 1536 + col) = w; } }
	v_pk_add_f32 v[52:53], v[52:53], v[158:159]
	v_pk_add_f32 v[54:55], v[54:55], v[160:161]
	v_pk_add_f32 v[48:49], v[48:49], v[164:165]
	v_pk_add_f32 v[50:51], v[50:51], v[166:167]
	v_mul_f32_e32 v52, 0xbfb8aa3b, v52
	v_mul_f32_e32 v53, 0xbfb8aa3b, v53
	v_mul_f32_e32 v54, 0xbfb8aa3b, v54
	v_mul_f32_e32 v55, 0xbfb8aa3b, v55
	v_mul_f32_e32 v48, 0xbfb8aa3b, v48
	v_mul_f32_e32 v49, 0xbfb8aa3b, v49
	v_mul_f32_e32 v50, 0xbfb8aa3b, v50
	v_mul_f32_e32 v51, 0xbfb8aa3b, v51
	v_exp_f32_e32 v52, v52
	v_exp_f32_e32 v53, v53
	v_exp_f32_e32 v54, v54
	v_exp_f32_e32 v55, v55
	v_exp_f32_e32 v48, v48
	v_exp_f32_e32 v49, v49
	v_exp_f32_e32 v50, v50
	v_exp_f32_e32 v51, v51
	v_add_f32_e32 v52, 1.0, v52
	v_add_f32_e32 v53, 1.0, v53
	v_add_f32_e32 v54, 1.0, v54
	v_add_f32_e32 v55, 1.0, v55
	v_add_f32_e32 v48, 1.0, v48
	v_add_f32_e32 v49, 1.0, v49
	v_add_f32_e32 v50, 1.0, v50
	v_add_f32_e32 v51, 1.0, v51
	v_rcp_f32_e32 v52, v52
	v_rcp_f32_e32 v53, v53
	v_rcp_f32_e32 v54, v54
	v_rcp_f32_e32 v55, v55
	v_rcp_f32_e32 v48, v48
	v_rcp_f32_e32 v49, v49
	v_rcp_f32_e32 v50, v50
	v_rcp_f32_e32 v51, v51
	v_lshlrev_b32_e32 v236, 16, v204
	v_and_b32_e32 v237, 0xffff0000, v204
	v_lshlrev_b32_e32 v238, 16, v205
	v_and_b32_e32 v239, 0xffff0000, v205
	v_lshlrev_b32_e32 v240, 16, v206
	v_and_b32_e32 v241, 0xffff0000, v206
	v_lshlrev_b32_e32 v242, 16, v207
	v_and_b32_e32 v243, 0xffff0000, v207
	v_mul_f32_e32 v52, v52, v236
	v_mul_f32_e32 v53, v53, v237
	v_mul_f32_e32 v54, v54, v238
	v_mul_f32_e32 v55, v55, v239
	v_mul_f32_e32 v48, v48, v240
	v_mul_f32_e32 v49, v49, v241
	v_mul_f32_e32 v50, v50, v242
	v_mul_f32_e32 v51, v51, v243
	v_cvt_pk_bf16_f32 v52, v52, v53
	v_cvt_pk_bf16_f32 v53, v54, v55
	v_cvt_pk_bf16_f32 v54, v48, v49
	v_cvt_pk_bf16_f32 v55, v50, v51
	global_store_dwordx4 v[162:163], v[52:55], off offset:3328
	s_mov_b32 s98, 0x10000
	v_lshl_add_u64 v[162:163], v[162:163], 0, s[98:99]
	v_pk_add_f32 v[44:45], v[44:45], v[150:151]
	v_pk_add_f32 v[46:47], v[46:47], v[152:153]
	v_pk_add_f32 v[40:41], v[40:41], v[154:155]
	v_pk_add_f32 v[42:43], v[42:43], v[156:157]
	v_mul_f32_e32 v44, 0xbfb8aa3b, v44
	v_mul_f32_e32 v45, 0xbfb8aa3b, v45
	v_mul_f32_e32 v46, 0xbfb8aa3b, v46
	v_mul_f32_e32 v47, 0xbfb8aa3b, v47
	v_mul_f32_e32 v40, 0xbfb8aa3b, v40
	v_mul_f32_e32 v41, 0xbfb8aa3b, v41
	v_mul_f32_e32 v42, 0xbfb8aa3b, v42
	v_mul_f32_e32 v43, 0xbfb8aa3b, v43
	v_exp_f32_e32 v44, v44
	v_exp_f32_e32 v45, v45
	v_exp_f32_e32 v46, v46
	v_exp_f32_e32 v47, v47
	v_exp_f32_e32 v40, v40
	v_exp_f32_e32 v41, v41
	v_exp_f32_e32 v42, v42
	v_exp_f32_e32 v43, v43
	v_add_f32_e32 v44, 1.0, v44
	v_add_f32_e32 v45, 1.0, v45
	v_add_f32_e32 v46, 1.0, v46
	v_add_f32_e32 v47, 1.0, v47
	v_add_f32_e32 v40, 1.0, v40
	v_add_f32_e32 v41, 1.0, v41
	v_add_f32_e32 v42, 1.0, v42
	v_add_f32_e32 v43, 1.0, v43
	v_rcp_f32_e32 v44, v44
	v_rcp_f32_e32 v45, v45
	v_rcp_f32_e32 v46, v46
	v_rcp_f32_e32 v47, v47
	v_rcp_f32_e32 v40, v40
	v_rcp_f32_e32 v41, v41
	v_rcp_f32_e32 v42, v42
	v_rcp_f32_e32 v43, v43
	v_lshlrev_b32_e32 v236, 16, v208
	v_and_b32_e32 v237, 0xffff0000, v208
	v_lshlrev_b32_e32 v238, 16, v209
	v_and_b32_e32 v239, 0xffff0000, v209
	v_lshlrev_b32_e32 v240, 16, v210
	v_and_b32_e32 v241, 0xffff0000, v210
	v_lshlrev_b32_e32 v242, 16, v211
	v_and_b32_e32 v243, 0xffff0000, v211
	v_mul_f32_e32 v44, v44, v236
	v_mul_f32_e32 v45, v45, v237
	v_mul_f32_e32 v46, v46, v238
	v_mul_f32_e32 v47, v47, v239
	v_mul_f32_e32 v40, v40, v240
	v_mul_f32_e32 v41, v41, v241
	v_mul_f32_e32 v42, v42, v242
	v_mul_f32_e32 v43, v43, v243
	v_cvt_pk_bf16_f32 v44, v44, v45
	v_cvt_pk_bf16_f32 v45, v46, v47
	v_cvt_pk_bf16_f32 v46, v40, v41
	v_cvt_pk_bf16_f32 v47, v42, v43
	global_store_dwordx4 v[162:163], v[44:47], off offset:3072
	v_pk_add_f32 v[36:37], v[36:37], v[158:159]
	v_pk_add_f32 v[38:39], v[38:39], v[160:161]
	v_pk_add_f32 v[32:33], v[32:33], v[164:165]
	v_pk_add_f32 v[34:35], v[34:35], v[166:167]
	v_mul_f32_e32 v36, 0xbfb8aa3b, v36
	v_mul_f32_e32 v37, 0xbfb8aa3b, v37
	v_mul_f32_e32 v38, 0xbfb8aa3b, v38
	v_mul_f32_e32 v39, 0xbfb8aa3b, v39
	v_mul_f32_e32 v32, 0xbfb8aa3b, v32
	v_mul_f32_e32 v33, 0xbfb8aa3b, v33
	v_mul_f32_e32 v34, 0xbfb8aa3b, v34
	v_mul_f32_e32 v35, 0xbfb8aa3b, v35
	v_exp_f32_e32 v36, v36
	v_exp_f32_e32 v37, v37
	v_exp_f32_e32 v38, v38
	v_exp_f32_e32 v39, v39
	v_exp_f32_e32 v32, v32
	v_exp_f32_e32 v33, v33
	v_exp_f32_e32 v34, v34
	v_exp_f32_e32 v35, v35
	v_add_f32_e32 v36, 1.0, v36
	v_add_f32_e32 v37, 1.0, v37
	v_add_f32_e32 v38, 1.0, v38
	v_add_f32_e32 v39, 1.0, v39
	v_add_f32_e32 v32, 1.0, v32
	v_add_f32_e32 v33, 1.0, v33
	v_add_f32_e32 v34, 1.0, v34
	v_add_f32_e32 v35, 1.0, v35
	v_rcp_f32_e32 v36, v36
	v_rcp_f32_e32 v37, v37
	v_rcp_f32_e32 v38, v38
	v_rcp_f32_e32 v39, v39
	v_rcp_f32_e32 v32, v32
	v_rcp_f32_e32 v33, v33
	v_rcp_f32_e32 v34, v34
	v_rcp_f32_e32 v35, v35
	v_lshlrev_b32_e32 v236, 16, v212
	v_and_b32_e32 v237, 0xffff0000, v212
	v_lshlrev_b32_e32 v238, 16, v213
	v_and_b32_e32 v239, 0xffff0000, v213
	v_lshlrev_b32_e32 v240, 16, v214
	v_and_b32_e32 v241, 0xffff0000, v214
	v_lshlrev_b32_e32 v242, 16, v215
	v_and_b32_e32 v243, 0xffff0000, v215
	v_mul_f32_e32 v36, v36, v236
	v_mul_f32_e32 v37, v37, v237
	v_mul_f32_e32 v38, v38, v238
	v_mul_f32_e32 v39, v39, v239
	v_mul_f32_e32 v32, v32, v240
	v_mul_f32_e32 v33, v33, v241
	v_mul_f32_e32 v34, v34, v242
	v_mul_f32_e32 v35, v35, v243
	v_cvt_pk_bf16_f32 v36, v36, v37
	v_cvt_pk_bf16_f32 v37, v38, v39
	v_cvt_pk_bf16_f32 v38, v32, v33
	v_cvt_pk_bf16_f32 v39, v34, v35
	global_store_dwordx4 v[162:163], v[36:39], off offset:3328
	s_mov_b32 s98, 0x10000
	v_lshl_add_u64 v[162:163], v[162:163], 0, s[98:99]
	v_pk_add_f32 v[28:29], v[28:29], v[150:151]
	v_pk_add_f32 v[30:31], v[30:31], v[152:153]
; __device__ __forceinline__ unsigned cvt_pk_bf16(float lo, float hi) { unsigned r; asm("v_cvt_pk_bf16_f32 %0, %1, %2" : "=v"(r) : "v"(lo), "v"(hi)); return r; }
; __device__ __forceinline__ float bflo(unsigned w) { return __uint_as_float(w << 16); }
; __device__ __forceinline__ float bfhi(unsigned w) { return __uint_as_float(w & 0xffff0000u); }
; __device__ __forceinline__ float sigmoidf_(float x) { return 1.f / (1.f + __expf(-x)); }
;     __device__ __forceinline__ void operator()(const f32x4 (&acc)[2][2][4][2], const pg8::Unit& u, int wr_, int wc_, int fr_, int fq_) const {
;     ...
;         for (int ai = 0; ai < 2; ++ai)
; #pragma unroll
;             for (int m = 0; m < 4; ++m) { const int row = row0 + ai * 128 + m * 16;
; #pragma unroll
;                 for (int bj = 0; bj < 2; ++bj) { const int col = col0 + bj * 128;
;                     const f32x4 b0 = *(const f32x4*)(bias + col), b1 = *(const f32x4*)(bias + col + 4);
;                     const f32x4 v0 = acc[ai][bj][m][0] + b0, v1 = acc[ai][bj][m][1] + b1;
;                     const u32x4 z = *(const u32x4*)(Z + (size_t)row * 512 + col);
;                     u32x4 w;
;                     w.x = cvt_pk_bf16(bflo(z.x) * sigmoidf_(v0[0]), bfhi(z.x) * sigmoidf_(v0[1]));
;                     w.y = cvt_pk_bf16(bflo(z.y) * sigmoidf_(v0[2]), bfhi(z.y) * sigmoidf_(v0[3]));
;                     w.z = cvt_pk_bf16(bflo(z.z) * sigmoidf_(v1[0]), bfhi(z.z) * sigmoidf_(v1[1]));
;                     w.w = cvt_pk_bf16(bflo(z.w) * sigmoidf_(v1[2]), bfhi(z.w) * sigmoidf_(v1[3]));
;                     *(u32x4*)(MIX + (size_t)row * 2048 + 1536 + col) = w; } }
	v_pk_add_f32 v[24:25], v[24:25], v[154:155]
	v_pk_add_f32 v[26:27], v[26:27], v[156:157]
	v_mul_f32_e32 v28, 0xbfb8aa3b, v28
	v_mul_f32_e32 v29, 0xbfb8aa3b, v29
	v_mul_f32_e32 v30, 0xbfb8aa3b, v30
	v_mul_f32_e32 v31, 0xbfb8aa3b, v31
	v_mul_f32_e32 v24, 0xbfb8aa3b, v24
	v_mul_f32_e32 v25, 0xbfb8aa3b, v25
	v_mul_f32_e32 v26, 0xbfb8aa3b, v26
	v_mul_f32_e32 v27, 0xbfb8aa3b, v27
	v_exp_f32_e32 v28, v28
	v_exp_f32_e32 v29, v29
	v_exp_f32_e32 v30, v30
	v_exp_f32_e32 v31, v31
	v_exp_f32_e32 v24, v24
	v_exp_f32_e32 v25, v25
	v_exp_f32_e32 v26, v26
	v_exp_f32_e32 v27, v27
	v_add_f32_e32 v28, 1.0, v28
	v_add_f32_e32 v29, 1.0, v29
	v_add_f32_e32 v30, 1.0, v30
	v_add_f32_e32 v31, 1.0, v31
	v_add_f32_e32 v24, 1.0, v24
	v_add_f32_e32 v25, 1.0, v25
	v_add_f32_e32 v26, 1.0, v26
	v_add_f32_e32 v27, 1.0, v27
	v_rcp_f32_e32 v28, v28
	v_rcp_f32_e32 v29, v29
	v_rcp_f32_e32 v30, v30
	v_rcp_f32_e32 v31, v31
	v_rcp_f32_e32 v24, v24
	v_rcp_f32_e32 v25, v25
	v_rcp_f32_e32 v26, v26
	v_rcp_f32_e32 v27, v27
	v_lshlrev_b32_e32 v236, 16, v216
	v_and_b32_e32 v237, 0xffff0000, v216
	v_lshlrev_b32_e32 v238, 16, v217
	v_and_b32_e32 v239, 0xffff0000, v217
	v_lshlrev_b32_e32 v240, 16, v218
	v_and_b32_e32 v241, 0xffff0000, v218
	v_lshlrev_b32_e32 v242, 16, v219
	v_and_b32_e32 v243, 0xffff0000, v219
	v_mul_f32_e32 v28, v28, v236
	v_mul_f32_e32 v29, v29, v237
	v_mul_f32_e32 v30, v30, v238
	v_mul_f32_e32 v31, v31, v239
	v_mul_f32_e32 v24, v24, v240
	v_mul_f32_e32 v25, v25, v241
	v_mul_f32_e32 v26, v26, v242
	v_mul_f32_e32 v27, v27, v243
	v_cvt_pk_bf16_f32 v28, v28, v29
	v_cvt_pk_bf16_f32 v29, v30, v31
	v_cvt_pk_bf16_f32 v30, v24, v25
	v_cvt_pk_bf16_f32 v31, v26, v27
	global_store_dwordx4 v[162:163], v[28:31], off offset:3072
	v_pk_add_f32 v[20:21], v[20:21], v[158:159]
	v_pk_add_f32 v[22:23], v[22:23], v[160:161]
	v_pk_add_f32 v[16:17], v[16:17], v[164:165]
	v_pk_add_f32 v[18:19], v[18:19], v[166:167]
	v_mul_f32_e32 v20, 0xbfb8aa3b, v20
	v_mul_f32_e32 v21, 0xbfb8aa3b, v21
	v_mul_f32_e32 v22, 0xbfb8aa3b, v22
	v_mul_f32_e32 v23, 0xbfb8aa3b, v23
	v_mul_f32_e32 v16, 0xbfb8aa3b, v16
	v_mul_f32_e32 v17, 0xbfb8aa3b, v17
	v_mul_f32_e32 v18, 0xbfb8aa3b, v18
	v_mul_f32_e32 v19, 0xbfb8aa3b, v19
	v_exp_f32_e32 v20, v20
	v_exp_f32_e32 v21, v21
	v_exp_f32_e32 v22, v22
	v_exp_f32_e32 v23, v23
	v_exp_f32_e32 v16, v16
	v_exp_f32_e32 v17, v17
	v_exp_f32_e32 v18, v18
	v_exp_f32_e32 v19, v19
	v_add_f32_e32 v20, 1.0, v20
	v_add_f32_e32 v21, 1.0, v21
	v_add_f32_e32 v22, 1.0, v22
	v_add_f32_e32 v23, 1.0, v23
	v_add_f32_e32 v16, 1.0, v16
	v_add_f32_e32 v17, 1.0, v17
	v_add_f32_e32 v18, 1.0, v18
	v_add_f32_e32 v19, 1.0, v19
	v_rcp_f32_e32 v20, v20
	v_rcp_f32_e32 v21, v21
	v_rcp_f32_e32 v22, v22
	v_rcp_f32_e32 v23, v23
	v_rcp_f32_e32 v16, v16
	v_rcp_f32_e32 v17, v17
	v_rcp_f32_e32 v18, v18
	v_rcp_f32_e32 v19, v19
	v_lshlrev_b32_e32 v236, 16, v224
	v_and_b32_e32 v237, 0xffff0000, v224
	v_lshlrev_b32_e32 v238, 16, v225
	v_and_b32_e32 v239, 0xffff0000, v225
	v_lshlrev_b32_e32 v240, 16, v226
	v_and_b32_e32 v241, 0xffff0000, v226
	v_lshlrev_b32_e32 v242, 16, v227
	v_and_b32_e32 v243, 0xffff0000, v227
	v_mul_f32_e32 v20, v20, v236
	v_mul_f32_e32 v21, v21, v237
	v_mul_f32_e32 v22, v22, v238
	v_mul_f32_e32 v23, v23, v239
	v_mul_f32_e32 v16, v16, v240
	v_mul_f32_e32 v17, v17, v241
	v_mul_f32_e32 v18, v18, v242
	v_mul_f32_e32 v19, v19, v243
	v_cvt_pk_bf16_f32 v20, v20, v21
	v_cvt_pk_bf16_f32 v21, v22, v23
	v_cvt_pk_bf16_f32 v22, v16, v17
	v_cvt_pk_bf16_f32 v23, v18, v19
	global_store_dwordx4 v[162:163], v[20:23], off offset:3328
	s_mov_b32 s98, 0x10000
	v_lshl_add_u64 v[162:163], v[162:163], 0, s[98:99]
; __device__ __forceinline__ unsigned cvt_pk_bf16(float lo, float hi) { unsigned r; asm("v_cvt_pk_bf16_f32 %0, %1, %2" : "=v"(r) : "v"(lo), "v"(hi)); return r; }
; __device__ __forceinline__ float bflo(unsigned w) { return __uint_as_float(w << 16); }
; __device__ __forceinline__ float bfhi(unsigned w) { return __uint_as_float(w & 0xffff0000u); }
; __device__ __forceinline__ float sigmoidf_(float x) { return 1.f / (1.f + __expf(-x)); }
; #define PG8_WAIT_V(n) asm volatile("s_waitcnt vmcnt(" #n ")" ::: "memory")
; #define PG8_BAR __builtin_amdgcn_s_barrier()
; template <class Epi, class Sched>
; __device__ __forceinline__ void gemm_phase(LAS unsigned char* lds, const Gemm g, const Sched& S, const Epi& E) {
;     ...
;     PG8_WAIT_V(0);
;     if (wr == 0) PG8_BAR;
;     PG8_BAR;
;     __device__ __forceinline__ void operator()(const f32x4 (&acc)[2][2][4][2], const pg8::Unit& u, int wr_, int wc_, int fr_, int fq_) const {
;     ...
;         for (int ai = 0; ai < 2; ++ai)
; #pragma unroll
;             for (int m = 0; m < 4; ++m) { const int row = row0 + ai * 128 + m * 16;
; #pragma unroll
;                 for (int bj = 0; bj < 2; ++bj) { const int col = col0 + bj * 128;
;                     const f32x4 b0 = *(const f32x4*)(bias + col), b1 = *(const f32x4*)(bias + col + 4);
;                     const f32x4 v0 = acc[ai][bj][m][0] + b0, v1 = acc[ai][bj][m][1] + b1;
;                     const u32x4 z = *(const u32x4*)(Z + (size_t)row * 512 + col);
;                     u32x4 w;
;                     w.x = cvt_pk_bf16(bflo(z.x) * sigmoidf_(v0[0]), bfhi(z.x) * sigmoidf_(v0[1]));
;                     w.y = cvt_pk_bf16(bflo(z.y) * sigmoidf_(v0[2]), bfhi(z.y) * sigmoidf_(v0[3]));
;                     w.z = cvt_pk_bf16(bflo(z.z) * sigmoidf_(v1[0]), bfhi(z.z) * sigmoidf_(v1[1]));
;                     w.w = cvt_pk_bf16(bflo(z.w) * sigmoidf_(v1[2]), bfhi(z.w) * sigmoidf_(v1[3]));
;                     *(u32x4*)(MIX + (size_t)row * 2048 + 1536 + col) = w; } }
	v_pk_add_f32 v[12:13], v[12:13], v[150:151]
	v_pk_add_f32 v[14:15], v[14:15], v[152:153]
	v_pk_add_f32 v[8:9], v[8:9], v[154:155]
	v_pk_add_f32 v[10:11], v[10:11], v[156:157]
	v_mul_f32_e32 v12, 0xbfb8aa3b, v12
	v_mul_f32_e32 v13, 0xbfb8aa3b, v13
	v_mul_f32_e32 v14, 0xbfb8aa3b, v14
	v_mul_f32_e32 v15, 0xbfb8aa3b, v15
	v_mul_f32_e32 v8, 0xbfb8aa3b, v8
	v_mul_f32_e32 v9, 0xbfb8aa3b, v9
	v_mul_f32_e32 v10, 0xbfb8aa3b, v10
	v_mul_f32_e32 v11, 0xbfb8aa3b, v11
	v_exp_f32_e32 v12, v12
	v_exp_f32_e32 v13, v13
	v_exp_f32_e32 v14, v14
	v_exp_f32_e32 v15, v15
	v_exp_f32_e32 v8, v8
	v_exp_f32_e32 v9, v9
	v_exp_f32_e32 v10, v10
	v_exp_f32_e32 v11, v11
	v_add_f32_e32 v12, 1.0, v12
	v_add_f32_e32 v13, 1.0, v13
	v_add_f32_e32 v14, 1.0, v14
	v_add_f32_e32 v15, 1.0, v15
	v_add_f32_e32 v8, 1.0, v8
	v_add_f32_e32 v9, 1.0, v9
	v_add_f32_e32 v10, 1.0, v10
	v_add_f32_e32 v11, 1.0, v11
	v_rcp_f32_e32 v12, v12
	v_rcp_f32_e32 v13, v13
	v_rcp_f32_e32 v14, v14
	v_rcp_f32_e32 v15, v15
	v_rcp_f32_e32 v8, v8
	v_rcp_f32_e32 v9, v9
	v_rcp_f32_e32 v10, v10
	v_rcp_f32_e32 v11, v11
	v_lshlrev_b32_e32 v236, 16, v228
	v_and_b32_e32 v237, 0xffff0000, v228
	v_lshlrev_b32_e32 v238, 16, v229
	v_and_b32_e32 v239, 0xffff0000, v229
	v_lshlrev_b32_e32 v240, 16, v230
	v_and_b32_e32 v241, 0xffff0000, v230
	v_lshlrev_b32_e32 v242, 16, v231
	v_and_b32_e32 v243, 0xffff0000, v231
	v_mul_f32_e32 v12, v12, v236
	v_mul_f32_e32 v13, v13, v237
	v_mul_f32_e32 v14, v14, v238
	v_mul_f32_e32 v15, v15, v239
	v_mul_f32_e32 v8, v8, v240
	v_mul_f32_e32 v9, v9, v241
	v_mul_f32_e32 v10, v10, v242
	v_mul_f32_e32 v11, v11, v243
	v_cvt_pk_bf16_f32 v12, v12, v13
	v_cvt_pk_bf16_f32 v13, v14, v15
	v_cvt_pk_bf16_f32 v14, v8, v9
	v_cvt_pk_bf16_f32 v15, v10, v11
	global_store_dwordx4 v[162:163], v[12:15], off offset:3072
	v_pk_add_f32 v[4:5], v[4:5], v[158:159]
	v_pk_add_f32 v[6:7], v[6:7], v[160:161]
	v_pk_add_f32 v[0:1], v[0:1], v[164:165]
	v_pk_add_f32 v[2:3], v[2:3], v[166:167]
	v_mul_f32_e32 v4, 0xbfb8aa3b, v4
	v_mul_f32_e32 v5, 0xbfb8aa3b, v5
	v_mul_f32_e32 v6, 0xbfb8aa3b, v6
	v_mul_f32_e32 v7, 0xbfb8aa3b, v7
	v_mul_f32_e32 v0, 0xbfb8aa3b, v0
	v_mul_f32_e32 v1, 0xbfb8aa3b, v1
	v_mul_f32_e32 v2, 0xbfb8aa3b, v2
	v_mul_f32_e32 v3, 0xbfb8aa3b, v3
	v_exp_f32_e32 v4, v4
	v_exp_f32_e32 v5, v5
	v_exp_f32_e32 v6, v6
	v_exp_f32_e32 v7, v7
	v_exp_f32_e32 v0, v0
	v_exp_f32_e32 v1, v1
	v_exp_f32_e32 v2, v2
	v_exp_f32_e32 v3, v3
	v_add_f32_e32 v4, 1.0, v4
	v_add_f32_e32 v5, 1.0, v5
	v_add_f32_e32 v6, 1.0, v6
	v_add_f32_e32 v7, 1.0, v7
	v_add_f32_e32 v0, 1.0, v0
	v_add_f32_e32 v1, 1.0, v1
	v_add_f32_e32 v2, 1.0, v2
	v_add_f32_e32 v3, 1.0, v3
	v_rcp_f32_e32 v4, v4
	v_rcp_f32_e32 v5, v5
	v_rcp_f32_e32 v6, v6
	v_rcp_f32_e32 v7, v7
	v_rcp_f32_e32 v0, v0
	v_rcp_f32_e32 v1, v1
	v_rcp_f32_e32 v2, v2
	v_rcp_f32_e32 v3, v3
	v_lshlrev_b32_e32 v236, 16, v232
	v_and_b32_e32 v237, 0xffff0000, v232
	v_lshlrev_b32_e32 v238, 16, v233
	v_and_b32_e32 v239, 0xffff0000, v233
	v_lshlrev_b32_e32 v240, 16, v234
	v_and_b32_e32 v241, 0xffff0000, v234
	v_lshlrev_b32_e32 v242, 16, v235
	v_and_b32_e32 v243, 0xffff0000, v235
	v_mul_f32_e32 v4, v4, v236
	v_mul_f32_e32 v5, v5, v237
	v_mul_f32_e32 v6, v6, v238
	v_mul_f32_e32 v7, v7, v239
	v_mul_f32_e32 v0, v0, v240
	v_mul_f32_e32 v1, v1, v241
	v_mul_f32_e32 v2, v2, v242
	v_mul_f32_e32 v3, v3, v243
	v_cvt_pk_bf16_f32 v4, v4, v5
	v_cvt_pk_bf16_f32 v5, v6, v7
	v_cvt_pk_bf16_f32 v6, v0, v1
	v_cvt_pk_bf16_f32 v7, v2, v3
	global_store_dwordx4 v[162:163], v[4:7], off offset:3328
	s_cbranch_vccnz .LBB0_951
	s_waitcnt vmcnt(0)
	s_cmpk_gt_u32 s2, 0xff
	s_cbranch_scc1 .LBB0_958
	s_barrier
